# v13: GEMM loops VALU-free + static prio, flips and duplicate waits removed, MMA-tail bookkeeping moved behind the barrier; measure 1
# speedup vs baseline: 1.0054x; 1.0002x over previous
; #define PG8_STAGE(bufoff, gbase, voff) do { _Pragma("unroll") for (int _i = 0; _i < 2; ++_i) \
;         __builtin_amdgcn_global_load_lds((const unsigned*)((const char*)(gbase) + (voff)[_i]), (LAS unsigned*)(lds + (bufoff) + ldsw + _i * 8192), 16, 0, 0); } while (0)
; #define PG8_LDA(dst, b, h) do { _Pragma("unroll") for (int m = 0; m < 4; ++m) _Pragma("unroll") for (int k = 0; k < 2; ++k) dst[m][k] = *(const LAS bf16x8*)(lds + PG8_SA(b, h) + aoff + m * 2048 + k * 1024); } while (0)
; #define PG8_LDB(dst, b, h) do { _Pragma("unroll") for (int n = 0; n < 2; ++n) _Pragma("unroll") for (int k = 0; k < 2; ++k) dst[n][k] = *(const LAS bf16x8*)(lds + PG8_SB(b, h) + boff + n * 2048 + k * 1024); } while (0)
; #define PG8_MMA(ai, bj, At, Bt) do { __builtin_amdgcn_s_setprio(1); _Pragma("unroll") for (int m = 0; m < 4; ++m) _Pragma("unroll") for (int n = 0; n < 2; ++n) _Pragma("unroll") for (int k = 0; k < 2; ++k) \
;         acc[ai][bj][m][n] = __builtin_amdgcn_mfma_f32_16x16x32_bf16(Bt[n][k], At[m][k], acc[ai][bj][m][n], 0, 0, 0); __builtin_amdgcn_s_setprio(0); } while (0)
; #define PG8_WAIT_L(n) asm volatile("s_waitcnt lgkmcnt(" #n ")" ::: "memory")
; #define PG8_BAR __builtin_amdgcn_s_barrier()
; #define PG8_SCHED __builtin_amdgcn_sched_barrier(0)
; template <class Epi, class Ptrs>
; __device__ __forceinline__ void gemm_phase(LAS unsigned char* lds, const int K, const StaticOrder& S, const Ptrs& P, const Epi& E) {
;     ...
;         for (int t = 0; t < nt; t += 2) {
;             const bool last = (t == nt - 2);
;             const char* a1 = cA + (size_t)(t + 1) * kstep;
;             const char* a2 = last ? nA : cA + (size_t)(t + 2) * kstep; const char* b2 = last ? nB : cB + (size_t)(t + 2) * kstep;
;             const char* a3 = a2 + kstep; const char* b3 = b2 + kstep;
;             PG8_LDB(B0, 0, 0); PG8_SCHED; PG8_LDA(At, 0, 0); PG8_STAGE(PG8_SA(1, 1), a1 + hstep, voffA);
;             PG8_WAIT_L(8); PG8_BAR; PG8_WAIT_L(0); PG8_MMA(0, 0, At, B0); PG8_BAR; PG8_SCHED;
;     ...
; #pragma unroll
;         for (int a = 0; a < 2; ++a)
; #pragma unroll
;             for (int b = 0; b < 2; ++b)
; #pragma unroll
;                 for (int m = 0; m < 4; ++m)
; #pragma unroll
;                     for (int n = 0; n < 2; ++n) acc[a][b][m][n] = (f32x4){0.f, 0.f, 0.f, 0.f};
.LBB0_126:
	s_add_u32 s6, s6, 0x40080
	s_nop 0
	s_nop 0
	s_nop 0
	s_nop 0
	s_nop 0
	s_nop 0
	s_nop 0
	s_nop 0
	s_nop 0
	s_nop 0
	s_nop 0
	s_nop 0
	s_nop 0
	s_nop 0
	s_nop 0
	s_nop 0
	s_nop 0
	s_nop 0
	s_nop 0
	s_nop 0
	s_nop 0
	s_nop 0
	s_nop 0
	s_nop 0
	s_nop 0
	s_nop 0
	s_nop 0
	s_nop 0
	s_nop 0
	s_nop 0
	s_nop 0
	s_nop 0
	s_nop 0
	s_nop 0
	s_nop 0
	s_nop 0
	s_nop 0
	s_nop 0
	s_nop 0
	s_nop 0
	s_nop 0
	s_nop 0
	s_nop 0
	s_nop 0
	s_nop 0
	s_nop 0
	s_nop 0
	s_nop 0
	s_nop 0
	s_nop 0
	s_nop 0
	s_nop 0
	s_nop 0
	s_nop 0
	s_nop 0
	s_nop 0
	s_nop 0
	s_addc_u32 s7, s7, 0
	s_add_u32 s20, s78, 0x100
	v_mov_b32_e32 v0, 0
	s_addc_u32 s25, s79, 0
	s_mov_b32 s63, -2
	v_mov_b32_e32 v1, v0
	v_mov_b32_e32 v2, v0
	v_mov_b32_e32 v3, v0
	v_mov_b32_e32 v12, v0
	v_mov_b32_e32 v13, v0
	v_mov_b32_e32 v14, v0
	v_mov_b32_e32 v15, v0
	v_mov_b32_e32 v16, v0
	v_mov_b32_e32 v17, v0
	v_mov_b32_e32 v18, v0
	v_mov_b32_e32 v19, v0
	v_mov_b32_e32 v28, v0
	v_mov_b32_e32 v29, v0
	v_mov_b32_e32 v30, v0
	v_mov_b32_e32 v31, v0
	v_mov_b32_e32 v32, v0
	v_mov_b32_e32 v33, v0
	v_mov_b32_e32 v34, v0
	v_mov_b32_e32 v35, v0
	v_mov_b32_e32 v44, v0
	v_mov_b32_e32 v45, v0
	v_mov_b32_e32 v46, v0
	v_mov_b32_e32 v47, v0
	v_mov_b32_e32 v48, v0
	v_mov_b32_e32 v49, v0
	v_mov_b32_e32 v50, v0
	v_mov_b32_e32 v51, v0
	v_mov_b32_e32 v60, v0
	v_mov_b32_e32 v61, v0
	v_mov_b32_e32 v62, v0
	v_mov_b32_e32 v63, v0
	v_mov_b32_e32 v4, v0
	v_mov_b32_e32 v5, v0
	v_mov_b32_e32 v6, v0
	v_mov_b32_e32 v7, v0
	v_mov_b32_e32 v8, v0
	v_mov_b32_e32 v9, v0
	v_mov_b32_e32 v10, v0
	v_mov_b32_e32 v11, v0
	v_mov_b32_e32 v20, v0
	v_mov_b32_e32 v21, v0
	v_mov_b32_e32 v22, v0
	v_mov_b32_e32 v23, v0
	v_mov_b32_e32 v24, v0
	v_mov_b32_e32 v25, v0
	v_mov_b32_e32 v26, v0
	v_mov_b32_e32 v27, v0
	v_mov_b32_e32 v36, v0
	v_mov_b32_e32 v37, v0
	v_mov_b32_e32 v38, v0
	v_mov_b32_e32 v39, v0
	v_mov_b32_e32 v40, v0
	v_mov_b32_e32 v41, v0
	v_mov_b32_e32 v42, v0
	v_mov_b32_e32 v43, v0
	v_mov_b32_e32 v52, v0
	v_mov_b32_e32 v53, v0
	v_mov_b32_e32 v54, v0
	v_mov_b32_e32 v55, v0
	v_mov_b32_e32 v56, v0
	v_mov_b32_e32 v57, v0
	v_mov_b32_e32 v58, v0
	v_mov_b32_e32 v59, v0
	v_mov_b32_e32 v64, v0
	v_mov_b32_e32 v65, v0
	v_mov_b32_e32 v66, v0
	v_mov_b32_e32 v67, v0
	v_mov_b32_e32 v76, v0
	v_mov_b32_e32 v77, v0
	v_mov_b32_e32 v78, v0
	v_mov_b32_e32 v79, v0
	v_mov_b32_e32 v80, v0
	v_mov_b32_e32 v81, v0
	v_mov_b32_e32 v82, v0
	v_mov_b32_e32 v83, v0
	v_mov_b32_e32 v92, v0
	v_mov_b32_e32 v93, v0
	v_mov_b32_e32 v94, v0
	v_mov_b32_e32 v95, v0
	v_mov_b32_e32 v96, v0
	v_mov_b32_e32 v97, v0
	v_mov_b32_e32 v98, v0
	v_mov_b32_e32 v99, v0
	v_mov_b32_e32 v108, v0
	v_mov_b32_e32 v109, v0
	v_mov_b32_e32 v110, v0
	v_mov_b32_e32 v111, v0
	v_mov_b32_e32 v112, v0
	v_mov_b32_e32 v113, v0
	v_mov_b32_e32 v114, v0
	v_mov_b32_e32 v115, v0
	v_mov_b32_e32 v124, v0
	v_mov_b32_e32 v125, v0
	v_mov_b32_e32 v126, v0
	v_mov_b32_e32 v127, v0
	v_mov_b32_e32 v68, v0
	v_mov_b32_e32 v69, v0
	v_mov_b32_e32 v70, v0
	v_mov_b32_e32 v71, v0
	v_mov_b32_e32 v72, v0
	v_mov_b32_e32 v73, v0
	v_mov_b32_e32 v74, v0
	v_mov_b32_e32 v75, v0
	v_mov_b32_e32 v84, v0
	v_mov_b32_e32 v85, v0
	v_mov_b32_e32 v86, v0
	v_mov_b32_e32 v87, v0
	v_mov_b32_e32 v88, v0
	v_mov_b32_e32 v89, v0
	v_mov_b32_e32 v90, v0
	v_mov_b32_e32 v91, v0
	v_mov_b32_e32 v100, v0
	v_mov_b32_e32 v101, v0
	v_mov_b32_e32 v102, v0
	v_mov_b32_e32 v103, v0
	v_mov_b32_e32 v104, v0
	v_mov_b32_e32 v105, v0
	v_mov_b32_e32 v106, v0
	v_mov_b32_e32 v107, v0
	v_mov_b32_e32 v116, v0
	v_mov_b32_e32 v117, v0
	v_mov_b32_e32 v118, v0
	v_mov_b32_e32 v119, v0
	v_mov_b32_e32 v120, v0
	v_mov_b32_e32 v121, v0
	v_mov_b32_e32 v122, v0
	v_add_u32_e32 v252, 0x18000, v131
	v_add_u32_e32 v253, 0x1c000, v131
	v_mov_b32_e32 v123, v0
.LBB0_127:
	ds_read_b128 v[150:153], v205
	ds_read_b128 v[154:157], v205 offset:1024
	ds_read_b128 v[158:161], v205 offset:2048
	ds_read_b128 v[162:165], v205 offset:3072
	s_add_u32 s69, s6, 0xfffc0080
	s_addc_u32 s71, s7, -1
	s_cmp_eq_u32 s63, 12
	s_cselect_b32 s81, s1, s71
	s_cselect_b32 s80, s0, s69
	s_cselect_b32 s79, s73, s25
	s_cselect_b32 s78, s72, s20
	s_add_i32 m0, s67, 0xc000
	ds_read_b128 v[166:169], v206
	ds_read_b128 v[170:173], v206 offset:1024
	ds_read_b128 v[174:177], v206 offset:2048
	ds_read_b128 v[178:181], v206 offset:3072
	ds_read_b128 v[182:185], v206 offset:4096
	ds_read_b128 v[186:189], v206 offset:5120
	ds_read_b128 v[190:193], v206 offset:6144
	ds_read_b128 v[194:197], v206 offset:7168
	global_load_lds_dwordx4 v142, s[6:7]
	s_add_i32 m0, s67, 0xe000
	s_nop 0
	global_load_lds_dwordx4 v144, s[6:7]
	s_waitcnt lgkmcnt(8)
	s_barrier
	s_waitcnt lgkmcnt(0)
	v_mfma_f32_16x16x32_bf16 v[120:123], v[150:153], v[166:169], v[120:123]
	v_mfma_f32_16x16x32_bf16 v[120:123], v[154:157], v[170:173], v[120:123]
	v_mfma_f32_16x16x32_bf16 v[116:119], v[162:165], v[170:173], v[116:119]
	v_mfma_f32_16x16x32_bf16 v[116:119], v[158:161], v[166:169], v[116:119]
	v_mfma_f32_16x16x32_bf16 v[100:103], v[158:161], v[174:177], v[100:103]
	v_mfma_f32_16x16x32_bf16 v[100:103], v[162:165], v[178:181], v[100:103]
	v_mfma_f32_16x16x32_bf16 v[104:107], v[154:157], v[178:181], v[104:107]
	v_mfma_f32_16x16x32_bf16 v[104:107], v[150:153], v[174:177], v[104:107]
	v_mfma_f32_16x16x32_bf16 v[88:91], v[150:153], v[182:185], v[88:91]
	v_mfma_f32_16x16x32_bf16 v[88:91], v[154:157], v[186:189], v[88:91]
	v_mfma_f32_16x16x32_bf16 v[84:87], v[162:165], v[186:189], v[84:87]
	v_mfma_f32_16x16x32_bf16 v[84:87], v[158:161], v[182:185], v[84:87]
	v_mfma_f32_16x16x32_bf16 v[68:71], v[158:161], v[190:193], v[68:71]
	v_mfma_f32_16x16x32_bf16 v[68:71], v[162:165], v[194:197], v[68:71]
	v_mfma_f32_16x16x32_bf16 v[72:75], v[154:157], v[194:197], v[72:75]
	v_mfma_f32_16x16x32_bf16 v[72:75], v[150:153], v[190:193], v[72:75]
	s_barrier
; #define PG8_STAGE(bufoff, gbase, voff) do { _Pragma("unroll") for (int _i = 0; _i < 2; ++_i) \
;         __builtin_amdgcn_global_load_lds((const unsigned*)((const char*)(gbase) + (voff)[_i]), (LAS unsigned*)(lds + (bufoff) + ldsw + _i * 8192), 16, 0, 0); } while (0)
; #define PG8_LDA(dst, b, h) do { _Pragma("unroll") for (int m = 0; m < 4; ++m) _Pragma("unroll") for (int k = 0; k < 2; ++k) dst[m][k] = *(const LAS bf16x8*)(lds + PG8_SA(b, h) + aoff + m * 2048 + k * 1024); } while (0)
; #define PG8_LDB(dst, b, h) do { _Pragma("unroll") for (int n = 0; n < 2; ++n) _Pragma("unroll") for (int k = 0; k < 2; ++k) dst[n][k] = *(const LAS bf16x8*)(lds + PG8_SB(b, h) + boff + n * 2048 + k * 1024); } while (0)
; #define PG8_MMA(ai, bj, At, Bt) do { __builtin_amdgcn_s_setprio(1); _Pragma("unroll") for (int m = 0; m < 4; ++m) _Pragma("unroll") for (int n = 0; n < 2; ++n) _Pragma("unroll") for (int k = 0; k < 2; ++k) \
;         acc[ai][bj][m][n] = __builtin_amdgcn_mfma_f32_16x16x32_bf16(Bt[n][k], At[m][k], acc[ai][bj][m][n], 0, 0, 0); __builtin_amdgcn_s_setprio(0); } while (0)
; #define PG8_WAIT_V(n) asm volatile("s_waitcnt vmcnt(" #n ")" ::: "memory")
; #define PG8_WAIT_L(n) asm volatile("s_waitcnt lgkmcnt(" #n ")" ::: "memory")
; #define PG8_BAR __builtin_amdgcn_s_barrier()
; #define PG8_SCHED __builtin_amdgcn_sched_barrier(0)
; template <class Epi, class Ptrs>
; __device__ __forceinline__ void gemm_phase(LAS unsigned char* lds, const int K, const StaticOrder& S, const Ptrs& P, const Epi& E) {
;     ...
;             PG8_LDB(B1, 0, 1); PG8_STAGE(PG8_SB(0, 0), b2, voffB);
;             PG8_BAR; PG8_WAIT_L(0); PG8_MMA(0, 1, At, B1); PG8_BAR;
;             PG8_LDA(At, 0, 1); PG8_STAGE(PG8_SA(0, 0), a2, voffA);
;             PG8_BAR; PG8_WAIT_L(0); PG8_MMA(1, 0, At, B0); PG8_BAR; PG8_SCHED;
;             PG8_STAGE(PG8_SB(0, 1), b2 + hstep, voffB);
;             PG8_WAIT_V(6); PG8_BAR; PG8_MMA(1, 1, At, B1); PG8_BAR;
;             PG8_LDB(B0, 1, 0); PG8_SCHED; PG8_LDA(At, 1, 0); PG8_STAGE(PG8_SA(0, 1), a2 + hstep, voffA);
;             PG8_WAIT_L(8); PG8_BAR; PG8_WAIT_L(0); PG8_MMA(0, 0, At, B0); PG8_BAR; PG8_SCHED;
	s_add_i32 s69, s91, s65
	s_add_u32 s100, s78, 0x80
	s_addc_u32 s101, s79, 0
	s_mov_b32 m0, s69
	ds_read_b128 v[198:201], v207
	ds_read_b128 v[210:213], v207 offset:1024
	ds_read_b128 v[214:217], v207 offset:2048
	ds_read_b128 v[218:221], v207 offset:3072
	global_load_lds_dwordx4 v134, s[78:79]
	s_add_i32 m0, s69, 0x2000
	s_nop 0
	global_load_lds_dwordx4 v138, s[78:79]
	s_barrier
	s_waitcnt lgkmcnt(0)
	v_mfma_f32_16x16x32_bf16 v[124:127], v[198:201], v[166:169], v[124:127]
	v_mfma_f32_16x16x32_bf16 v[124:127], v[210:213], v[170:173], v[124:127]
	v_mfma_f32_16x16x32_bf16 v[112:115], v[218:221], v[170:173], v[112:115]
	v_mfma_f32_16x16x32_bf16 v[112:115], v[214:217], v[166:169], v[112:115]
	v_mfma_f32_16x16x32_bf16 v[96:99], v[214:217], v[174:177], v[96:99]
	v_mfma_f32_16x16x32_bf16 v[96:99], v[218:221], v[178:181], v[96:99]
	v_mfma_f32_16x16x32_bf16 v[108:111], v[210:213], v[178:181], v[108:111]
	v_mfma_f32_16x16x32_bf16 v[108:111], v[198:201], v[174:177], v[108:111]
	v_mfma_f32_16x16x32_bf16 v[92:95], v[198:201], v[182:185], v[92:95]
	v_mfma_f32_16x16x32_bf16 v[92:95], v[210:213], v[186:189], v[92:95]
	v_mfma_f32_16x16x32_bf16 v[80:83], v[218:221], v[186:189], v[80:83]
	v_mfma_f32_16x16x32_bf16 v[80:83], v[214:217], v[182:185], v[80:83]
	v_mfma_f32_16x16x32_bf16 v[64:67], v[214:217], v[190:193], v[64:67]
	v_mfma_f32_16x16x32_bf16 v[64:67], v[218:221], v[194:197], v[64:67]
	v_mfma_f32_16x16x32_bf16 v[76:79], v[210:213], v[194:197], v[76:79]
	v_mfma_f32_16x16x32_bf16 v[76:79], v[198:201], v[190:193], v[76:79]
	s_barrier
	s_mov_b32 m0, s67
	ds_read_b128 v[166:169], v206 offset:16384
	ds_read_b128 v[170:173], v206 offset:17408
	ds_read_b128 v[174:177], v206 offset:18432
	ds_read_b128 v[178:181], v206 offset:19456
	ds_read_b128 v[182:185], v206 offset:20480
	ds_read_b128 v[186:189], v206 offset:21504
	ds_read_b128 v[190:193], v206 offset:22528
	ds_read_b128 v[194:197], v206 offset:23552
	global_load_lds_dwordx4 v132, s[80:81]
	s_mov_b32 m0, s75
	s_nop 0
	global_load_lds_dwordx4 v136, s[80:81]
	s_barrier
	s_waitcnt lgkmcnt(0)
	v_mfma_f32_16x16x32_bf16 v[56:59], v[150:153], v[166:169], v[56:59]
	v_mfma_f32_16x16x32_bf16 v[56:59], v[154:157], v[170:173], v[56:59]
	v_mfma_f32_16x16x32_bf16 v[52:55], v[162:165], v[170:173], v[52:55]
	v_mfma_f32_16x16x32_bf16 v[52:55], v[158:161], v[166:169], v[52:55]
	v_mfma_f32_16x16x32_bf16 v[36:39], v[158:161], v[174:177], v[36:39]
	v_mfma_f32_16x16x32_bf16 v[36:39], v[162:165], v[178:181], v[36:39]
	v_mfma_f32_16x16x32_bf16 v[40:43], v[154:157], v[178:181], v[40:43]
	v_mfma_f32_16x16x32_bf16 v[40:43], v[150:153], v[174:177], v[40:43]
	v_mfma_f32_16x16x32_bf16 v[24:27], v[150:153], v[182:185], v[24:27]
	v_mfma_f32_16x16x32_bf16 v[24:27], v[154:157], v[186:189], v[24:27]
	v_mfma_f32_16x16x32_bf16 v[20:23], v[162:165], v[186:189], v[20:23]
	v_mfma_f32_16x16x32_bf16 v[20:23], v[158:161], v[182:185], v[20:23]
	v_mfma_f32_16x16x32_bf16 v[4:7], v[158:161], v[190:193], v[4:7]
	v_mfma_f32_16x16x32_bf16 v[4:7], v[162:165], v[194:197], v[4:7]
	v_mfma_f32_16x16x32_bf16 v[8:11], v[154:157], v[194:197], v[8:11]
	v_mfma_f32_16x16x32_bf16 v[8:11], v[150:153], v[190:193], v[8:11]
	s_barrier
	s_add_u32 s82, s78, 0x40000
	s_addc_u32 s83, s79, 0
	s_add_i32 s69, s92, s65
	s_mov_b32 m0, s69
	s_nop 0
	global_load_lds_dwordx4 v134, s[82:83]
	s_add_i32 m0, s69, 0x2000
	s_nop 0
	global_load_lds_dwordx4 v138, s[82:83]
	s_waitcnt vmcnt(6)
	s_barrier
	v_mfma_f32_16x16x32_bf16 v[60:63], v[198:201], v[166:169], v[60:63]
	v_mfma_f32_16x16x32_bf16 v[60:63], v[210:213], v[170:173], v[60:63]
	v_mfma_f32_16x16x32_bf16 v[48:51], v[218:221], v[170:173], v[48:51]
	v_mfma_f32_16x16x32_bf16 v[48:51], v[214:217], v[166:169], v[48:51]
	v_mfma_f32_16x16x32_bf16 v[32:35], v[214:217], v[174:177], v[32:35]
	v_mfma_f32_16x16x32_bf16 v[32:35], v[218:221], v[178:181], v[32:35]
	v_mfma_f32_16x16x32_bf16 v[44:47], v[210:213], v[178:181], v[44:47]
	v_mfma_f32_16x16x32_bf16 v[44:47], v[198:201], v[174:177], v[44:47]
	v_mfma_f32_16x16x32_bf16 v[28:31], v[198:201], v[182:185], v[28:31]
	v_mfma_f32_16x16x32_bf16 v[28:31], v[210:213], v[186:189], v[28:31]
	v_mfma_f32_16x16x32_bf16 v[16:19], v[218:221], v[186:189], v[16:19]
	v_mfma_f32_16x16x32_bf16 v[16:19], v[214:217], v[182:185], v[16:19]
	v_mfma_f32_16x16x32_bf16 v[0:3], v[214:217], v[190:193], v[0:3]
	v_mfma_f32_16x16x32_bf16 v[0:3], v[218:221], v[194:197], v[0:3]
	v_mfma_f32_16x16x32_bf16 v[12:15], v[210:213], v[194:197], v[12:15]
	v_mfma_f32_16x16x32_bf16 v[12:15], v[198:201], v[190:193], v[12:15]
	s_barrier
	s_add_i32 s69, 0, 0x18000
	ds_read_b128 v[150:153], v252
	ds_read_b128 v[154:157], v252 offset:1024
	ds_read_b128 v[158:161], v252 offset:2048
	ds_read_b128 v[162:165], v252 offset:3072
	s_add_u32 s80, s80, 0x40000
	s_addc_u32 s81, s81, 0
	s_mov_b32 m0, s77
	ds_read_b128 v[166:169], v206 offset:32768
	ds_read_b128 v[170:173], v206 offset:33792
	ds_read_b128 v[174:177], v206 offset:34816
	ds_read_b128 v[178:181], v206 offset:35840
	ds_read_b128 v[182:185], v206 offset:36864
	ds_read_b128 v[186:189], v206 offset:37888
	ds_read_b128 v[190:193], v206 offset:38912
	ds_read_b128 v[194:197], v206 offset:39936
	global_load_lds_dwordx4 v132, s[80:81]
	s_mov_b32 m0, s85
	s_nop 0
	global_load_lds_dwordx4 v136, s[80:81]
	s_waitcnt lgkmcnt(8)
	s_barrier
; template <class Epi, class Ptrs>
; __device__ __forceinline__ void gemm_phase(LAS unsigned char* lds, const int K, const StaticOrder& S, const Ptrs& P, const Epi& E) {
;     ...
;             PG8_WAIT_L(8); PG8_BAR; PG8_WAIT_L(0); PG8_MMA(0, 0, At, B0); PG8_BAR; PG8_SCHED;
;             PG8_LDB(B1, 1, 1); PG8_STAGE(PG8_SB(1, 0), b3, voffB);
;             PG8_BAR; PG8_WAIT_L(0); PG8_MMA(0, 1, At, B1); PG8_BAR;
;             PG8_LDA(At, 1, 1); PG8_STAGE(PG8_SA(1, 0), a3, voffA);
;             PG8_BAR; PG8_WAIT_L(0); PG8_MMA(1, 0, At, B0); PG8_BAR; PG8_SCHED;
;             PG8_STAGE(PG8_SB(1, 1), b3 + hstep, voffB);
;             PG8_WAIT_V(6); PG8_BAR; PG8_MMA(1, 1, At, B1); PG8_BAR;
;     __device__ __forceinline__ void operator()(const f32x4 (&acc)[2][2][4][2], const Unit& u, int ui, int wr, int wc, int fr, int fq) const {
;         const int pn = u.pn;
;         if (pn < 8) {
;             bf16_t* base = (bf16_t*)(ws + WS_U) + (size_t)(u.pm * 256 + wr * 64 + fr) * DM + pn * 128 + wc * 32 + 8 * fq;
; #pragma unroll
;             for (int ai = 0; ai < 2; ++ai)
; #pragma unroll
;                 for (int m = 0; m < 4; ++m) {
;                     const f32x4 g0 = g1_4(acc[ai][0][m][0], acc[ai][1][m][0]), g1 = g1_4(acc[ai][0][m][1], acc[ai][1][m][1]);
;                     *(u32x4*)(base + (size_t)(ai * 128 + m * 16) * DM) = pack8(g0, g1); }
;             return; }
;         if (pn >= 17 && pn < 21) {
;             bf16_t* base = (bf16_t*)(dout + DO_GVT) + (size_t)((pn - 17) * 256 + wr * 64 + fr) * MTOK + u.pm * 256 + wc * 32 + 8 * fq;
;             float* pp = (float*)(ws + WS_PART) + (size_t)(u.pm * 256 + wc * 32 + 8 * fq) * 8 + (pn - 17) * 2 + wr;
; #pragma unroll
;             for (int bj = 0; bj < 2; ++bj) { f32x4 sq0 = {0.f, 0.f, 0.f, 0.f}, sq1 = {0.f, 0.f, 0.f, 0.f};
; #pragma unroll
;                 for (int ai = 0; ai < 2; ++ai)
; #pragma unroll
;                     for (int m = 0; m < 4; ++m) { const f32x4 g0 = gelu4(acc[ai][bj][m][0]), g1 = gelu4(acc[ai][bj][m][1]);
;                         sq0 += g0 * g0; sq1 += g1 * g1;
;                         *(u32x4*)(base + (size_t)(ai * 128 + m * 16) * MTOK + bj * 128) = pack8(g0, g1); }
; #pragma unroll
;                 for (int j = 0; j < 4; ++j) { const float t0 = row16_sum(sq0[j]), t1 = row16_sum(sq1[j]); if (fr == 0) { pp[(size_t)(bj * 128 + j) * 8] = t0; pp[(size_t)(bj * 128 + 4 + j) * 8] = t1; } } }
	s_waitcnt lgkmcnt(0)
	v_mfma_f32_16x16x32_bf16 v[120:123], v[150:153], v[166:169], v[120:123]
	v_mfma_f32_16x16x32_bf16 v[120:123], v[154:157], v[170:173], v[120:123]
	v_mfma_f32_16x16x32_bf16 v[116:119], v[162:165], v[170:173], v[116:119]
	v_mfma_f32_16x16x32_bf16 v[116:119], v[158:161], v[166:169], v[116:119]
	v_mfma_f32_16x16x32_bf16 v[100:103], v[158:161], v[174:177], v[100:103]
	v_mfma_f32_16x16x32_bf16 v[100:103], v[162:165], v[178:181], v[100:103]
	v_mfma_f32_16x16x32_bf16 v[104:107], v[154:157], v[178:181], v[104:107]
	v_mfma_f32_16x16x32_bf16 v[104:107], v[150:153], v[174:177], v[104:107]
	v_mfma_f32_16x16x32_bf16 v[88:91], v[150:153], v[182:185], v[88:91]
	v_mfma_f32_16x16x32_bf16 v[88:91], v[154:157], v[186:189], v[88:91]
	v_mfma_f32_16x16x32_bf16 v[84:87], v[162:165], v[186:189], v[84:87]
	v_mfma_f32_16x16x32_bf16 v[84:87], v[158:161], v[182:185], v[84:87]
	v_mfma_f32_16x16x32_bf16 v[68:71], v[158:161], v[190:193], v[68:71]
	v_mfma_f32_16x16x32_bf16 v[68:71], v[162:165], v[194:197], v[68:71]
	v_mfma_f32_16x16x32_bf16 v[72:75], v[154:157], v[194:197], v[72:75]
	v_mfma_f32_16x16x32_bf16 v[72:75], v[150:153], v[190:193], v[72:75]
	s_barrier
	s_add_i32 s71, 0, 0x1c000
	s_add_i32 s69, s69, s65
	s_mov_b32 m0, s69
	ds_read_b128 v[198:201], v253
	ds_read_b128 v[210:213], v253 offset:1024
	ds_read_b128 v[214:217], v253 offset:2048
	ds_read_b128 v[218:221], v253 offset:3072
	global_load_lds_dwordx4 v134, s[100:101]
	s_add_i32 m0, s69, 0x2000
	s_nop 0
	global_load_lds_dwordx4 v138, s[100:101]
	s_barrier
	s_waitcnt lgkmcnt(0)
	v_mfma_f32_16x16x32_bf16 v[124:127], v[198:201], v[166:169], v[124:127]
	v_mfma_f32_16x16x32_bf16 v[124:127], v[210:213], v[170:173], v[124:127]
	v_mfma_f32_16x16x32_bf16 v[112:115], v[218:221], v[170:173], v[112:115]
	v_mfma_f32_16x16x32_bf16 v[112:115], v[214:217], v[166:169], v[112:115]
	v_mfma_f32_16x16x32_bf16 v[96:99], v[214:217], v[174:177], v[96:99]
	v_mfma_f32_16x16x32_bf16 v[96:99], v[218:221], v[178:181], v[96:99]
	v_mfma_f32_16x16x32_bf16 v[108:111], v[210:213], v[178:181], v[108:111]
	v_mfma_f32_16x16x32_bf16 v[108:111], v[198:201], v[174:177], v[108:111]
	v_mfma_f32_16x16x32_bf16 v[92:95], v[198:201], v[182:185], v[92:95]
	v_mfma_f32_16x16x32_bf16 v[92:95], v[210:213], v[186:189], v[92:95]
	v_mfma_f32_16x16x32_bf16 v[80:83], v[218:221], v[186:189], v[80:83]
	v_mfma_f32_16x16x32_bf16 v[80:83], v[214:217], v[182:185], v[80:83]
	v_mfma_f32_16x16x32_bf16 v[64:67], v[214:217], v[190:193], v[64:67]
	v_mfma_f32_16x16x32_bf16 v[64:67], v[218:221], v[194:197], v[64:67]
	v_mfma_f32_16x16x32_bf16 v[76:79], v[210:213], v[194:197], v[76:79]
	v_mfma_f32_16x16x32_bf16 v[76:79], v[198:201], v[190:193], v[76:79]
	s_barrier
	s_mov_b32 m0, s89
	s_add_u32 s100, s80, 0xfffc0080
	s_addc_u32 s101, s81, -1
	ds_read_b128 v[166:169], v206 offset:49152
	ds_read_b128 v[170:173], v206 offset:50176
	ds_read_b128 v[174:177], v206 offset:51200
	ds_read_b128 v[178:181], v206 offset:52224
	ds_read_b128 v[182:185], v206 offset:53248
	ds_read_b128 v[186:189], v206 offset:54272
	ds_read_b128 v[190:193], v206 offset:55296
	ds_read_b128 v[194:197], v206 offset:56320
	global_load_lds_dwordx4 v132, s[100:101]
	s_mov_b32 m0, s90
	s_nop 0
	global_load_lds_dwordx4 v136, s[100:101]
	s_barrier
	s_waitcnt lgkmcnt(0)
	v_mfma_f32_16x16x32_bf16 v[56:59], v[150:153], v[166:169], v[56:59]
	v_mfma_f32_16x16x32_bf16 v[56:59], v[154:157], v[170:173], v[56:59]
	v_mfma_f32_16x16x32_bf16 v[52:55], v[162:165], v[170:173], v[52:55]
	v_mfma_f32_16x16x32_bf16 v[52:55], v[158:161], v[166:169], v[52:55]
	v_mfma_f32_16x16x32_bf16 v[36:39], v[158:161], v[174:177], v[36:39]
	v_mfma_f32_16x16x32_bf16 v[36:39], v[162:165], v[178:181], v[36:39]
	v_mfma_f32_16x16x32_bf16 v[40:43], v[154:157], v[178:181], v[40:43]
	v_mfma_f32_16x16x32_bf16 v[40:43], v[150:153], v[174:177], v[40:43]
	v_mfma_f32_16x16x32_bf16 v[24:27], v[150:153], v[182:185], v[24:27]
	v_mfma_f32_16x16x32_bf16 v[24:27], v[154:157], v[186:189], v[24:27]
	v_mfma_f32_16x16x32_bf16 v[20:23], v[162:165], v[186:189], v[20:23]
	v_mfma_f32_16x16x32_bf16 v[20:23], v[158:161], v[182:185], v[20:23]
	v_mfma_f32_16x16x32_bf16 v[4:7], v[158:161], v[190:193], v[4:7]
	v_mfma_f32_16x16x32_bf16 v[4:7], v[162:165], v[194:197], v[4:7]
	v_mfma_f32_16x16x32_bf16 v[8:11], v[154:157], v[194:197], v[8:11]
	v_mfma_f32_16x16x32_bf16 v[8:11], v[150:153], v[190:193], v[8:11]
	s_barrier
	s_add_u32 s78, s78, 0x40080
	s_addc_u32 s79, s79, 0
	s_add_i32 s69, s71, s65
	s_mov_b32 m0, s69
	s_nop 0
	global_load_lds_dwordx4 v134, s[78:79]
	s_add_i32 m0, s69, 0x2000
	s_nop 0
	global_load_lds_dwordx4 v138, s[78:79]
	s_waitcnt vmcnt(6)
	s_barrier
	v_mfma_f32_16x16x32_bf16 v[60:63], v[198:201], v[166:169], v[60:63]
	v_mfma_f32_16x16x32_bf16 v[60:63], v[210:213], v[170:173], v[60:63]
	v_mfma_f32_16x16x32_bf16 v[48:51], v[218:221], v[170:173], v[48:51]
	v_mfma_f32_16x16x32_bf16 v[48:51], v[214:217], v[166:169], v[48:51]
	v_mfma_f32_16x16x32_bf16 v[32:35], v[214:217], v[174:177], v[32:35]
	v_mfma_f32_16x16x32_bf16 v[32:35], v[218:221], v[178:181], v[32:35]
	v_mfma_f32_16x16x32_bf16 v[44:47], v[210:213], v[178:181], v[44:47]
	v_mfma_f32_16x16x32_bf16 v[44:47], v[198:201], v[174:177], v[44:47]
	v_mfma_f32_16x16x32_bf16 v[28:31], v[198:201], v[182:185], v[28:31]
	v_mfma_f32_16x16x32_bf16 v[28:31], v[210:213], v[186:189], v[28:31]
	v_mfma_f32_16x16x32_bf16 v[16:19], v[218:221], v[186:189], v[16:19]
	v_mfma_f32_16x16x32_bf16 v[16:19], v[214:217], v[182:185], v[16:19]
	v_mfma_f32_16x16x32_bf16 v[0:3], v[214:217], v[190:193], v[0:3]
	v_mfma_f32_16x16x32_bf16 v[0:3], v[218:221], v[194:197], v[0:3]
	v_mfma_f32_16x16x32_bf16 v[12:15], v[210:213], v[194:197], v[12:15]
	v_mfma_f32_16x16x32_bf16 v[12:15], v[198:201], v[190:193], v[12:15]
	s_barrier
	s_add_i32 s63, s63, 2
	s_add_u32 s6, s6, 0x100
	s_addc_u32 s7, s7, 0
	s_add_u32 s20, s20, 0x100
	s_addc_u32 s25, s25, 0
	s_cmp_gt_u32 s63, 13
	s_cbranch_scc0 .LBB0_127
	s_nop 0
	s_nop 0
	s_nop 0
	s_nop 0
	s_nop 0
	s_nop 0
	s_nop 0
	s_nop 0
	s_nop 0
	s_nop 0
	s_nop 0
	s_nop 0
	s_nop 0
	s_nop 0
	s_nop 0
	s_nop 0
	s_nop 0
	s_nop 0
	s_nop 0
	s_nop 0
	s_nop 0
	s_nop 0
	s_nop 0
	s_nop 0
	s_nop 0
	s_nop 0
	s_nop 0
	s_nop 0
	s_nop 0
	s_nop 0
	s_nop 0
	s_nop 0
	s_nop 0
	s_nop 0
	s_nop 0
	s_nop 0
	s_nop 0
	s_nop 0
	s_nop 0
	s_nop 0
	s_nop 0
	s_nop 0
	s_nop 0
	s_nop 0
	s_nop 0
	s_nop 0
	s_nop 0
	s_nop 0
	s_nop 0
	s_nop 0
	s_cmp_gt_i32 s74, 7
	s_mov_b64 s[6:7], -1
	s_cbranch_scc0 .LBB0_188
	s_sub_i32 s25, s74, 17
	s_cmp_gt_u32 s25, 3
	s_cbranch_scc0 .LBB0_170
	s_lshl_b32 s69, s76, 8
	s_cmp_gt_u32 s74, 11
	s_cbranch_scc0 .LBB0_135
	s_cmp_eq_u32 s74, 12
	s_mov_b64 s[6:7], 0
	s_cbranch_scc1 .LBB0_134
	s_cmp_gt_u32 s74, 16
	s_cbranch_scc1 .LBB0_191
	s_lshl_b32 s20, s74, 8
	v_readlane_b32 s80, v254, 2
	s_addk_i32 s20, 0xf300
	s_mov_b64 s[78:79], 0x400
	s_mov_b64 s[82:83], -1
	s_mov_b32 s63, s69
	v_readlane_b32 s81, v254, 3
	s_andn2_b64 vcc, exec, s[6:7]
	s_cbranch_vccz .LBB0_136
	s_branch .LBB0_137

; #define PG8_STAGE(bufoff, gbase, voff) do { _Pragma("unroll") for (int _i = 0; _i < 2; ++_i) \
;         __builtin_amdgcn_global_load_lds((const unsigned*)((const char*)(gbase) + (voff)[_i]), (LAS unsigned*)(lds + (bufoff) + ldsw + _i * 8192), 16, 0, 0); } while (0)
; #define PG8_LDA(dst, b, h) do { _Pragma("unroll") for (int m = 0; m < 4; ++m) _Pragma("unroll") for (int k = 0; k < 2; ++k) dst[m][k] = *(const LAS bf16x8*)(lds + PG8_SA(b, h) + aoff + m * 2048 + k * 1024); } while (0)
; #define PG8_LDB(dst, b, h) do { _Pragma("unroll") for (int n = 0; n < 2; ++n) _Pragma("unroll") for (int k = 0; k < 2; ++k) dst[n][k] = *(const LAS bf16x8*)(lds + PG8_SB(b, h) + boff + n * 2048 + k * 1024); } while (0)
; #define PG8_MMA(ai, bj, At, Bt) do { __builtin_amdgcn_s_setprio(1); _Pragma("unroll") for (int m = 0; m < 4; ++m) _Pragma("unroll") for (int n = 0; n < 2; ++n) _Pragma("unroll") for (int k = 0; k < 2; ++k) \
;         acc[ai][bj][m][n] = __builtin_amdgcn_mfma_f32_16x16x32_bf16(Bt[n][k], At[m][k], acc[ai][bj][m][n], 0, 0, 0); __builtin_amdgcn_s_setprio(0); } while (0)
; #define PG8_WAIT_L(n) asm volatile("s_waitcnt lgkmcnt(" #n ")" ::: "memory")
; #define PG8_BAR __builtin_amdgcn_s_barrier()
; #define PG8_SCHED __builtin_amdgcn_sched_barrier(0)
; template <class Epi, class Ptrs>
; __device__ __forceinline__ void gemm_phase(LAS unsigned char* lds, const int K, const StaticOrder& S, const Ptrs& P, const Epi& E) {
;     ...
;         for (int t = 0; t < nt; t += 2) {
;             const bool last = (t == nt - 2);
;             const char* a1 = cA + (size_t)(t + 1) * kstep;
;             const char* a2 = last ? nA : cA + (size_t)(t + 2) * kstep; const char* b2 = last ? nB : cB + (size_t)(t + 2) * kstep;
;             const char* a3 = a2 + kstep; const char* b3 = b2 + kstep;
;             PG8_LDB(B0, 0, 0); PG8_SCHED; PG8_LDA(At, 0, 0); PG8_STAGE(PG8_SA(1, 1), a1 + hstep, voffA);
;             PG8_WAIT_L(8); PG8_BAR; PG8_WAIT_L(0); PG8_MMA(0, 0, At, B0); PG8_BAR; PG8_SCHED;
;     ...
; #pragma unroll
;         for (int a = 0; a < 2; ++a)
; #pragma unroll
;             for (int b = 0; b < 2; ++b)
; #pragma unroll
;                 for (int m = 0; m < 4; ++m)
; #pragma unroll
;                     for (int n = 0; n < 2; ++n) acc[a][b][m][n] = (f32x4){0.f, 0.f, 0.f, 0.f};
.LBB0_352:
	s_add_u32 s38, s44, 0x40080
	s_nop 0
	s_nop 0
	s_nop 0
	s_nop 0
	s_nop 0
	s_nop 0
	s_nop 0
	s_nop 0
	s_nop 0
	s_nop 0
	s_nop 0
	s_nop 0
	s_nop 0
	s_nop 0
	s_nop 0
	s_nop 0
	s_nop 0
	s_nop 0
	s_nop 0
	s_nop 0
	s_nop 0
	s_nop 0
	s_nop 0
	s_nop 0
	s_nop 0
	s_nop 0
	s_nop 0
	s_nop 0
	s_nop 0
	s_nop 0
	s_nop 0
	s_nop 0
	s_nop 0
	s_nop 0
	s_nop 0
	s_nop 0
	s_nop 0
	s_nop 0
	s_nop 0
	s_nop 0
	s_nop 0
	s_nop 0
	s_nop 0
	s_nop 0
	s_nop 0
	s_nop 0
	s_nop 0
	s_nop 0
	s_nop 0
	s_nop 0
	s_nop 0
	s_nop 0
	s_nop 0
	s_nop 0
	s_nop 0
	s_nop 0
	s_nop 0
	s_addc_u32 s39, s45, 0
	s_add_u32 s21, s42, 0x100
	v_mov_b32_e32 v0, 0
	s_addc_u32 s23, s43, 0
	s_mov_b32 s41, -2
	v_mov_b32_e32 v1, v0
	v_mov_b32_e32 v2, v0
	v_mov_b32_e32 v3, v0
	v_mov_b32_e32 v4, v0
	v_mov_b32_e32 v5, v0
	v_mov_b32_e32 v6, v0
	v_mov_b32_e32 v7, v0
	v_mov_b32_e32 v16, v0
	v_mov_b32_e32 v17, v0
	v_mov_b32_e32 v18, v0
	v_mov_b32_e32 v19, v0
	v_mov_b32_e32 v20, v0
	v_mov_b32_e32 v21, v0
	v_mov_b32_e32 v22, v0
	v_mov_b32_e32 v23, v0
	v_mov_b32_e32 v32, v0
	v_mov_b32_e32 v33, v0
	v_mov_b32_e32 v34, v0
	v_mov_b32_e32 v35, v0
	v_mov_b32_e32 v36, v0
	v_mov_b32_e32 v37, v0
	v_mov_b32_e32 v38, v0
	v_mov_b32_e32 v39, v0
	v_mov_b32_e32 v48, v0
	v_mov_b32_e32 v49, v0
	v_mov_b32_e32 v50, v0
	v_mov_b32_e32 v51, v0
	v_mov_b32_e32 v52, v0
	v_mov_b32_e32 v53, v0
	v_mov_b32_e32 v54, v0
	v_mov_b32_e32 v55, v0
	v_mov_b32_e32 v8, v0
	v_mov_b32_e32 v9, v0
	v_mov_b32_e32 v10, v0
	v_mov_b32_e32 v11, v0
	v_mov_b32_e32 v12, v0
	v_mov_b32_e32 v13, v0
	v_mov_b32_e32 v14, v0
	v_mov_b32_e32 v15, v0
	v_mov_b32_e32 v24, v0
	v_mov_b32_e32 v25, v0
	v_mov_b32_e32 v26, v0
	v_mov_b32_e32 v27, v0
	v_mov_b32_e32 v28, v0
	v_mov_b32_e32 v29, v0
	v_mov_b32_e32 v30, v0
	v_mov_b32_e32 v31, v0
	v_mov_b32_e32 v40, v0
	v_mov_b32_e32 v41, v0
	v_mov_b32_e32 v42, v0
	v_mov_b32_e32 v43, v0
	v_mov_b32_e32 v44, v0
	v_mov_b32_e32 v45, v0
	v_mov_b32_e32 v46, v0
	v_mov_b32_e32 v47, v0
	v_mov_b32_e32 v56, v0
	v_mov_b32_e32 v57, v0
	v_mov_b32_e32 v58, v0
	v_mov_b32_e32 v59, v0
	v_mov_b32_e32 v60, v0
	v_mov_b32_e32 v61, v0
	v_mov_b32_e32 v62, v0
	v_mov_b32_e32 v63, v0
	v_mov_b32_e32 v64, v0
	v_mov_b32_e32 v65, v0
	v_mov_b32_e32 v66, v0
	v_mov_b32_e32 v67, v0
	v_mov_b32_e32 v68, v0
	v_mov_b32_e32 v69, v0
	v_mov_b32_e32 v70, v0
	v_mov_b32_e32 v71, v0
	v_mov_b32_e32 v80, v0
	v_mov_b32_e32 v81, v0
	v_mov_b32_e32 v82, v0
	v_mov_b32_e32 v83, v0
	v_mov_b32_e32 v84, v0
	v_mov_b32_e32 v85, v0
	v_mov_b32_e32 v86, v0
	v_mov_b32_e32 v87, v0
	v_mov_b32_e32 v96, v0
	v_mov_b32_e32 v97, v0
	v_mov_b32_e32 v98, v0
	v_mov_b32_e32 v99, v0
	v_mov_b32_e32 v100, v0
	v_mov_b32_e32 v101, v0
	v_mov_b32_e32 v102, v0
	v_mov_b32_e32 v103, v0
	v_mov_b32_e32 v112, v0
	v_mov_b32_e32 v113, v0
	v_mov_b32_e32 v114, v0
	v_mov_b32_e32 v115, v0
	v_mov_b32_e32 v116, v0
	v_mov_b32_e32 v117, v0
	v_mov_b32_e32 v118, v0
	v_mov_b32_e32 v119, v0
	v_mov_b32_e32 v72, v0
	v_mov_b32_e32 v73, v0
	v_mov_b32_e32 v74, v0
	v_mov_b32_e32 v75, v0
	v_mov_b32_e32 v76, v0
	v_mov_b32_e32 v77, v0
	v_mov_b32_e32 v78, v0
	v_mov_b32_e32 v79, v0
	v_mov_b32_e32 v88, v0
	v_mov_b32_e32 v89, v0
	v_mov_b32_e32 v90, v0
	v_mov_b32_e32 v91, v0
	v_mov_b32_e32 v92, v0
	v_mov_b32_e32 v93, v0
	v_mov_b32_e32 v94, v0
	v_mov_b32_e32 v95, v0
	v_mov_b32_e32 v104, v0
	v_mov_b32_e32 v105, v0
	v_mov_b32_e32 v106, v0
	v_mov_b32_e32 v107, v0
	v_mov_b32_e32 v108, v0
	v_mov_b32_e32 v109, v0
	v_mov_b32_e32 v110, v0
	v_mov_b32_e32 v111, v0
	v_mov_b32_e32 v120, v0
	v_mov_b32_e32 v121, v0
	v_mov_b32_e32 v122, v0
	v_mov_b32_e32 v123, v0
	v_mov_b32_e32 v124, v0
	v_mov_b32_e32 v125, v0
	v_mov_b32_e32 v126, v0
	v_add_u32_e32 v252, 0x18000, v205
	v_add_u32_e32 v253, 0x1c000, v205
	v_mov_b32_e32 v127, v0
.LBB0_353:
	ds_read_b128 v[128:131], v207
	ds_read_b128 v[132:135], v207 offset:1024
	ds_read_b128 v[136:139], v207 offset:2048
	ds_read_b128 v[140:143], v207 offset:3072
	s_add_u32 s42, s38, 0xfffc0080
	s_addc_u32 s43, s39, -1
	s_cmp_eq_u32 s41, 12
	s_cselect_b32 s45, s1, s43
	s_cselect_b32 s44, s0, s42
	s_cselect_b32 s43, s25, s23
	s_cselect_b32 s42, s24, s21
	s_add_i32 m0, s54, 0xc000
	ds_read_b128 v[144:147], v209
	ds_read_b128 v[148:151], v209 offset:1024
	ds_read_b128 v[152:155], v209 offset:2048
	ds_read_b128 v[156:159], v209 offset:3072
	ds_read_b128 v[160:163], v209 offset:4096
	ds_read_b128 v[164:167], v209 offset:5120
	ds_read_b128 v[168:171], v209 offset:6144
	ds_read_b128 v[172:175], v209 offset:7168
	global_load_lds_dwordx4 v184, s[38:39]
	s_add_i32 m0, s54, 0xe000
	s_nop 0
	global_load_lds_dwordx4 v186, s[38:39]
	s_waitcnt lgkmcnt(8)
	s_barrier
	s_waitcnt lgkmcnt(0)
	v_mfma_f32_16x16x32_bf16 v[124:127], v[128:131], v[144:147], v[124:127]
	v_mfma_f32_16x16x32_bf16 v[124:127], v[132:135], v[148:151], v[124:127]
	v_mfma_f32_16x16x32_bf16 v[120:123], v[140:143], v[148:151], v[120:123]
	v_mfma_f32_16x16x32_bf16 v[120:123], v[136:139], v[144:147], v[120:123]
	v_mfma_f32_16x16x32_bf16 v[104:107], v[136:139], v[152:155], v[104:107]
	v_mfma_f32_16x16x32_bf16 v[104:107], v[140:143], v[156:159], v[104:107]
	v_mfma_f32_16x16x32_bf16 v[108:111], v[132:135], v[156:159], v[108:111]
	v_mfma_f32_16x16x32_bf16 v[108:111], v[128:131], v[152:155], v[108:111]
	v_mfma_f32_16x16x32_bf16 v[92:95], v[128:131], v[160:163], v[92:95]
	v_mfma_f32_16x16x32_bf16 v[92:95], v[132:135], v[164:167], v[92:95]
	v_mfma_f32_16x16x32_bf16 v[88:91], v[140:143], v[164:167], v[88:91]
	v_mfma_f32_16x16x32_bf16 v[88:91], v[136:139], v[160:163], v[88:91]
	v_mfma_f32_16x16x32_bf16 v[72:75], v[136:139], v[168:171], v[72:75]
	v_mfma_f32_16x16x32_bf16 v[72:75], v[140:143], v[172:175], v[72:75]
	v_mfma_f32_16x16x32_bf16 v[76:79], v[132:135], v[172:175], v[76:79]
	v_mfma_f32_16x16x32_bf16 v[76:79], v[128:131], v[168:171], v[76:79]
	s_barrier
; #define PG8_STAGE(bufoff, gbase, voff) do { _Pragma("unroll") for (int _i = 0; _i < 2; ++_i) \
;         __builtin_amdgcn_global_load_lds((const unsigned*)((const char*)(gbase) + (voff)[_i]), (LAS unsigned*)(lds + (bufoff) + ldsw + _i * 8192), 16, 0, 0); } while (0)
; #define PG8_LDA(dst, b, h) do { _Pragma("unroll") for (int m = 0; m < 4; ++m) _Pragma("unroll") for (int k = 0; k < 2; ++k) dst[m][k] = *(const LAS bf16x8*)(lds + PG8_SA(b, h) + aoff + m * 2048 + k * 1024); } while (0)
; #define PG8_LDB(dst, b, h) do { _Pragma("unroll") for (int n = 0; n < 2; ++n) _Pragma("unroll") for (int k = 0; k < 2; ++k) dst[n][k] = *(const LAS bf16x8*)(lds + PG8_SB(b, h) + boff + n * 2048 + k * 1024); } while (0)
; #define PG8_MMA(ai, bj, At, Bt) do { __builtin_amdgcn_s_setprio(1); _Pragma("unroll") for (int m = 0; m < 4; ++m) _Pragma("unroll") for (int n = 0; n < 2; ++n) _Pragma("unroll") for (int k = 0; k < 2; ++k) \
;         acc[ai][bj][m][n] = __builtin_amdgcn_mfma_f32_16x16x32_bf16(Bt[n][k], At[m][k], acc[ai][bj][m][n], 0, 0, 0); __builtin_amdgcn_s_setprio(0); } while (0)
; #define PG8_WAIT_V(n) asm volatile("s_waitcnt vmcnt(" #n ")" ::: "memory")
; #define PG8_WAIT_L(n) asm volatile("s_waitcnt lgkmcnt(" #n ")" ::: "memory")
; #define PG8_BAR __builtin_amdgcn_s_barrier()
; #define PG8_SCHED __builtin_amdgcn_sched_barrier(0)
; template <class Epi, class Ptrs>
; __device__ __forceinline__ void gemm_phase(LAS unsigned char* lds, const int K, const StaticOrder& S, const Ptrs& P, const Epi& E) {
;     ...
;             PG8_LDB(B1, 0, 1); PG8_STAGE(PG8_SB(0, 0), b2, voffB);
;             PG8_BAR; PG8_WAIT_L(0); PG8_MMA(0, 1, At, B1); PG8_BAR;
;             PG8_LDA(At, 0, 1); PG8_STAGE(PG8_SA(0, 0), a2, voffA);
;             PG8_BAR; PG8_WAIT_L(0); PG8_MMA(1, 0, At, B0); PG8_BAR; PG8_SCHED;
;             PG8_STAGE(PG8_SB(0, 1), b2 + hstep, voffB);
;             PG8_WAIT_V(6); PG8_BAR; PG8_MMA(1, 1, At, B1); PG8_BAR;
;             PG8_LDB(B0, 1, 0); PG8_SCHED; PG8_LDA(At, 1, 0); PG8_STAGE(PG8_SA(0, 1), a2 + hstep, voffA);
;             PG8_WAIT_L(8); PG8_BAR; PG8_WAIT_L(0); PG8_MMA(0, 0, At, B0); PG8_BAR; PG8_SCHED;
	s_add_i32 s69, s66, s51
	s_add_u32 s90, s42, 0x80
	s_addc_u32 s91, s43, 0
	s_mov_b32 m0, s69
	ds_read_b128 v[192:195], v210
	ds_read_b128 v[196:199], v210 offset:1024
	ds_read_b128 v[200:203], v210 offset:2048
	ds_read_b128 v[212:215], v210 offset:3072
	global_load_lds_dwordx4 v178, s[42:43]
	s_add_i32 m0, s69, 0x2000
	s_nop 0
	global_load_lds_dwordx4 v182, s[42:43]
	s_barrier
	s_waitcnt lgkmcnt(0)
	v_mfma_f32_16x16x32_bf16 v[116:119], v[192:195], v[144:147], v[116:119]
	v_mfma_f32_16x16x32_bf16 v[116:119], v[196:199], v[148:151], v[116:119]
	v_mfma_f32_16x16x32_bf16 v[112:115], v[212:215], v[148:151], v[112:115]
	v_mfma_f32_16x16x32_bf16 v[112:115], v[200:203], v[144:147], v[112:115]
	v_mfma_f32_16x16x32_bf16 v[96:99], v[200:203], v[152:155], v[96:99]
	v_mfma_f32_16x16x32_bf16 v[96:99], v[212:215], v[156:159], v[96:99]
	v_mfma_f32_16x16x32_bf16 v[100:103], v[196:199], v[156:159], v[100:103]
	v_mfma_f32_16x16x32_bf16 v[100:103], v[192:195], v[152:155], v[100:103]
	v_mfma_f32_16x16x32_bf16 v[84:87], v[192:195], v[160:163], v[84:87]
	v_mfma_f32_16x16x32_bf16 v[84:87], v[196:199], v[164:167], v[84:87]
	v_mfma_f32_16x16x32_bf16 v[80:83], v[212:215], v[164:167], v[80:83]
	v_mfma_f32_16x16x32_bf16 v[80:83], v[200:203], v[160:163], v[80:83]
	v_mfma_f32_16x16x32_bf16 v[64:67], v[200:203], v[168:171], v[64:67]
	v_mfma_f32_16x16x32_bf16 v[64:67], v[212:215], v[172:175], v[64:67]
	v_mfma_f32_16x16x32_bf16 v[68:71], v[196:199], v[172:175], v[68:71]
	v_mfma_f32_16x16x32_bf16 v[68:71], v[192:195], v[168:171], v[68:71]
	s_barrier
	s_mov_b32 m0, s54
	s_add_u32 s92, s44, 0x80
	s_addc_u32 s93, s45, 0
	ds_read_b128 v[144:147], v209 offset:16384
	ds_read_b128 v[148:151], v209 offset:17408
	ds_read_b128 v[152:155], v209 offset:18432
	ds_read_b128 v[156:159], v209 offset:19456
	ds_read_b128 v[160:163], v209 offset:20480
	ds_read_b128 v[164:167], v209 offset:21504
	ds_read_b128 v[168:171], v209 offset:22528
	ds_read_b128 v[172:175], v209 offset:23552
	global_load_lds_dwordx4 v176, s[44:45]
	s_mov_b32 m0, s55
	s_nop 0
	global_load_lds_dwordx4 v180, s[44:45]
	s_barrier
	s_waitcnt lgkmcnt(0)
	v_mfma_f32_16x16x32_bf16 v[60:63], v[128:131], v[144:147], v[60:63]
	v_mfma_f32_16x16x32_bf16 v[60:63], v[132:135], v[148:151], v[60:63]
	v_mfma_f32_16x16x32_bf16 v[56:59], v[140:143], v[148:151], v[56:59]
	v_mfma_f32_16x16x32_bf16 v[56:59], v[136:139], v[144:147], v[56:59]
	v_mfma_f32_16x16x32_bf16 v[40:43], v[136:139], v[152:155], v[40:43]
	v_mfma_f32_16x16x32_bf16 v[40:43], v[140:143], v[156:159], v[40:43]
	v_mfma_f32_16x16x32_bf16 v[44:47], v[132:135], v[156:159], v[44:47]
	v_mfma_f32_16x16x32_bf16 v[44:47], v[128:131], v[152:155], v[44:47]
	v_mfma_f32_16x16x32_bf16 v[28:31], v[128:131], v[160:163], v[28:31]
	v_mfma_f32_16x16x32_bf16 v[28:31], v[132:135], v[164:167], v[28:31]
	v_mfma_f32_16x16x32_bf16 v[24:27], v[140:143], v[164:167], v[24:27]
	v_mfma_f32_16x16x32_bf16 v[24:27], v[136:139], v[160:163], v[24:27]
	v_mfma_f32_16x16x32_bf16 v[8:11], v[136:139], v[168:171], v[8:11]
	v_mfma_f32_16x16x32_bf16 v[8:11], v[140:143], v[172:175], v[8:11]
	v_mfma_f32_16x16x32_bf16 v[12:15], v[132:135], v[172:175], v[12:15]
	v_mfma_f32_16x16x32_bf16 v[12:15], v[128:131], v[168:171], v[12:15]
	s_barrier
	s_add_u32 s70, s42, 0x40000
	s_addc_u32 s71, s43, 0
	s_add_i32 s69, s67, s51
	s_mov_b32 m0, s69
	s_nop 0
	global_load_lds_dwordx4 v178, s[70:71]
	s_add_i32 m0, s69, 0x2000
	s_nop 0
	global_load_lds_dwordx4 v182, s[70:71]
	s_waitcnt vmcnt(6)
	s_barrier
	v_mfma_f32_16x16x32_bf16 v[52:55], v[192:195], v[144:147], v[52:55]
	v_mfma_f32_16x16x32_bf16 v[52:55], v[196:199], v[148:151], v[52:55]
	v_mfma_f32_16x16x32_bf16 v[48:51], v[212:215], v[148:151], v[48:51]
	v_mfma_f32_16x16x32_bf16 v[48:51], v[200:203], v[144:147], v[48:51]
	v_mfma_f32_16x16x32_bf16 v[32:35], v[200:203], v[152:155], v[32:35]
	v_mfma_f32_16x16x32_bf16 v[32:35], v[212:215], v[156:159], v[32:35]
	v_mfma_f32_16x16x32_bf16 v[36:39], v[196:199], v[156:159], v[36:39]
	v_mfma_f32_16x16x32_bf16 v[36:39], v[192:195], v[152:155], v[36:39]
	v_mfma_f32_16x16x32_bf16 v[20:23], v[192:195], v[160:163], v[20:23]
	v_mfma_f32_16x16x32_bf16 v[20:23], v[196:199], v[164:167], v[20:23]
	v_mfma_f32_16x16x32_bf16 v[16:19], v[212:215], v[164:167], v[16:19]
	v_mfma_f32_16x16x32_bf16 v[16:19], v[200:203], v[160:163], v[16:19]
	v_mfma_f32_16x16x32_bf16 v[0:3], v[200:203], v[168:171], v[0:3]
	v_mfma_f32_16x16x32_bf16 v[0:3], v[212:215], v[172:175], v[0:3]
	v_mfma_f32_16x16x32_bf16 v[4:7], v[196:199], v[172:175], v[4:7]
	v_mfma_f32_16x16x32_bf16 v[4:7], v[192:195], v[168:171], v[4:7]
	s_barrier
	s_add_i32 s69, 0, 0x18000
	ds_read_b128 v[128:131], v252
	ds_read_b128 v[132:135], v252 offset:1024
	ds_read_b128 v[136:139], v252 offset:2048
	ds_read_b128 v[140:143], v252 offset:3072
	s_add_u32 s44, s44, 0x40000
	s_addc_u32 s45, s45, 0
	s_mov_b32 m0, s56
	ds_read_b128 v[144:147], v209 offset:32768
	ds_read_b128 v[148:151], v209 offset:33792
	ds_read_b128 v[152:155], v209 offset:34816
	ds_read_b128 v[156:159], v209 offset:35840
	ds_read_b128 v[160:163], v209 offset:36864
	ds_read_b128 v[164:167], v209 offset:37888
	ds_read_b128 v[168:171], v209 offset:38912
	ds_read_b128 v[172:175], v209 offset:39936
	global_load_lds_dwordx4 v176, s[44:45]
	s_mov_b32 m0, s57
	s_nop 0
	global_load_lds_dwordx4 v180, s[44:45]
	s_waitcnt lgkmcnt(8)
	s_barrier
; #define PG8_STAGE(bufoff, gbase, voff) do { _Pragma("unroll") for (int _i = 0; _i < 2; ++_i) \
;         __builtin_amdgcn_global_load_lds((const unsigned*)((const char*)(gbase) + (voff)[_i]), (LAS unsigned*)(lds + (bufoff) + ldsw + _i * 8192), 16, 0, 0); } while (0)
; #define PG8_LDA(dst, b, h) do { _Pragma("unroll") for (int m = 0; m < 4; ++m) _Pragma("unroll") for (int k = 0; k < 2; ++k) dst[m][k] = *(const LAS bf16x8*)(lds + PG8_SA(b, h) + aoff + m * 2048 + k * 1024); } while (0)
; #define PG8_LDB(dst, b, h) do { _Pragma("unroll") for (int n = 0; n < 2; ++n) _Pragma("unroll") for (int k = 0; k < 2; ++k) dst[n][k] = *(const LAS bf16x8*)(lds + PG8_SB(b, h) + boff + n * 2048 + k * 1024); } while (0)
; #define PG8_MMA(ai, bj, At, Bt) do { __builtin_amdgcn_s_setprio(1); _Pragma("unroll") for (int m = 0; m < 4; ++m) _Pragma("unroll") for (int n = 0; n < 2; ++n) _Pragma("unroll") for (int k = 0; k < 2; ++k) \
;         acc[ai][bj][m][n] = __builtin_amdgcn_mfma_f32_16x16x32_bf16(Bt[n][k], At[m][k], acc[ai][bj][m][n], 0, 0, 0); __builtin_amdgcn_s_setprio(0); } while (0)
; #define PG8_WAIT_V(n) asm volatile("s_waitcnt vmcnt(" #n ")" ::: "memory")
; #define PG8_WAIT_L(n) asm volatile("s_waitcnt lgkmcnt(" #n ")" ::: "memory")
; #define PG8_BAR __builtin_amdgcn_s_barrier()
; #define PG8_SCHED __builtin_amdgcn_sched_barrier(0)
; template <class Epi, class Ptrs>
; __device__ __forceinline__ void gemm_phase(LAS unsigned char* lds, const int K, const StaticOrder& S, const Ptrs& P, const Epi& E) {
;     ...
;             PG8_WAIT_L(8); PG8_BAR; PG8_WAIT_L(0); PG8_MMA(0, 0, At, B0); PG8_BAR; PG8_SCHED;
;             PG8_LDB(B1, 1, 1); PG8_STAGE(PG8_SB(1, 0), b3, voffB);
;             PG8_BAR; PG8_WAIT_L(0); PG8_MMA(0, 1, At, B1); PG8_BAR;
;             PG8_LDA(At, 1, 1); PG8_STAGE(PG8_SA(1, 0), a3, voffA);
;             PG8_BAR; PG8_WAIT_L(0); PG8_MMA(1, 0, At, B0); PG8_BAR; PG8_SCHED;
;             PG8_STAGE(PG8_SB(1, 1), b3 + hstep, voffB);
;             PG8_WAIT_V(6); PG8_BAR; PG8_MMA(1, 1, At, B1); PG8_BAR;
	s_waitcnt lgkmcnt(0)
	v_mfma_f32_16x16x32_bf16 v[124:127], v[128:131], v[144:147], v[124:127]
	v_mfma_f32_16x16x32_bf16 v[124:127], v[132:135], v[148:151], v[124:127]
	v_mfma_f32_16x16x32_bf16 v[120:123], v[140:143], v[148:151], v[120:123]
	v_mfma_f32_16x16x32_bf16 v[120:123], v[136:139], v[144:147], v[120:123]
	v_mfma_f32_16x16x32_bf16 v[104:107], v[136:139], v[152:155], v[104:107]
	v_mfma_f32_16x16x32_bf16 v[104:107], v[140:143], v[156:159], v[104:107]
	v_mfma_f32_16x16x32_bf16 v[108:111], v[132:135], v[156:159], v[108:111]
	v_mfma_f32_16x16x32_bf16 v[108:111], v[128:131], v[152:155], v[108:111]
	v_mfma_f32_16x16x32_bf16 v[92:95], v[128:131], v[160:163], v[92:95]
	v_mfma_f32_16x16x32_bf16 v[92:95], v[132:135], v[164:167], v[92:95]
	v_mfma_f32_16x16x32_bf16 v[88:91], v[140:143], v[164:167], v[88:91]
	v_mfma_f32_16x16x32_bf16 v[88:91], v[136:139], v[160:163], v[88:91]
	v_mfma_f32_16x16x32_bf16 v[72:75], v[136:139], v[168:171], v[72:75]
	v_mfma_f32_16x16x32_bf16 v[72:75], v[140:143], v[172:175], v[72:75]
	v_mfma_f32_16x16x32_bf16 v[76:79], v[132:135], v[172:175], v[76:79]
	v_mfma_f32_16x16x32_bf16 v[76:79], v[128:131], v[168:171], v[76:79]
	s_barrier
	s_add_i32 s44, 0, 0x1c000
	s_add_i32 s45, s69, s51
	s_mov_b32 m0, s45
	ds_read_b128 v[192:195], v253
	ds_read_b128 v[196:199], v253 offset:1024
	ds_read_b128 v[200:203], v253 offset:2048
	ds_read_b128 v[212:215], v253 offset:3072
	global_load_lds_dwordx4 v178, s[90:91]
	s_add_i32 m0, s45, 0x2000
	s_nop 0
	global_load_lds_dwordx4 v182, s[90:91]
	s_barrier
	s_waitcnt lgkmcnt(0)
	v_mfma_f32_16x16x32_bf16 v[116:119], v[192:195], v[144:147], v[116:119]
	v_mfma_f32_16x16x32_bf16 v[116:119], v[196:199], v[148:151], v[116:119]
	v_mfma_f32_16x16x32_bf16 v[112:115], v[212:215], v[148:151], v[112:115]
	v_mfma_f32_16x16x32_bf16 v[112:115], v[200:203], v[144:147], v[112:115]
	v_mfma_f32_16x16x32_bf16 v[96:99], v[200:203], v[152:155], v[96:99]
	v_mfma_f32_16x16x32_bf16 v[96:99], v[212:215], v[156:159], v[96:99]
	v_mfma_f32_16x16x32_bf16 v[100:103], v[196:199], v[156:159], v[100:103]
	v_mfma_f32_16x16x32_bf16 v[100:103], v[192:195], v[152:155], v[100:103]
	v_mfma_f32_16x16x32_bf16 v[84:87], v[192:195], v[160:163], v[84:87]
	v_mfma_f32_16x16x32_bf16 v[84:87], v[196:199], v[164:167], v[84:87]
	v_mfma_f32_16x16x32_bf16 v[80:83], v[212:215], v[164:167], v[80:83]
	v_mfma_f32_16x16x32_bf16 v[80:83], v[200:203], v[160:163], v[80:83]
	v_mfma_f32_16x16x32_bf16 v[64:67], v[200:203], v[168:171], v[64:67]
	v_mfma_f32_16x16x32_bf16 v[64:67], v[212:215], v[172:175], v[64:67]
	v_mfma_f32_16x16x32_bf16 v[68:71], v[196:199], v[172:175], v[68:71]
	v_mfma_f32_16x16x32_bf16 v[68:71], v[192:195], v[168:171], v[68:71]
	s_barrier
	s_mov_b32 m0, s63
	ds_read_b128 v[144:147], v209 offset:49152
	ds_read_b128 v[148:151], v209 offset:50176
	ds_read_b128 v[152:155], v209 offset:51200
	ds_read_b128 v[156:159], v209 offset:52224
	ds_read_b128 v[160:163], v209 offset:53248
	ds_read_b128 v[164:167], v209 offset:54272
	ds_read_b128 v[168:171], v209 offset:55296
	ds_read_b128 v[172:175], v209 offset:56320
	global_load_lds_dwordx4 v176, s[92:93]
	s_mov_b32 m0, s64
	s_nop 0
	global_load_lds_dwordx4 v180, s[92:93]
	s_barrier
	s_waitcnt lgkmcnt(0)
	v_mfma_f32_16x16x32_bf16 v[60:63], v[128:131], v[144:147], v[60:63]
	v_mfma_f32_16x16x32_bf16 v[60:63], v[132:135], v[148:151], v[60:63]
	v_mfma_f32_16x16x32_bf16 v[56:59], v[140:143], v[148:151], v[56:59]
	v_mfma_f32_16x16x32_bf16 v[56:59], v[136:139], v[144:147], v[56:59]
	v_mfma_f32_16x16x32_bf16 v[40:43], v[136:139], v[152:155], v[40:43]
	v_mfma_f32_16x16x32_bf16 v[40:43], v[140:143], v[156:159], v[40:43]
	v_mfma_f32_16x16x32_bf16 v[44:47], v[132:135], v[156:159], v[44:47]
	v_mfma_f32_16x16x32_bf16 v[44:47], v[128:131], v[152:155], v[44:47]
	v_mfma_f32_16x16x32_bf16 v[28:31], v[128:131], v[160:163], v[28:31]
	v_mfma_f32_16x16x32_bf16 v[28:31], v[132:135], v[164:167], v[28:31]
	v_mfma_f32_16x16x32_bf16 v[24:27], v[140:143], v[164:167], v[24:27]
	v_mfma_f32_16x16x32_bf16 v[24:27], v[136:139], v[160:163], v[24:27]
	v_mfma_f32_16x16x32_bf16 v[8:11], v[136:139], v[168:171], v[8:11]
	v_mfma_f32_16x16x32_bf16 v[8:11], v[140:143], v[172:175], v[8:11]
	v_mfma_f32_16x16x32_bf16 v[12:15], v[132:135], v[172:175], v[12:15]
	v_mfma_f32_16x16x32_bf16 v[12:15], v[128:131], v[168:171], v[12:15]
	s_barrier
	s_add_u32 s42, s42, 0x40080
	s_addc_u32 s43, s43, 0
	s_add_i32 s44, s44, s51
	s_mov_b32 m0, s44
	s_nop 0
	global_load_lds_dwordx4 v178, s[42:43]
	s_add_i32 m0, s44, 0x2000
	s_nop 0
	global_load_lds_dwordx4 v182, s[42:43]
	s_waitcnt vmcnt(6)
	s_barrier
	v_mfma_f32_16x16x32_bf16 v[52:55], v[192:195], v[144:147], v[52:55]
	v_mfma_f32_16x16x32_bf16 v[52:55], v[196:199], v[148:151], v[52:55]
	v_mfma_f32_16x16x32_bf16 v[48:51], v[212:215], v[148:151], v[48:51]
	v_mfma_f32_16x16x32_bf16 v[48:51], v[200:203], v[144:147], v[48:51]
	v_mfma_f32_16x16x32_bf16 v[32:35], v[200:203], v[152:155], v[32:35]
	v_mfma_f32_16x16x32_bf16 v[32:35], v[212:215], v[156:159], v[32:35]
	v_mfma_f32_16x16x32_bf16 v[36:39], v[196:199], v[156:159], v[36:39]
	v_mfma_f32_16x16x32_bf16 v[36:39], v[192:195], v[152:155], v[36:39]
	v_mfma_f32_16x16x32_bf16 v[20:23], v[192:195], v[160:163], v[20:23]
	v_mfma_f32_16x16x32_bf16 v[20:23], v[196:199], v[164:167], v[20:23]
	v_mfma_f32_16x16x32_bf16 v[16:19], v[212:215], v[164:167], v[16:19]
	v_mfma_f32_16x16x32_bf16 v[16:19], v[200:203], v[160:163], v[16:19]
	v_mfma_f32_16x16x32_bf16 v[0:3], v[200:203], v[168:171], v[0:3]
	v_mfma_f32_16x16x32_bf16 v[0:3], v[212:215], v[172:175], v[0:3]
	v_mfma_f32_16x16x32_bf16 v[4:7], v[196:199], v[172:175], v[4:7]
	v_mfma_f32_16x16x32_bf16 v[4:7], v[192:195], v[168:171], v[4:7]
	s_barrier
; __device__ __forceinline__ unsigned cvt_pk_bf16(float lo, float hi) { unsigned r; asm volatile("v_cvt_pk_bf16_f32 %0, %1, %2" : "=v"(r) : "v"(lo), "v"(hi)); return r; }
; __device__ __forceinline__ float x16_sum(float x) { auto s = __builtin_amdgcn_permlane16_swap(__float_as_uint(x), __float_as_uint(x), false, false); return __uint_as_float(s[0]) + __uint_as_float(s[1]); }
; __device__ __forceinline__ float x32_sum(float x) { auto s = __builtin_amdgcn_permlane32_swap(__float_as_uint(x), __float_as_uint(x), false, false); return __uint_as_float(s[0]) + __uint_as_float(s[1]); }
;     __device__ __forceinline__ void operator()(const f32x4 (&acc)[2][2][4][2], const Unit& u, int ui, int wr, int wc, int fr, int fq) const {
;         const int row0 = u.pm * 256 + wr * 64 + fr, col0 = u.pn * 256 + wc * 32 + 8 * fq;
;         const float* xb0 = (u.pm * 256 < MP) ? xp : xs - (size_t)MP * DM;
; #pragma unroll
;         for (int ai = 0; ai < 2; ++ai) {
;             f32x4 xv[4][2][2];
; #pragma unroll
;             for (int m = 0; m < 4; ++m)
; #pragma unroll
;                 for (int bj = 0; bj < 2; ++bj) { const float* p = xb0 + (size_t)(row0 + ai * 128 + m * 16) * DM + col0 + bj * 128; xv[m][bj][0] = *(const f32x4*)p; xv[m][bj][1] = *(const f32x4*)(p + 4); }
; #pragma unroll
;             for (int m = 0; m < 4; ++m) { const int row = row0 + ai * 128 + m * 16; const size_t off = (size_t)row * DM + col0; float ss = 0.f;
; #pragma unroll
;                 for (int bj = 0; bj < 2; ++bj) {
;                     const f32x4 v0 = acc[ai][bj][m][0] + xv[m][bj][0], v1 = acc[ai][bj][m][1] + xv[m][bj][1];
;                     u32x4 w; w.x = cvt_pk_bf16(v0[0], v0[1]); w.y = cvt_pk_bf16(v0[2], v0[3]); w.z = cvt_pk_bf16(v1[0], v1[1]); w.w = cvt_pk_bf16(v1[2], v1[3]);
;                     *(u32x4*)(xb + off + bj * 128) = w;
;                     ss += (v0[0] * v0[0] + v0[1] * v0[1]) + (v0[2] * v0[2] + v0[3] * v0[3]) + (v1[0] * v1[0] + v1[1] * v1[1]) + (v1[2] * v1[2] + v1[3] * v1[3]); }
;                 ss = x32_sum(x16_sum(ss));
;                 if (fq == 0) part[(size_t)row * 16 + u.pn * 4 + wc] = ss; }
	s_add_i32 s41, s41, 2
	s_add_u32 s38, s38, 0x100
	s_addc_u32 s39, s39, 0
	s_add_u32 s21, s21, 0x100
	s_addc_u32 s23, s23, 0
	s_cmp_gt_u32 s41, 13
	s_cbranch_scc0 .LBB0_353
	s_nop 0
	s_nop 0
	s_nop 0
	s_nop 0
	s_nop 0
	s_nop 0
	s_nop 0
	s_nop 0
	s_nop 0
	s_nop 0
	s_nop 0
	s_nop 0
	s_nop 0
	s_nop 0
	s_nop 0
	s_nop 0
	s_nop 0
	s_nop 0
	s_nop 0
	s_nop 0
	s_nop 0
	s_nop 0
	s_nop 0
	s_nop 0
	s_nop 0
	s_nop 0
	s_nop 0
	s_nop 0
	s_nop 0
	s_nop 0
	s_nop 0
	s_nop 0
	s_nop 0
	s_nop 0
	s_nop 0
	s_nop 0
	s_nop 0
	s_nop 0
	s_nop 0
	s_nop 0
	s_nop 0
	s_nop 0
	s_nop 0
	s_nop 0
	s_nop 0
	s_nop 0
	s_nop 0
	s_nop 0
	s_nop 0
	s_nop 0
	s_cmpk_lt_i32 s40, 0x80
	v_lshl_add_u32 v194, s40, 8, v204
	v_lshl_or_b32 v192, s12, 8, v206
	s_cselect_b32 s21, s37, s61
	s_cselect_b32 s23, s36, s60
	v_mov_b32_e32 v128, s23
	v_mov_b32_e32 v129, s21
	v_ashrrev_i32_e32 v193, 31, v192
	v_ashrrev_i32_e32 v195, 31, v194
	v_lshl_add_u64 v[196:197], v[192:193], 2, v[128:129]
	v_lshlrev_b64 v[128:129], 12, v[194:195]
	v_or_b32_e32 v202, 16, v194
	v_or_b32_e32 v200, 32, v194
	v_or_b32_e32 v198, 48, v194
	v_lshl_add_u64 v[128:129], v[196:197], 0, v[128:129]
	v_ashrrev_i32_e32 v203, 31, v202
	v_ashrrev_i32_e32 v201, 31, v200
	v_ashrrev_i32_e32 v199, 31, v198
	global_load_dwordx4 v[212:215], v[128:129], off
	global_load_dwordx4 v[216:219], v[128:129], off offset:16
	global_load_dwordx4 v[220:223], v[128:129], off offset:512
	global_load_dwordx4 v[224:227], v[128:129], off offset:528
	v_lshlrev_b64 v[128:129], 12, v[202:203]
	v_lshlrev_b64 v[130:131], 12, v[200:201]
	v_lshlrev_b64 v[132:133], 12, v[198:199]
	v_lshl_add_u64 v[128:129], v[196:197], 0, v[128:129]
	v_lshl_add_u64 v[130:131], v[196:197], 0, v[130:131]
	v_lshl_add_u64 v[132:133], v[196:197], 0, v[132:133]
	global_load_dwordx4 v[168:171], v[128:129], off offset:16
	global_load_dwordx4 v[172:175], v[128:129], off
	global_load_dwordx4 v[160:163], v[128:129], off offset:528
	global_load_dwordx4 v[164:167], v[128:129], off offset:512
	global_load_dwordx4 v[152:155], v[130:131], off offset:16
	global_load_dwordx4 v[156:159], v[130:131], off
	global_load_dwordx4 v[144:147], v[130:131], off offset:528
	global_load_dwordx4 v[148:151], v[130:131], off offset:512
	global_load_dwordx4 v[136:139], v[132:133], off offset:16
	global_load_dwordx4 v[140:143], v[132:133], off
	s_nop 0
	global_load_dwordx4 v[128:131], v[132:133], off offset:528
	s_nop 0
	global_load_dwordx4 v[132:135], v[132:133], off offset:512
	v_lshlrev_b64 v[228:229], 11, v[194:195]
	v_lshl_add_u64 v[228:229], s[14:15], 0, v[228:229]
	v_lshl_add_u64 v[228:229], v[192:193], 1, v[228:229]
	s_lshl_b32 s38, s12, 2
	s_ashr_i32 s39, s38, 31
	s_waitcnt vmcnt(0)
	v_pk_add_f32 v[126:127], v[126:127], v[214:215]
	v_pk_add_f32 v[124:125], v[124:125], v[212:213]
	v_pk_add_f32 v[118:119], v[118:119], v[222:223]
	v_pk_add_f32 v[116:117], v[116:117], v[220:221]
	v_pk_add_f32 v[120:121], v[120:121], v[216:217]
	v_pk_add_f32 v[214:215], v[112:113], v[224:225]
	v_cvt_pk_bf16_f32 v112, v124, v125
	v_cvt_pk_bf16_f32 v113, v126, v127
	v_mul_f32_e32 v125, v125, v125
	v_mul_f32_e32 v127, v127, v127
	v_mul_f32_e32 v211, v117, v117
	v_mul_f32_e32 v216, v119, v119
	v_pk_add_f32 v[122:123], v[122:123], v[218:219]
	v_pk_add_f32 v[212:213], v[114:115], v[226:227]
	v_cvt_pk_bf16_f32 v114, v120, v121
	v_cvt_pk_bf16_f32 v115, v122, v123
	v_mul_f32_e32 v121, v121, v121
	v_mul_f32_e32 v217, v215, v215
	global_store_dwordx4 v[228:229], v[112:115], off
	v_fmac_f32_e32 v125, v124, v124
	v_fmac_f32_e32 v127, v126, v126
	v_cvt_pk_bf16_f32 v112, v116, v117
	v_fmac_f32_e32 v211, v116, v116
	v_fmac_f32_e32 v216, v118, v118
	v_mul_f32_e32 v123, v123, v123
	v_mul_f32_e32 v218, v213, v213
	v_fmac_f32_e32 v121, v120, v120
	v_cvt_pk_bf16_f32 v113, v118, v119
	v_cvt_pk_bf16_f32 v114, v214, v215
	v_cvt_pk_bf16_f32 v115, v212, v213
	v_fmac_f32_e32 v217, v214, v214
	v_add_f32_e32 v116, v125, v127
	global_store_dwordx4 v[228:229], v[112:115], off offset:256
	v_fmac_f32_e32 v123, v122, v122
	v_fmac_f32_e32 v218, v212, v212
	v_add_f32_e32 v112, v211, v216
	v_add_f32_e32 v113, v116, v121
	v_add_f32_e32 v112, v112, v217
	v_add_f32_e32 v113, v123, v113
	v_add_f32_e32 v112, v218, v112
	v_add_f32_e32 v112, v113, v112
	v_mov_b32_e32 v113, v112
	s_nop 1
	v_permlane16_swap_b32_e32 v112, v113
	v_add_f32_e32 v112, v112, v113
	v_mov_b32_e32 v113, v112
	s_nop 1
	v_permlane32_swap_b32_e32 v112, v113
	s_and_saveexec_b64 s[40:41], s[6:7]
	s_cbranch_execz .LBB0_356
	v_lshlrev_b64 v[114:115], 6, v[194:195]
	v_lshl_add_u64 v[114:115], s[16:17], 0, v[114:115]
	v_lshl_add_u64 v[114:115], s[38:39], 2, v[114:115]
	s_lshl_b32 s12, s62, 2
	v_lshl_add_u64 v[114:115], v[114:115], 0, s[12:13]
	v_add_f32_e32 v112, v112, v113
	global_store_dword v[114:115], v112, off

; #define PG8_STAGE(bufoff, gbase, voff) do { _Pragma("unroll") for (int _i = 0; _i < 2; ++_i) \
;         __builtin_amdgcn_global_load_lds((const unsigned*)((const char*)(gbase) + (voff)[_i]), (LAS unsigned*)(lds + (bufoff) + ldsw + _i * 8192), 16, 0, 0); } while (0)
; #define PG8_WAIT_V(n) asm volatile("s_waitcnt vmcnt(" #n ")" ::: "memory")
; #define PG8_BAR __builtin_amdgcn_s_barrier()
; template <class Epi, class Ptrs>
; __device__ __forceinline__ void gemm_phase(LAS unsigned char* lds, const int K, const StaticOrder& S, const Ptrs& P, const Epi& E) {
;     const int tid = threadIdx.x, wid = __builtin_amdgcn_readfirstlane(tid >> 6), lane = tid & 63, wr = wid >> 2, wc = wid & 3, fr = lane & 15, fq = lane >> 4;
;     const int nt = K / BK;
;     unsigned voffA[2], voffB[2];
; #pragma unroll
;     for (int i = 0; i < 2; ++i) { int R, C; stage_rc(tid * 16 + i * 8192, R, C); const int Rb = (R & ~31) + perm32(R & 31);
;         voffA[i] = (unsigned)(R * K + C) * 2u; voffB[i] = (unsigned)(Rb * K + C) * 2u; }
;     const size_t kstep = (size_t)(BK * 2);
;     const size_t hstep = (size_t)HALF * K * 2;
;     const unsigned ldsw = (unsigned)wid * 1024u;
;     const int aoff = lds_byte(wr * 64 + fr, fq * 8), boff = lds_byte(wc * 32 + fr, fq * 8);
;     ...
;     Unit cur, nxt; int ui = 0;
;     if (!S.next(0, cur)) return;
;     f32x4 acc[2][2][4][2];
; #pragma unroll
;     for (int a = 0; a < 2; ++a)
; #pragma unroll
;         for (int b = 0; b < 2; ++b)
; #pragma unroll
;             for (int m = 0; m < 4; ++m)
; #pragma unroll
;                 for (int n = 0; n < 2; ++n) acc[a][b][m][n] = (f32x4){0.f, 0.f, 0.f, 0.f};
;     bf16x8 At[4][2], B0[2][2], B1[2][2];
;     const char* cA; const char* cB; P.get(cur, cA, cB);
;     PG8_STAGE(PG8_SB(0, 0), cB, voffB); PG8_STAGE(PG8_SA(0, 0), cA, voffA); PG8_STAGE(PG8_SB(0, 1), cB + hstep, voffB); PG8_STAGE(PG8_SA(0, 1), cA + hstep, voffA);
;     if (wr == 1) PG8_BAR;
;     PG8_WAIT_V(4); PG8_BAR;
;     PG8_STAGE(PG8_SB(1, 0), cB + kstep, voffB); PG8_STAGE(PG8_SA(1, 0), cA + kstep, voffA); PG8_STAGE(PG8_SB(1, 1), cB + hstep + kstep, voffB);
;     PG8_WAIT_V(6); PG8_BAR;
.LBB0_427:
	s_nop 0
	s_nop 0
	s_nop 0
	s_nop 0
	s_nop 0
	s_nop 0
	s_nop 0
	s_nop 0
	s_nop 0
	s_nop 0
	s_nop 0
	s_nop 0
	s_nop 0
	s_nop 0
	s_nop 0
	s_nop 0
	s_nop 0
	s_nop 0
	s_nop 0
	s_nop 0
	s_nop 0
	s_nop 0
	s_nop 0
	s_nop 0
	s_nop 0
	s_nop 0
	s_nop 0
	s_nop 0
	s_nop 0
	s_nop 0
	s_nop 0
	s_nop 0
	s_nop 0
	s_nop 0
	s_nop 0
	s_nop 0
	s_nop 0
	s_nop 0
	s_nop 0
	s_nop 0
	s_nop 0
	s_nop 0
	s_nop 0
	s_nop 0
	s_nop 0
	s_nop 0
	s_nop 0
	s_nop 0
	s_nop 0
	s_nop 0
	s_add_u32 s10, s28, 0xe000000
	s_addc_u32 s11, s29, 0
	s_lshl_b32 s4, s4, 5
	s_mov_b64 s[12:13], 0x80
	s_and_b32 s15, s4, 0x60
	s_add_i32 m0, s39, 0x18000
	v_lshl_add_u64 v[6:7], v[6:7], 0, s[12:13]
	s_ashr_i32 s60, s3, 31
	s_lshl_b32 s14, s1, 13
	s_lshl_b32 s16, s15, 7
	s_waitcnt vmcnt(4)
	s_barrier
	global_load_lds_dwordx4 v[6:7], off
	v_lshl_add_u64 v[4:5], v[4:5], 0, s[12:13]
	s_add_i32 m0, s39, 0x1a000
	s_add_i32 s61, s39, 0x8000
	s_add_i32 s62, s39, 0xa000
	global_load_lds_dwordx4 v[4:5], off
	v_lshl_add_u64 v[2:3], v[2:3], 0, s[12:13]
	s_mov_b32 m0, s61
	s_add_u32 s4, s42, 0x40080
	global_load_lds_dwordx4 v[2:3], off
	v_lshl_add_u64 v[0:1], v[0:1], 0, s[12:13]
	s_mov_b32 m0, s62
	s_addc_u32 s5, s43, 0
	global_load_lds_dwordx4 v[0:1], off
	s_add_i32 m0, s39, 0x1c000
	v_lshl_add_u64 v[0:1], s[4:5], 0, v[130:131]
	global_load_lds_dwordx4 v[0:1], off
	v_lshl_add_u64 v[0:1], s[4:5], 0, v[134:135]
	s_add_i32 m0, s39, 0x1e000
	s_sext_i32_i8 s69, s0
	global_load_lds_dwordx4 v[0:1], off
	v_and_b32_e32 v0, 15, v208
	v_lshlrev_b32_e32 v1, 1, v11
	v_lshlrev_b32_e32 v2, 6, v208
	s_movk_i32 s0, 0x3c0
	v_lshlrev_b32_e32 v3, 2, v208
	v_and_or_b32 v2, v2, s0, v1
	v_and_b32_e32 v3, 32, v3
	v_lshl_or_b32 v146, s1, 6, v0
	v_lshl_or_b32 v0, v0, 6, v1
	v_lshlrev_b32_e32 v1, 8, v208
	v_bitop3_b32 v147, s16, v2, v3 bitop3:0xf6
	v_and_b32_e32 v1, 0x38000, v1
	v_lshlrev_b32_e32 v2, 11, v10
	v_or3_b32 v1, v8, v1, v2
	v_add_u32_e32 v136, v1, v9
	v_lshlrev_b32_e32 v1, 4, v12
	s_waitcnt vmcnt(6)
	v_and_b32_e32 v1, 0x78000, v1
	v_bitop3_b32 v0, v0, s14, v3 bitop3:0xde
	v_or3_b32 v1, v8, v1, v2
	s_add_i32 s63, 0, 0x10000
	s_add_i32 s64, 0, 0x14000
	v_or_b32_e32 v148, s15, v11
	v_mov_b32_e32 v137, v131
	v_add_u32_e32 v138, v1, v9
	v_mov_b32_e32 v139, v131
	v_mov_b64_e32 v[140:141], 0x1800
	v_mov_b64_e32 v[142:143], 0x17ff
	v_add_u32_e32 v149, s63, v147
	v_add_u32_e32 v150, 0, v0
	v_add_u32_e32 v151, s64, v147
	s_mov_b64 s[14:15], 0x100000
	s_mov_b32 s65, 0x100000
	s_mov_b64 s[16:17], 0x120000
	s_mov_b32 s66, 0x120000
	s_mov_b64 s[18:19], 0x140000
	s_mov_b32 s67, 0x140000
	s_mov_b64 s[20:21], 0x160000
	s_mov_b32 s68, 0x160000
	s_cmpk_lt_u32 s46, 0x100
	s_cbranch_scc1 .Lsprio_2
	s_setprio 1

; #define PG8_STAGE(bufoff, gbase, voff) do { _Pragma("unroll") for (int _i = 0; _i < 2; ++_i) \
;         __builtin_amdgcn_global_load_lds((const unsigned*)((const char*)(gbase) + (voff)[_i]), (LAS unsigned*)(lds + (bufoff) + ldsw + _i * 8192), 16, 0, 0); } while (0)
; #define PG8_LDA(dst, b, h) do { _Pragma("unroll") for (int m = 0; m < 4; ++m) _Pragma("unroll") for (int k = 0; k < 2; ++k) dst[m][k] = *(const LAS bf16x8*)(lds + PG8_SA(b, h) + aoff + m * 2048 + k * 1024); } while (0)
; #define PG8_LDB(dst, b, h) do { _Pragma("unroll") for (int n = 0; n < 2; ++n) _Pragma("unroll") for (int k = 0; k < 2; ++k) dst[n][k] = *(const LAS bf16x8*)(lds + PG8_SB(b, h) + boff + n * 2048 + k * 1024); } while (0)
; #define PG8_MMA(ai, bj, At, Bt) do { __builtin_amdgcn_s_setprio(1); _Pragma("unroll") for (int m = 0; m < 4; ++m) _Pragma("unroll") for (int n = 0; n < 2; ++n) _Pragma("unroll") for (int k = 0; k < 2; ++k) \
;         acc[ai][bj][m][n] = __builtin_amdgcn_mfma_f32_16x16x32_bf16(Bt[n][k], At[m][k], acc[ai][bj][m][n], 0, 0, 0); __builtin_amdgcn_s_setprio(0); } while (0)
; #define PG8_WAIT_V(n) asm volatile("s_waitcnt vmcnt(" #n ")" ::: "memory")
; #define PG8_WAIT_L(n) asm volatile("s_waitcnt lgkmcnt(" #n ")" ::: "memory")
; #define PG8_BAR __builtin_amdgcn_s_barrier()
; #define PG8_SCHED __builtin_amdgcn_sched_barrier(0)
; template <class Epi, class Ptrs>
; __device__ __forceinline__ void gemm_phase(LAS unsigned char* lds, const int K, const StaticOrder& S, const Ptrs& P, const Epi& E) {
;     ...
;             PG8_LDB(B0, 0, 0); PG8_SCHED; PG8_LDA(At, 0, 0); PG8_STAGE(PG8_SA(1, 1), a1 + hstep, voffA);
;             PG8_WAIT_L(8); PG8_BAR; PG8_WAIT_L(0); PG8_MMA(0, 0, At, B0); PG8_BAR; PG8_SCHED;
;             PG8_LDB(B1, 0, 1); PG8_STAGE(PG8_SB(0, 0), b2, voffB);
;             PG8_BAR; PG8_WAIT_L(0); PG8_MMA(0, 1, At, B1); PG8_BAR;
;             PG8_LDA(At, 0, 1); PG8_STAGE(PG8_SA(0, 0), a2, voffA);
;             PG8_BAR; PG8_WAIT_L(0); PG8_MMA(1, 0, At, B0); PG8_BAR; PG8_SCHED;
;             PG8_STAGE(PG8_SB(0, 1), b2 + hstep, voffB);
;             PG8_WAIT_V(6); PG8_BAR; PG8_MMA(1, 1, At, B1); PG8_BAR;
.LBB0_433:
	ds_read_b128 v[152:155], v149
	ds_read_b128 v[156:159], v149 offset:1024
	ds_read_b128 v[160:163], v149 offset:2048
	ds_read_b128 v[164:167], v149 offset:3072
	s_add_u32 s42, s40, 0xfffc0080
	s_addc_u32 s43, s41, -1
	s_cmp_eq_u32 s70, 12
	s_cselect_b32 s45, s1, s43
	s_cselect_b32 s44, s0, s42
	s_cselect_b32 s43, s37, s25
	s_cselect_b32 s42, s36, s23
	s_add_i32 m0, s39, 0xc000
	ds_read_b128 v[168:171], v150
	ds_read_b128 v[172:175], v150 offset:1024
	ds_read_b128 v[176:179], v150 offset:2048
	ds_read_b128 v[180:183], v150 offset:3072
	ds_read_b128 v[184:187], v150 offset:4096
	ds_read_b128 v[188:191], v150 offset:5120
	ds_read_b128 v[192:195], v150 offset:6144
	ds_read_b128 v[196:199], v150 offset:7168
	global_load_lds_dwordx4 v136, s[40:41]
	s_add_i32 m0, s39, 0xe000
	s_nop 0
	global_load_lds_dwordx4 v138, s[40:41]
	s_waitcnt lgkmcnt(8)
	s_barrier
	s_waitcnt lgkmcnt(0)
	v_mfma_f32_16x16x32_bf16 v[124:127], v[152:155], v[168:171], v[124:127]
	v_mfma_f32_16x16x32_bf16 v[124:127], v[156:159], v[172:175], v[124:127]
	v_mfma_f32_16x16x32_bf16 v[120:123], v[164:167], v[172:175], v[120:123]
	v_mfma_f32_16x16x32_bf16 v[120:123], v[160:163], v[168:171], v[120:123]
	v_mfma_f32_16x16x32_bf16 v[104:107], v[160:163], v[176:179], v[104:107]
	v_mfma_f32_16x16x32_bf16 v[104:107], v[164:167], v[180:183], v[104:107]
	v_mfma_f32_16x16x32_bf16 v[108:111], v[156:159], v[180:183], v[108:111]
	v_mfma_f32_16x16x32_bf16 v[108:111], v[152:155], v[176:179], v[108:111]
	v_mfma_f32_16x16x32_bf16 v[92:95], v[152:155], v[184:187], v[92:95]
	v_mfma_f32_16x16x32_bf16 v[92:95], v[156:159], v[188:191], v[92:95]
	v_mfma_f32_16x16x32_bf16 v[88:91], v[164:167], v[188:191], v[88:91]
	v_mfma_f32_16x16x32_bf16 v[88:91], v[160:163], v[184:187], v[88:91]
	v_mfma_f32_16x16x32_bf16 v[72:75], v[160:163], v[192:195], v[72:75]
	v_mfma_f32_16x16x32_bf16 v[72:75], v[164:167], v[196:199], v[72:75]
	v_mfma_f32_16x16x32_bf16 v[76:79], v[156:159], v[196:199], v[76:79]
	v_mfma_f32_16x16x32_bf16 v[76:79], v[152:155], v[192:195], v[76:79]
	s_barrier
	s_add_i32 s71, s63, s51
	s_add_u32 s76, s42, 0x80
	s_addc_u32 s77, s43, 0
	s_mov_b32 m0, s71
	ds_read_b128 v[200:203], v151
	ds_read_b128 v[204:207], v151 offset:1024
	ds_read_b128 v[210:213], v151 offset:2048
	ds_read_b128 v[214:217], v151 offset:3072
	global_load_lds_dwordx4 v130, s[42:43]
	s_add_i32 m0, s71, 0x2000
	s_nop 0
	global_load_lds_dwordx4 v134, s[42:43]
	s_barrier
	s_waitcnt lgkmcnt(0)
	v_mfma_f32_16x16x32_bf16 v[116:119], v[200:203], v[168:171], v[116:119]
	v_mfma_f32_16x16x32_bf16 v[116:119], v[204:207], v[172:175], v[116:119]
	v_mfma_f32_16x16x32_bf16 v[112:115], v[214:217], v[172:175], v[112:115]
	v_mfma_f32_16x16x32_bf16 v[112:115], v[210:213], v[168:171], v[112:115]
	v_mfma_f32_16x16x32_bf16 v[96:99], v[210:213], v[176:179], v[96:99]
	v_mfma_f32_16x16x32_bf16 v[96:99], v[214:217], v[180:183], v[96:99]
	v_mfma_f32_16x16x32_bf16 v[100:103], v[204:207], v[180:183], v[100:103]
	v_mfma_f32_16x16x32_bf16 v[100:103], v[200:203], v[176:179], v[100:103]
	v_mfma_f32_16x16x32_bf16 v[84:87], v[200:203], v[184:187], v[84:87]
	v_mfma_f32_16x16x32_bf16 v[84:87], v[204:207], v[188:191], v[84:87]
	v_mfma_f32_16x16x32_bf16 v[80:83], v[214:217], v[188:191], v[80:83]
	v_mfma_f32_16x16x32_bf16 v[80:83], v[210:213], v[184:187], v[80:83]
	v_mfma_f32_16x16x32_bf16 v[64:67], v[210:213], v[192:195], v[64:67]
	v_mfma_f32_16x16x32_bf16 v[64:67], v[214:217], v[196:199], v[64:67]
	v_mfma_f32_16x16x32_bf16 v[68:71], v[204:207], v[196:199], v[68:71]
	v_mfma_f32_16x16x32_bf16 v[68:71], v[200:203], v[192:195], v[68:71]
	s_barrier
	s_mov_b32 m0, s39
	s_add_u32 s78, s44, 0x80
	s_addc_u32 s79, s45, 0
	ds_read_b128 v[168:171], v150 offset:16384
	ds_read_b128 v[172:175], v150 offset:17408
	ds_read_b128 v[176:179], v150 offset:18432
	ds_read_b128 v[180:183], v150 offset:19456
	ds_read_b128 v[184:187], v150 offset:20480
	ds_read_b128 v[188:191], v150 offset:21504
	ds_read_b128 v[192:195], v150 offset:22528
	ds_read_b128 v[196:199], v150 offset:23552
	global_load_lds_dwordx4 v128, s[44:45]
	s_mov_b32 m0, s56
	s_nop 0
	global_load_lds_dwordx4 v132, s[44:45]
	s_barrier
	s_waitcnt lgkmcnt(0)
	v_mfma_f32_16x16x32_bf16 v[60:63], v[152:155], v[168:171], v[60:63]
	v_mfma_f32_16x16x32_bf16 v[60:63], v[156:159], v[172:175], v[60:63]
	v_mfma_f32_16x16x32_bf16 v[56:59], v[164:167], v[172:175], v[56:59]
	v_mfma_f32_16x16x32_bf16 v[56:59], v[160:163], v[168:171], v[56:59]
	v_mfma_f32_16x16x32_bf16 v[40:43], v[160:163], v[176:179], v[40:43]
	v_mfma_f32_16x16x32_bf16 v[40:43], v[164:167], v[180:183], v[40:43]
	v_mfma_f32_16x16x32_bf16 v[44:47], v[156:159], v[180:183], v[44:47]
	v_mfma_f32_16x16x32_bf16 v[44:47], v[152:155], v[176:179], v[44:47]
	v_mfma_f32_16x16x32_bf16 v[28:31], v[152:155], v[184:187], v[28:31]
	v_mfma_f32_16x16x32_bf16 v[28:31], v[156:159], v[188:191], v[28:31]
	v_mfma_f32_16x16x32_bf16 v[24:27], v[164:167], v[188:191], v[24:27]
	v_mfma_f32_16x16x32_bf16 v[24:27], v[160:163], v[184:187], v[24:27]
	v_mfma_f32_16x16x32_bf16 v[8:11], v[160:163], v[192:195], v[8:11]
	v_mfma_f32_16x16x32_bf16 v[8:11], v[164:167], v[196:199], v[8:11]
	v_mfma_f32_16x16x32_bf16 v[12:15], v[156:159], v[196:199], v[12:15]
	v_mfma_f32_16x16x32_bf16 v[12:15], v[152:155], v[192:195], v[12:15]
	s_barrier
	s_add_u32 s72, s42, 0x40000
	s_addc_u32 s73, s43, 0
	s_add_i32 s71, s64, s51
	s_mov_b32 m0, s71
	s_nop 0
	global_load_lds_dwordx4 v130, s[72:73]
	s_add_i32 m0, s71, 0x2000
	s_nop 0
	global_load_lds_dwordx4 v134, s[72:73]
	s_waitcnt vmcnt(6)
	s_barrier
; #define PG8_STAGE(bufoff, gbase, voff) do { _Pragma("unroll") for (int _i = 0; _i < 2; ++_i) \
;         __builtin_amdgcn_global_load_lds((const unsigned*)((const char*)(gbase) + (voff)[_i]), (LAS unsigned*)(lds + (bufoff) + ldsw + _i * 8192), 16, 0, 0); } while (0)
; #define PG8_LDA(dst, b, h) do { _Pragma("unroll") for (int m = 0; m < 4; ++m) _Pragma("unroll") for (int k = 0; k < 2; ++k) dst[m][k] = *(const LAS bf16x8*)(lds + PG8_SA(b, h) + aoff + m * 2048 + k * 1024); } while (0)
; #define PG8_LDB(dst, b, h) do { _Pragma("unroll") for (int n = 0; n < 2; ++n) _Pragma("unroll") for (int k = 0; k < 2; ++k) dst[n][k] = *(const LAS bf16x8*)(lds + PG8_SB(b, h) + boff + n * 2048 + k * 1024); } while (0)
; #define PG8_MMA(ai, bj, At, Bt) do { __builtin_amdgcn_s_setprio(1); _Pragma("unroll") for (int m = 0; m < 4; ++m) _Pragma("unroll") for (int n = 0; n < 2; ++n) _Pragma("unroll") for (int k = 0; k < 2; ++k) \
;         acc[ai][bj][m][n] = __builtin_amdgcn_mfma_f32_16x16x32_bf16(Bt[n][k], At[m][k], acc[ai][bj][m][n], 0, 0, 0); __builtin_amdgcn_s_setprio(0); } while (0)
; #define PG8_WAIT_V(n) asm volatile("s_waitcnt vmcnt(" #n ")" ::: "memory")
; #define PG8_WAIT_L(n) asm volatile("s_waitcnt lgkmcnt(" #n ")" ::: "memory")
; #define PG8_BAR __builtin_amdgcn_s_barrier()
; #define PG8_SCHED __builtin_amdgcn_sched_barrier(0)
; template <class Epi, class Ptrs>
; __device__ __forceinline__ void gemm_phase(LAS unsigned char* lds, const int K, const StaticOrder& S, const Ptrs& P, const Epi& E) {
;     ...
;             PG8_WAIT_V(6); PG8_BAR; PG8_MMA(1, 1, At, B1); PG8_BAR;
;             PG8_LDB(B0, 1, 0); PG8_SCHED; PG8_LDA(At, 1, 0); PG8_STAGE(PG8_SA(0, 1), a2 + hstep, voffA);
;             PG8_WAIT_L(8); PG8_BAR; PG8_WAIT_L(0); PG8_MMA(0, 0, At, B0); PG8_BAR; PG8_SCHED;
;             PG8_LDB(B1, 1, 1); PG8_STAGE(PG8_SB(1, 0), b3, voffB);
;             PG8_BAR; PG8_WAIT_L(0); PG8_MMA(0, 1, At, B1); PG8_BAR;
;             PG8_LDA(At, 1, 1); PG8_STAGE(PG8_SA(1, 0), a3, voffA);
;             PG8_BAR; PG8_WAIT_L(0); PG8_MMA(1, 0, At, B0); PG8_BAR; PG8_SCHED;
	v_mfma_f32_16x16x32_bf16 v[52:55], v[200:203], v[168:171], v[52:55]
	v_mfma_f32_16x16x32_bf16 v[52:55], v[204:207], v[172:175], v[52:55]
	v_mfma_f32_16x16x32_bf16 v[48:51], v[214:217], v[172:175], v[48:51]
	v_mfma_f32_16x16x32_bf16 v[48:51], v[210:213], v[168:171], v[48:51]
	v_mfma_f32_16x16x32_bf16 v[32:35], v[210:213], v[176:179], v[32:35]
	v_mfma_f32_16x16x32_bf16 v[32:35], v[214:217], v[180:183], v[32:35]
	v_mfma_f32_16x16x32_bf16 v[36:39], v[204:207], v[180:183], v[36:39]
	v_mfma_f32_16x16x32_bf16 v[36:39], v[200:203], v[176:179], v[36:39]
	v_mfma_f32_16x16x32_bf16 v[20:23], v[200:203], v[184:187], v[20:23]
	v_mfma_f32_16x16x32_bf16 v[20:23], v[204:207], v[188:191], v[20:23]
	v_mfma_f32_16x16x32_bf16 v[16:19], v[214:217], v[188:191], v[16:19]
	v_mfma_f32_16x16x32_bf16 v[16:19], v[210:213], v[184:187], v[16:19]
	v_mfma_f32_16x16x32_bf16 v[0:3], v[210:213], v[192:195], v[0:3]
	v_mfma_f32_16x16x32_bf16 v[0:3], v[214:217], v[196:199], v[0:3]
	v_mfma_f32_16x16x32_bf16 v[4:7], v[204:207], v[196:199], v[4:7]
	v_mfma_f32_16x16x32_bf16 v[4:7], v[200:203], v[192:195], v[4:7]
	s_barrier
	s_add_i32 s71, 0, 0x18000
	ds_read_b128 v[152:155], v252
	ds_read_b128 v[156:159], v252 offset:1024
	ds_read_b128 v[160:163], v252 offset:2048
	ds_read_b128 v[164:167], v252 offset:3072
	s_add_u32 s44, s44, 0x40000
	s_addc_u32 s45, s45, 0
	s_mov_b32 m0, s57
	ds_read_b128 v[168:171], v150 offset:32768
	ds_read_b128 v[172:175], v150 offset:33792
	ds_read_b128 v[176:179], v150 offset:34816
	ds_read_b128 v[180:183], v150 offset:35840
	ds_read_b128 v[184:187], v150 offset:36864
	ds_read_b128 v[188:191], v150 offset:37888
	ds_read_b128 v[192:195], v150 offset:38912
	ds_read_b128 v[196:199], v150 offset:39936
	global_load_lds_dwordx4 v128, s[44:45]
	s_mov_b32 m0, s58
	s_nop 0
	global_load_lds_dwordx4 v132, s[44:45]
	s_waitcnt lgkmcnt(8)
	s_barrier
	s_waitcnt lgkmcnt(0)
	v_mfma_f32_16x16x32_bf16 v[124:127], v[152:155], v[168:171], v[124:127]
	v_mfma_f32_16x16x32_bf16 v[124:127], v[156:159], v[172:175], v[124:127]
	v_mfma_f32_16x16x32_bf16 v[120:123], v[164:167], v[172:175], v[120:123]
	v_mfma_f32_16x16x32_bf16 v[120:123], v[160:163], v[168:171], v[120:123]
	v_mfma_f32_16x16x32_bf16 v[104:107], v[160:163], v[176:179], v[104:107]
	v_mfma_f32_16x16x32_bf16 v[104:107], v[164:167], v[180:183], v[104:107]
	v_mfma_f32_16x16x32_bf16 v[108:111], v[156:159], v[180:183], v[108:111]
	v_mfma_f32_16x16x32_bf16 v[108:111], v[152:155], v[176:179], v[108:111]
	v_mfma_f32_16x16x32_bf16 v[92:95], v[152:155], v[184:187], v[92:95]
	v_mfma_f32_16x16x32_bf16 v[92:95], v[156:159], v[188:191], v[92:95]
	v_mfma_f32_16x16x32_bf16 v[88:91], v[164:167], v[188:191], v[88:91]
	v_mfma_f32_16x16x32_bf16 v[88:91], v[160:163], v[184:187], v[88:91]
	v_mfma_f32_16x16x32_bf16 v[72:75], v[160:163], v[192:195], v[72:75]
	v_mfma_f32_16x16x32_bf16 v[72:75], v[164:167], v[196:199], v[72:75]
	v_mfma_f32_16x16x32_bf16 v[76:79], v[156:159], v[196:199], v[76:79]
	v_mfma_f32_16x16x32_bf16 v[76:79], v[152:155], v[192:195], v[76:79]
	s_barrier
	s_add_i32 s44, 0, 0x1c000
	s_add_i32 s45, s71, s51
	s_mov_b32 m0, s45
	ds_read_b128 v[200:203], v253
	ds_read_b128 v[204:207], v253 offset:1024
	ds_read_b128 v[210:213], v253 offset:2048
	ds_read_b128 v[214:217], v253 offset:3072
	global_load_lds_dwordx4 v130, s[76:77]
	s_add_i32 m0, s45, 0x2000
	s_nop 0
	global_load_lds_dwordx4 v134, s[76:77]
	s_barrier
	s_waitcnt lgkmcnt(0)
	v_mfma_f32_16x16x32_bf16 v[116:119], v[200:203], v[168:171], v[116:119]
	v_mfma_f32_16x16x32_bf16 v[116:119], v[204:207], v[172:175], v[116:119]
	v_mfma_f32_16x16x32_bf16 v[112:115], v[214:217], v[172:175], v[112:115]
	v_mfma_f32_16x16x32_bf16 v[112:115], v[210:213], v[168:171], v[112:115]
	v_mfma_f32_16x16x32_bf16 v[96:99], v[210:213], v[176:179], v[96:99]
	v_mfma_f32_16x16x32_bf16 v[96:99], v[214:217], v[180:183], v[96:99]
	v_mfma_f32_16x16x32_bf16 v[100:103], v[204:207], v[180:183], v[100:103]
	v_mfma_f32_16x16x32_bf16 v[100:103], v[200:203], v[176:179], v[100:103]
	v_mfma_f32_16x16x32_bf16 v[84:87], v[200:203], v[184:187], v[84:87]
	v_mfma_f32_16x16x32_bf16 v[84:87], v[204:207], v[188:191], v[84:87]
	v_mfma_f32_16x16x32_bf16 v[80:83], v[214:217], v[188:191], v[80:83]
	v_mfma_f32_16x16x32_bf16 v[80:83], v[210:213], v[184:187], v[80:83]
	v_mfma_f32_16x16x32_bf16 v[64:67], v[210:213], v[192:195], v[64:67]
	v_mfma_f32_16x16x32_bf16 v[64:67], v[214:217], v[196:199], v[64:67]
	v_mfma_f32_16x16x32_bf16 v[68:71], v[204:207], v[196:199], v[68:71]
	v_mfma_f32_16x16x32_bf16 v[68:71], v[200:203], v[192:195], v[68:71]
	s_barrier
	s_mov_b32 m0, s61
	ds_read_b128 v[168:171], v150 offset:49152
	ds_read_b128 v[172:175], v150 offset:50176
	ds_read_b128 v[176:179], v150 offset:51200
	ds_read_b128 v[180:183], v150 offset:52224
	ds_read_b128 v[184:187], v150 offset:53248
	ds_read_b128 v[188:191], v150 offset:54272
	ds_read_b128 v[192:195], v150 offset:55296
	ds_read_b128 v[196:199], v150 offset:56320
	global_load_lds_dwordx4 v128, s[78:79]
	s_mov_b32 m0, s62
	s_nop 0
	global_load_lds_dwordx4 v132, s[78:79]
	s_barrier
	s_waitcnt lgkmcnt(0)
	v_mfma_f32_16x16x32_bf16 v[60:63], v[152:155], v[168:171], v[60:63]
	v_mfma_f32_16x16x32_bf16 v[60:63], v[156:159], v[172:175], v[60:63]
	v_mfma_f32_16x16x32_bf16 v[56:59], v[164:167], v[172:175], v[56:59]
	v_mfma_f32_16x16x32_bf16 v[56:59], v[160:163], v[168:171], v[56:59]
	v_mfma_f32_16x16x32_bf16 v[40:43], v[160:163], v[176:179], v[40:43]
	v_mfma_f32_16x16x32_bf16 v[40:43], v[164:167], v[180:183], v[40:43]
	v_mfma_f32_16x16x32_bf16 v[44:47], v[156:159], v[180:183], v[44:47]
	v_mfma_f32_16x16x32_bf16 v[44:47], v[152:155], v[176:179], v[44:47]
	v_mfma_f32_16x16x32_bf16 v[28:31], v[152:155], v[184:187], v[28:31]
	v_mfma_f32_16x16x32_bf16 v[28:31], v[156:159], v[188:191], v[28:31]
	v_mfma_f32_16x16x32_bf16 v[24:27], v[164:167], v[188:191], v[24:27]
	v_mfma_f32_16x16x32_bf16 v[24:27], v[160:163], v[184:187], v[24:27]
	v_mfma_f32_16x16x32_bf16 v[8:11], v[160:163], v[192:195], v[8:11]
	v_mfma_f32_16x16x32_bf16 v[8:11], v[164:167], v[196:199], v[8:11]
	v_mfma_f32_16x16x32_bf16 v[12:15], v[156:159], v[196:199], v[12:15]
	v_mfma_f32_16x16x32_bf16 v[12:15], v[152:155], v[192:195], v[12:15]
	s_barrier
; __device__ __forceinline__ unsigned cvt_pk_bf16(float lo, float hi) { unsigned r; asm volatile("v_cvt_pk_bf16_f32 %0, %1, %2" : "=v"(r) : "v"(lo), "v"(hi)); return r; }
; #define PG8_STAGE(bufoff, gbase, voff) do { _Pragma("unroll") for (int _i = 0; _i < 2; ++_i) \
;         __builtin_amdgcn_global_load_lds((const unsigned*)((const char*)(gbase) + (voff)[_i]), (LAS unsigned*)(lds + (bufoff) + ldsw + _i * 8192), 16, 0, 0); } while (0)
; #define PG8_MMA(ai, bj, At, Bt) do { __builtin_amdgcn_s_setprio(1); _Pragma("unroll") for (int m = 0; m < 4; ++m) _Pragma("unroll") for (int n = 0; n < 2; ++n) _Pragma("unroll") for (int k = 0; k < 2; ++k) \
;         acc[ai][bj][m][n] = __builtin_amdgcn_mfma_f32_16x16x32_bf16(Bt[n][k], At[m][k], acc[ai][bj][m][n], 0, 0, 0); __builtin_amdgcn_s_setprio(0); } while (0)
; #define PG8_WAIT_V(n) asm volatile("s_waitcnt vmcnt(" #n ")" ::: "memory")
; #define PG8_BAR __builtin_amdgcn_s_barrier()
; template <class Epi, class Ptrs>
; __device__ __forceinline__ void gemm_phase(LAS unsigned char* lds, const int K, const StaticOrder& S, const Ptrs& P, const Epi& E) {
;     ...
;             PG8_STAGE(PG8_SB(1, 1), b3 + hstep, voffB);
;             PG8_WAIT_V(6); PG8_BAR; PG8_MMA(1, 1, At, B1); PG8_BAR;
;     __device__ __forceinline__ void operator()(const f32x4 (&acc)[2][2][4][2], const Unit& u, int ui, int wr, int wc, int fr, int fq) const {
;         const int row0 = u.pm * 256 + wr * 64 + fr, col0 = u.pn * 256 + wc * 32 + 8 * fq;
; #pragma unroll
;         for (int ai = 0; ai < 2; ++ai)
; #pragma unroll
;             for (int m = 0; m < 4; ++m) { bf16_t* rowp = hid + (size_t)(row0 + ai * 128 + m * 16) * DFF + col0;
; #pragma unroll
;                 for (int bj = 0; bj < 2; ++bj) { f32x4 v0 = acc[ai][bj][m][0], v1 = acc[ai][bj][m][1];
; #pragma unroll
;                     for (int j = 0; j < 4; ++j) { const float a = fmaxf(v0[j], 0.f), b = fmaxf(v1[j], 0.f); v0[j] = a * a; v1[j] = b * b; }
;                     u32x4 w; w.x = cvt_pk_bf16(v0[0], v0[1]); w.y = cvt_pk_bf16(v0[2], v0[3]); w.z = cvt_pk_bf16(v1[0], v1[1]); w.w = cvt_pk_bf16(v1[2], v1[3]);
;                     *(u32x4*)(rowp + bj * 128) = w; } }
	s_add_u32 s42, s42, 0x40080
	s_addc_u32 s43, s43, 0
	s_add_i32 s44, s44, s51
	s_mov_b32 m0, s44
	s_nop 0
	global_load_lds_dwordx4 v130, s[42:43]
	s_add_i32 m0, s44, 0x2000
	s_nop 0
	global_load_lds_dwordx4 v134, s[42:43]
	s_waitcnt vmcnt(6)
	s_barrier
	v_mfma_f32_16x16x32_bf16 v[52:55], v[200:203], v[168:171], v[52:55]
	v_mfma_f32_16x16x32_bf16 v[52:55], v[204:207], v[172:175], v[52:55]
	v_mfma_f32_16x16x32_bf16 v[48:51], v[214:217], v[172:175], v[48:51]
	v_mfma_f32_16x16x32_bf16 v[48:51], v[210:213], v[168:171], v[48:51]
	v_mfma_f32_16x16x32_bf16 v[32:35], v[210:213], v[176:179], v[32:35]
	v_mfma_f32_16x16x32_bf16 v[32:35], v[214:217], v[180:183], v[32:35]
	v_mfma_f32_16x16x32_bf16 v[36:39], v[204:207], v[180:183], v[36:39]
	v_mfma_f32_16x16x32_bf16 v[36:39], v[200:203], v[176:179], v[36:39]
	v_mfma_f32_16x16x32_bf16 v[20:23], v[200:203], v[184:187], v[20:23]
	v_mfma_f32_16x16x32_bf16 v[20:23], v[204:207], v[188:191], v[20:23]
	v_mfma_f32_16x16x32_bf16 v[16:19], v[214:217], v[188:191], v[16:19]
	v_mfma_f32_16x16x32_bf16 v[16:19], v[210:213], v[184:187], v[16:19]
	v_mfma_f32_16x16x32_bf16 v[0:3], v[210:213], v[192:195], v[0:3]
	v_mfma_f32_16x16x32_bf16 v[0:3], v[214:217], v[196:199], v[0:3]
	v_mfma_f32_16x16x32_bf16 v[4:7], v[204:207], v[196:199], v[4:7]
	v_mfma_f32_16x16x32_bf16 v[4:7], v[200:203], v[192:195], v[4:7]
	s_barrier
	s_add_i32 s70, s70, 2
	s_add_u32 s40, s40, 0x100
	s_addc_u32 s41, s41, 0
	s_add_u32 s23, s23, 0x100
	s_addc_u32 s25, s25, 0
	s_cmp_gt_u32 s70, 13
	s_cbranch_scc0 .LBB0_433
	s_nop 0
	s_nop 0
	s_nop 0
	s_nop 0
	s_nop 0
	s_nop 0
	s_nop 0
	s_nop 0
	s_nop 0
	s_nop 0
	s_nop 0
	s_nop 0
	s_nop 0
	s_nop 0
	s_nop 0
	s_nop 0
	s_nop 0
	s_nop 0
	s_nop 0
	s_nop 0
	s_nop 0
	s_nop 0
	s_nop 0
	s_nop 0
	s_nop 0
	s_nop 0
	s_nop 0
	s_nop 0
	s_nop 0
	s_nop 0
	s_nop 0
	s_nop 0
	s_nop 0
	s_nop 0
	s_nop 0
	s_nop 0
	s_nop 0
	s_nop 0
	s_nop 0
	s_nop 0
	s_nop 0
	s_nop 0
	s_nop 0
	s_nop 0
	s_nop 0
	s_nop 0
	s_nop 0
	s_nop 0
	s_nop 0
	s_nop 0
	v_lshl_add_u32 v152, s38, 8, v146
	v_max_f32_e32 v120, 0, v120
	v_ashrrev_i32_e32 v153, 31, v152
	v_max_f32_e32 v121, 0, v121
	v_max_f32_e32 v122, 0, v122
	v_lshl_or_b32 v144, s69, 8, v148
	v_lshlrev_b64 v[154:155], 13, v[152:153]
	v_mul_f32_e32 v153, v120, v120
	v_max_f32_e32 v120, 0, v125
	v_ashrrev_i32_e32 v145, 31, v144
	v_max_f32_e32 v124, 0, v124
	v_mul_f32_e32 v125, v121, v121
	v_max_f32_e32 v121, 0, v126
	v_mul_f32_e32 v126, v122, v122
	v_max_f32_e32 v122, 0, v127
	v_max_f32_e32 v123, 0, v123
	v_lshl_add_u64 v[154:155], s[10:11], 0, v[154:155]
	v_lshlrev_b64 v[156:157], 1, v[144:145]
	v_mul_f32_e32 v120, v120, v120
	v_max_f32_e32 v112, 0, v112
	v_lshl_add_u64 v[144:145], v[154:155], 0, v[156:157]
	v_mul_f32_e32 v124, v124, v124
	v_mul_f32_e32 v121, v121, v121
	v_mul_f32_e32 v122, v122, v122
	v_mul_f32_e32 v123, v123, v123
	v_cvt_pk_bf16_f32 v120, v124, v120
	v_max_f32_e32 v113, 0, v113
	v_max_f32_e32 v114, 0, v114
	v_cvt_pk_bf16_f32 v121, v121, v122
	v_cvt_pk_bf16_f32 v122, v153, v125
	v_cvt_pk_bf16_f32 v123, v126, v123
	global_store_dwordx4 v[144:145], v[120:123], off
	s_nop 1
	v_mul_f32_e32 v120, v112, v112
	v_max_f32_e32 v112, 0, v117
	v_max_f32_e32 v116, 0, v116
	v_mul_f32_e32 v117, v113, v113
	v_max_f32_e32 v113, 0, v118
	v_mul_f32_e32 v118, v114, v114
	v_max_f32_e32 v114, 0, v119
	v_max_f32_e32 v115, 0, v115
	v_mul_f32_e32 v112, v112, v112
	v_mul_f32_e32 v116, v116, v116
	v_mul_f32_e32 v113, v113, v113
	v_mul_f32_e32 v114, v114, v114
	v_mul_f32_e32 v115, v115, v115
	v_cvt_pk_bf16_f32 v112, v116, v112
	v_max_f32_e32 v104, 0, v104
	v_cvt_pk_bf16_f32 v113, v113, v114
	v_cvt_pk_bf16_f32 v114, v120, v117
	v_cvt_pk_bf16_f32 v115, v118, v115
	global_store_dwordx4 v[144:145], v[112:115], off offset:256
	s_nop 0
	v_max_f32_e32 v105, 0, v105
	v_or_b32_e32 v112, 16, v152
	v_max_f32_e32 v106, 0, v106
	v_ashrrev_i32_e32 v113, 31, v112
	v_mul_f32_e32 v114, v104, v104
	v_max_f32_e32 v104, 0, v109
	v_lshlrev_b64 v[112:113], 13, v[112:113]
	v_max_f32_e32 v108, 0, v108
	v_mul_f32_e32 v109, v105, v105
	v_max_f32_e32 v105, 0, v110
	v_mul_f32_e32 v110, v106, v106
	v_max_f32_e32 v106, 0, v111
	v_max_f32_e32 v107, 0, v107
	v_lshl_add_u64 v[112:113], s[10:11], 0, v[112:113]
	v_mul_f32_e32 v104, v104, v104
	v_max_f32_e32 v96, 0, v96
	v_lshl_add_u64 v[112:113], v[112:113], 0, v[156:157]
	v_mul_f32_e32 v108, v108, v108
	v_mul_f32_e32 v105, v105, v105
	v_mul_f32_e32 v106, v106, v106
	v_mul_f32_e32 v107, v107, v107
	v_cvt_pk_bf16_f32 v104, v108, v104
	v_max_f32_e32 v97, 0, v97
	v_max_f32_e32 v98, 0, v98
	v_cvt_pk_bf16_f32 v105, v105, v106
	v_cvt_pk_bf16_f32 v106, v114, v109
	v_cvt_pk_bf16_f32 v107, v110, v107
	global_store_dwordx4 v[112:113], v[104:107], off
	s_nop 1
	v_mul_f32_e32 v104, v96, v96
	v_max_f32_e32 v96, 0, v101
	v_max_f32_e32 v100, 0, v100
	v_mul_f32_e32 v101, v97, v97
	v_max_f32_e32 v97, 0, v102
	v_mul_f32_e32 v102, v98, v98
	v_max_f32_e32 v98, 0, v103
	v_max_f32_e32 v99, 0, v99
	v_mul_f32_e32 v96, v96, v96
	v_mul_f32_e32 v100, v100, v100
	v_mul_f32_e32 v97, v97, v97
	v_mul_f32_e32 v98, v98, v98
	v_mul_f32_e32 v99, v99, v99
	v_cvt_pk_bf16_f32 v96, v100, v96
	v_max_f32_e32 v88, 0, v88
	v_cvt_pk_bf16_f32 v97, v97, v98
	v_cvt_pk_bf16_f32 v98, v104, v101
	v_cvt_pk_bf16_f32 v99, v102, v99
	global_store_dwordx4 v[112:113], v[96:99], off offset:256
	s_nop 0
	v_max_f32_e32 v89, 0, v89
	v_or_b32_e32 v96, 32, v152
	v_max_f32_e32 v90, 0, v90
	v_ashrrev_i32_e32 v97, 31, v96
	v_mul_f32_e32 v98, v88, v88
	v_max_f32_e32 v88, 0, v93
	v_lshlrev_b64 v[96:97], 13, v[96:97]
	v_max_f32_e32 v92, 0, v92
	v_mul_f32_e32 v93, v89, v89
	v_max_f32_e32 v89, 0, v94
	v_mul_f32_e32 v94, v90, v90
	v_max_f32_e32 v90, 0, v95
; __device__ __forceinline__ unsigned cvt_pk_bf16(float lo, float hi) { unsigned r; asm volatile("v_cvt_pk_bf16_f32 %0, %1, %2" : "=v"(r) : "v"(lo), "v"(hi)); return r; }
;     __device__ __forceinline__ void operator()(const f32x4 (&acc)[2][2][4][2], const Unit& u, int ui, int wr, int wc, int fr, int fq) const {
;         const int row0 = u.pm * 256 + wr * 64 + fr, col0 = u.pn * 256 + wc * 32 + 8 * fq;
; #pragma unroll
;         for (int ai = 0; ai < 2; ++ai)
; #pragma unroll
;             for (int m = 0; m < 4; ++m) { bf16_t* rowp = hid + (size_t)(row0 + ai * 128 + m * 16) * DFF + col0;
; #pragma unroll
;                 for (int bj = 0; bj < 2; ++bj) { f32x4 v0 = acc[ai][bj][m][0], v1 = acc[ai][bj][m][1];
; #pragma unroll
;                     for (int j = 0; j < 4; ++j) { const float a = fmaxf(v0[j], 0.f), b = fmaxf(v1[j], 0.f); v0[j] = a * a; v1[j] = b * b; }
;                     u32x4 w; w.x = cvt_pk_bf16(v0[0], v0[1]); w.y = cvt_pk_bf16(v0[2], v0[3]); w.z = cvt_pk_bf16(v1[0], v1[1]); w.w = cvt_pk_bf16(v1[2], v1[3]);
;                     *(u32x4*)(rowp + bj * 128) = w; } }
	v_max_f32_e32 v91, 0, v91
	v_lshl_add_u64 v[96:97], s[10:11], 0, v[96:97]
	v_mul_f32_e32 v88, v88, v88
	v_max_f32_e32 v80, 0, v80
	v_lshl_add_u64 v[96:97], v[96:97], 0, v[156:157]
	v_mul_f32_e32 v92, v92, v92
	v_mul_f32_e32 v89, v89, v89
	v_mul_f32_e32 v90, v90, v90
	v_mul_f32_e32 v91, v91, v91
	v_cvt_pk_bf16_f32 v88, v92, v88
	v_max_f32_e32 v81, 0, v81
	v_max_f32_e32 v82, 0, v82
	v_cvt_pk_bf16_f32 v89, v89, v90
	v_cvt_pk_bf16_f32 v90, v98, v93
	v_cvt_pk_bf16_f32 v91, v94, v91
	global_store_dwordx4 v[96:97], v[88:91], off
	s_nop 1
	v_mul_f32_e32 v88, v80, v80
	v_max_f32_e32 v80, 0, v85
	v_max_f32_e32 v84, 0, v84
	v_mul_f32_e32 v85, v81, v81
	v_max_f32_e32 v81, 0, v86
	v_mul_f32_e32 v86, v82, v82
	v_max_f32_e32 v82, 0, v87
	v_max_f32_e32 v83, 0, v83
	v_mul_f32_e32 v80, v80, v80
	v_mul_f32_e32 v84, v84, v84
	v_mul_f32_e32 v81, v81, v81
	v_mul_f32_e32 v82, v82, v82
	v_mul_f32_e32 v83, v83, v83
	v_cvt_pk_bf16_f32 v80, v84, v80
	v_max_f32_e32 v72, 0, v72
	v_cvt_pk_bf16_f32 v81, v81, v82
	v_cvt_pk_bf16_f32 v82, v88, v85
	v_cvt_pk_bf16_f32 v83, v86, v83
	global_store_dwordx4 v[96:97], v[80:83], off offset:256
	s_nop 0
	v_max_f32_e32 v73, 0, v73
	v_or_b32_e32 v80, 48, v152
	v_max_f32_e32 v74, 0, v74
	v_ashrrev_i32_e32 v81, 31, v80
	v_mul_f32_e32 v82, v72, v72
	v_max_f32_e32 v72, 0, v77
	v_lshlrev_b64 v[80:81], 13, v[80:81]
	v_max_f32_e32 v76, 0, v76
	v_mul_f32_e32 v77, v73, v73
	v_max_f32_e32 v73, 0, v78
	v_mul_f32_e32 v78, v74, v74
	v_max_f32_e32 v74, 0, v79
	v_max_f32_e32 v75, 0, v75
	v_lshl_add_u64 v[80:81], s[10:11], 0, v[80:81]
	v_mul_f32_e32 v72, v72, v72
	v_max_f32_e32 v64, 0, v64
	v_max_f32_e32 v65, 0, v65
	v_max_f32_e32 v66, 0, v66
	v_lshl_add_u64 v[80:81], v[80:81], 0, v[156:157]
	v_mul_f32_e32 v76, v76, v76
	v_mul_f32_e32 v73, v73, v73
	v_mul_f32_e32 v74, v74, v74
	v_mul_f32_e32 v75, v75, v75
	v_cvt_pk_bf16_f32 v72, v76, v72
	v_cvt_pk_bf16_f32 v73, v73, v74
	v_cvt_pk_bf16_f32 v74, v82, v77
	v_cvt_pk_bf16_f32 v75, v78, v75
	global_store_dwordx4 v[80:81], v[72:75], off
	v_max_f32_e32 v68, 0, v68
	v_max_f32_e32 v67, 0, v67
	v_mul_f32_e32 v72, v64, v64
	v_max_f32_e32 v64, 0, v69
	v_mul_f32_e32 v69, v65, v65
	v_max_f32_e32 v65, 0, v70
	v_mul_f32_e32 v70, v66, v66
	v_max_f32_e32 v66, 0, v71
	v_mul_f32_e32 v64, v64, v64
	v_mul_f32_e32 v65, v65, v65
	v_mul_f32_e32 v66, v66, v66
	v_max_f32_e32 v56, 0, v56
	v_mul_f32_e32 v68, v68, v68
	v_mul_f32_e32 v67, v67, v67
	v_cvt_pk_bf16_f32 v64, v68, v64
	v_cvt_pk_bf16_f32 v65, v65, v66
	v_cvt_pk_bf16_f32 v66, v72, v69
	v_max_f32_e32 v57, 0, v57
	v_max_f32_e32 v58, 0, v58
	v_cvt_pk_bf16_f32 v67, v70, v67
	global_store_dwordx4 v[80:81], v[64:67], off offset:256
	s_nop 0
	v_max_f32_e32 v60, 0, v60
	v_mul_f32_e32 v66, v56, v56
	v_max_f32_e32 v56, 0, v61
	v_mul_f32_e32 v61, v57, v57
	v_max_f32_e32 v57, 0, v62
	v_mul_f32_e32 v62, v58, v58
	v_max_f32_e32 v58, 0, v63
	v_mul_f32_e32 v60, v60, v60
	v_mul_f32_e32 v56, v56, v56
	v_max_f32_e32 v59, 0, v59
	v_mul_f32_e32 v57, v57, v57
	v_mul_f32_e32 v58, v58, v58
	v_cvt_pk_bf16_f32 v56, v60, v56
	v_add_co_u32_e32 v60, vcc, s65, v144
	v_max_f32_e32 v48, 0, v48
	v_max_f32_e32 v49, 0, v49
	v_max_f32_e32 v50, 0, v50
	v_mul_f32_e32 v59, v59, v59
	v_cvt_pk_bf16_f32 v57, v57, v58
	v_cvt_pk_bf16_f32 v58, v66, v61
	v_addc_co_u32_e32 v61, vcc, 0, v145, vcc
	v_cvt_pk_bf16_f32 v59, v62, v59
	global_store_dwordx4 v[60:61], v[56:59], off
	v_max_f32_e32 v52, 0, v52
	v_max_f32_e32 v51, 0, v51
	v_mul_f32_e32 v56, v48, v48
	v_max_f32_e32 v48, 0, v53
	v_mul_f32_e32 v53, v49, v49
	v_max_f32_e32 v49, 0, v54
	v_mul_f32_e32 v54, v50, v50
	v_max_f32_e32 v50, 0, v55
	v_mul_f32_e32 v48, v48, v48
	v_mul_f32_e32 v49, v49, v49
	v_mul_f32_e32 v50, v50, v50
	v_max_f32_e32 v40, 0, v40
	v_lshl_add_u64 v[64:65], v[144:145], 0, s[14:15]
	v_mul_f32_e32 v52, v52, v52
	v_mul_f32_e32 v51, v51, v51
	v_cvt_pk_bf16_f32 v48, v52, v48
	v_cvt_pk_bf16_f32 v49, v49, v50
	v_cvt_pk_bf16_f32 v50, v56, v53
	v_max_f32_e32 v41, 0, v41
	v_max_f32_e32 v42, 0, v42
	v_cvt_pk_bf16_f32 v51, v54, v51
	global_store_dwordx4 v[64:65], v[48:51], off offset:256
	s_nop 0
	v_max_f32_e32 v44, 0, v44
	v_mul_f32_e32 v50, v40, v40
	v_max_f32_e32 v40, 0, v45
	v_mul_f32_e32 v45, v41, v41
; __device__ __forceinline__ unsigned cvt_pk_bf16(float lo, float hi) { unsigned r; asm volatile("v_cvt_pk_bf16_f32 %0, %1, %2" : "=v"(r) : "v"(lo), "v"(hi)); return r; }
; #define PG8_WAIT_V(n) asm volatile("s_waitcnt vmcnt(" #n ")" ::: "memory")
; #define PG8_BAR __builtin_amdgcn_s_barrier()
; template <class Epi, class Ptrs>
; __device__ __forceinline__ void gemm_phase(LAS unsigned char* lds, const int K, const StaticOrder& S, const Ptrs& P, const Epi& E) {
;     ...
;         E(acc, cur, ui, wr, wc, fr, fq);
;         if (!has_next) break;
; #pragma unroll
;         for (int a = 0; a < 2; ++a)
; #pragma unroll
;             for (int b = 0; b < 2; ++b)
; #pragma unroll
;                 for (int m = 0; m < 4; ++m)
; #pragma unroll
;                     for (int n = 0; n < 2; ++n) acc[a][b][m][n] = (f32x4){0.f, 0.f, 0.f, 0.f};
;         cur = nxt; cA = nA; cB = nB; ++ui;
;     }
;     PG8_WAIT_V(0);
;     if (wr == 0) PG8_BAR;
;     PG8_BAR;
;     __device__ __forceinline__ void operator()(const f32x4 (&acc)[2][2][4][2], const Unit& u, int ui, int wr, int wc, int fr, int fq) const {
;         const int row0 = u.pm * 256 + wr * 64 + fr, col0 = u.pn * 256 + wc * 32 + 8 * fq;
; #pragma unroll
;         for (int ai = 0; ai < 2; ++ai)
; #pragma unroll
;             for (int m = 0; m < 4; ++m) { bf16_t* rowp = hid + (size_t)(row0 + ai * 128 + m * 16) * DFF + col0;
; #pragma unroll
;                 for (int bj = 0; bj < 2; ++bj) { f32x4 v0 = acc[ai][bj][m][0], v1 = acc[ai][bj][m][1];
; #pragma unroll
;                     for (int j = 0; j < 4; ++j) { const float a = fmaxf(v0[j], 0.f), b = fmaxf(v1[j], 0.f); v0[j] = a * a; v1[j] = b * b; }
;                     u32x4 w; w.x = cvt_pk_bf16(v0[0], v0[1]); w.y = cvt_pk_bf16(v0[2], v0[3]); w.z = cvt_pk_bf16(v1[0], v1[1]); w.w = cvt_pk_bf16(v1[2], v1[3]);
;                     *(u32x4*)(rowp + bj * 128) = w; } }
	v_max_f32_e32 v41, 0, v46
	v_mul_f32_e32 v46, v42, v42
	v_max_f32_e32 v42, 0, v47
	v_mul_f32_e32 v44, v44, v44
	v_mul_f32_e32 v40, v40, v40
	v_max_f32_e32 v43, 0, v43
	v_mul_f32_e32 v41, v41, v41
	v_mul_f32_e32 v42, v42, v42
	v_cvt_pk_bf16_f32 v40, v44, v40
	v_add_co_u32_e32 v44, vcc, s66, v144
	v_max_f32_e32 v32, 0, v32
	v_max_f32_e32 v33, 0, v33
	v_max_f32_e32 v34, 0, v34
	v_mul_f32_e32 v43, v43, v43
	v_cvt_pk_bf16_f32 v41, v41, v42
	v_cvt_pk_bf16_f32 v42, v50, v45
	v_addc_co_u32_e32 v45, vcc, 0, v145, vcc
	v_cvt_pk_bf16_f32 v43, v46, v43
	global_store_dwordx4 v[44:45], v[40:43], off
	v_max_f32_e32 v36, 0, v36
	v_max_f32_e32 v35, 0, v35
	v_mul_f32_e32 v40, v32, v32
	v_max_f32_e32 v32, 0, v37
	v_mul_f32_e32 v37, v33, v33
	v_max_f32_e32 v33, 0, v38
	v_mul_f32_e32 v38, v34, v34
	v_max_f32_e32 v34, 0, v39
	v_mul_f32_e32 v32, v32, v32
	v_mul_f32_e32 v33, v33, v33
	v_mul_f32_e32 v34, v34, v34
	v_max_f32_e32 v24, 0, v24
	v_lshl_add_u64 v[48:49], v[144:145], 0, s[16:17]
	v_mul_f32_e32 v36, v36, v36
	v_mul_f32_e32 v35, v35, v35
	v_cvt_pk_bf16_f32 v32, v36, v32
	v_cvt_pk_bf16_f32 v33, v33, v34
	v_cvt_pk_bf16_f32 v34, v40, v37
	v_max_f32_e32 v25, 0, v25
	v_max_f32_e32 v26, 0, v26
	v_cvt_pk_bf16_f32 v35, v38, v35
	global_store_dwordx4 v[48:49], v[32:35], off offset:256
	s_nop 0
	v_max_f32_e32 v28, 0, v28
	v_mul_f32_e32 v34, v24, v24
	v_max_f32_e32 v24, 0, v29
	v_mul_f32_e32 v29, v25, v25
	v_max_f32_e32 v25, 0, v30
	v_mul_f32_e32 v30, v26, v26
	v_max_f32_e32 v26, 0, v31
	v_mul_f32_e32 v28, v28, v28
	v_mul_f32_e32 v24, v24, v24
	v_max_f32_e32 v27, 0, v27
	v_mul_f32_e32 v25, v25, v25
	v_mul_f32_e32 v26, v26, v26
	v_cvt_pk_bf16_f32 v24, v28, v24
	v_add_co_u32_e32 v28, vcc, s67, v144
	v_max_f32_e32 v16, 0, v16
	v_max_f32_e32 v17, 0, v17
	v_max_f32_e32 v18, 0, v18
	v_mul_f32_e32 v27, v27, v27
	v_cvt_pk_bf16_f32 v25, v25, v26
	v_cvt_pk_bf16_f32 v26, v34, v29
	v_addc_co_u32_e32 v29, vcc, 0, v145, vcc
	v_cvt_pk_bf16_f32 v27, v30, v27
	global_store_dwordx4 v[28:29], v[24:27], off
	v_max_f32_e32 v20, 0, v20
	v_max_f32_e32 v19, 0, v19
	v_mul_f32_e32 v24, v16, v16
	v_max_f32_e32 v16, 0, v21
	v_mul_f32_e32 v21, v17, v17
	v_max_f32_e32 v17, 0, v22
	v_mul_f32_e32 v22, v18, v18
	v_max_f32_e32 v18, 0, v23
	v_mul_f32_e32 v16, v16, v16
	v_mul_f32_e32 v17, v17, v17
	v_mul_f32_e32 v18, v18, v18
	v_max_f32_e32 v8, 0, v8
	v_lshl_add_u64 v[32:33], v[144:145], 0, s[18:19]
	v_mul_f32_e32 v20, v20, v20
	v_mul_f32_e32 v19, v19, v19
	v_cvt_pk_bf16_f32 v16, v20, v16
	v_cvt_pk_bf16_f32 v17, v17, v18
	v_cvt_pk_bf16_f32 v18, v24, v21
	v_max_f32_e32 v9, 0, v9
	v_max_f32_e32 v10, 0, v10
	v_cvt_pk_bf16_f32 v19, v22, v19
	global_store_dwordx4 v[32:33], v[16:19], off offset:256
	s_nop 0
	v_max_f32_e32 v12, 0, v12
	v_mul_f32_e32 v18, v8, v8
	v_max_f32_e32 v8, 0, v13
	v_mul_f32_e32 v13, v9, v9
	v_max_f32_e32 v9, 0, v14
	v_mul_f32_e32 v14, v10, v10
	v_max_f32_e32 v10, 0, v15
	v_mul_f32_e32 v12, v12, v12
	v_mul_f32_e32 v8, v8, v8
	v_max_f32_e32 v11, 0, v11
	v_mul_f32_e32 v9, v9, v9
	v_mul_f32_e32 v10, v10, v10
	v_cvt_pk_bf16_f32 v8, v12, v8
	v_add_co_u32_e32 v12, vcc, s68, v144
	v_max_f32_e32 v0, 0, v0
	v_max_f32_e32 v1, 0, v1
	v_max_f32_e32 v2, 0, v2
	v_mul_f32_e32 v11, v11, v11
	v_cvt_pk_bf16_f32 v9, v9, v10
	v_cvt_pk_bf16_f32 v10, v18, v13
	v_addc_co_u32_e32 v13, vcc, 0, v145, vcc
	v_cvt_pk_bf16_f32 v11, v14, v11
	global_store_dwordx4 v[12:13], v[8:11], off
	v_max_f32_e32 v3, 0, v3
	v_max_f32_e32 v4, 0, v4
	v_mul_f32_e32 v8, v0, v0
	v_max_f32_e32 v0, 0, v5
	v_mul_f32_e32 v5, v1, v1
	v_max_f32_e32 v1, 0, v6
	v_mul_f32_e32 v6, v2, v2
	v_max_f32_e32 v2, 0, v7
	v_lshl_add_u64 v[16:17], v[144:145], 0, s[20:21]
	v_mul_f32_e32 v0, v0, v0
	v_mul_f32_e32 v1, v1, v1
	v_mul_f32_e32 v2, v2, v2
	v_mul_f32_e32 v3, v3, v3
	s_and_b64 vcc, exec, s[4:5]
	s_mov_b32 s69, s22
	s_mov_b32 s38, s24
	s_mov_b64 s[40:41], s[0:1]
	s_mov_b64 s[42:43], s[36:37]
	v_mul_f32_e32 v4, v4, v4
	v_cvt_pk_bf16_f32 v0, v4, v0
	v_cvt_pk_bf16_f32 v1, v1, v2
	v_cvt_pk_bf16_f32 v2, v8, v5
	v_cvt_pk_bf16_f32 v3, v6, v3
	global_store_dwordx4 v[16:17], v[0:3], off offset:256
	s_cbranch_vccz .LBB0_428
	s_waitcnt vmcnt(0)
	s_setprio 0
	s_cmpk_gt_u32 s46, 0xff
	s_cbranch_scc1 .LBB0_437
	s_barrier

; #define PG8_STAGE(bufoff, gbase, voff) do { _Pragma("unroll") for (int _i = 0; _i < 2; ++_i) \
;         __builtin_amdgcn_global_load_lds((const unsigned*)((const char*)(gbase) + (voff)[_i]), (LAS unsigned*)(lds + (bufoff) + ldsw + _i * 8192), 16, 0, 0); } while (0)
; #define PG8_LDA(dst, b, h) do { _Pragma("unroll") for (int m = 0; m < 4; ++m) _Pragma("unroll") for (int k = 0; k < 2; ++k) dst[m][k] = *(const LAS bf16x8*)(lds + PG8_SA(b, h) + aoff + m * 2048 + k * 1024); } while (0)
; #define PG8_LDB(dst, b, h) do { _Pragma("unroll") for (int n = 0; n < 2; ++n) _Pragma("unroll") for (int k = 0; k < 2; ++k) dst[n][k] = *(const LAS bf16x8*)(lds + PG8_SB(b, h) + boff + n * 2048 + k * 1024); } while (0)
; #define PG8_MMA(ai, bj, At, Bt) do { __builtin_amdgcn_s_setprio(1); _Pragma("unroll") for (int m = 0; m < 4; ++m) _Pragma("unroll") for (int n = 0; n < 2; ++n) _Pragma("unroll") for (int k = 0; k < 2; ++k) \
;         acc[ai][bj][m][n] = __builtin_amdgcn_mfma_f32_16x16x32_bf16(Bt[n][k], At[m][k], acc[ai][bj][m][n], 0, 0, 0); __builtin_amdgcn_s_setprio(0); } while (0)
; #define PG8_WAIT_L(n) asm volatile("s_waitcnt lgkmcnt(" #n ")" ::: "memory")
; #define PG8_BAR __builtin_amdgcn_s_barrier()
; #define PG8_SCHED __builtin_amdgcn_sched_barrier(0)
; template <class Epi, class Ptrs>
; __device__ __forceinline__ void gemm_phase(LAS unsigned char* lds, const int K, const StaticOrder& S, const Ptrs& P, const Epi& E) {
;     ...
;         for (int t = 0; t < nt; t += 2) {
;             const bool last = (t == nt - 2);
;             const char* a1 = cA + (size_t)(t + 1) * kstep;
;             const char* a2 = last ? nA : cA + (size_t)(t + 2) * kstep; const char* b2 = last ? nB : cB + (size_t)(t + 2) * kstep;
;             const char* a3 = a2 + kstep; const char* b3 = b2 + kstep;
;             PG8_LDB(B0, 0, 0); PG8_SCHED; PG8_LDA(At, 0, 0); PG8_STAGE(PG8_SA(1, 1), a1 + hstep, voffA);
;             PG8_WAIT_L(8); PG8_BAR; PG8_WAIT_L(0); PG8_MMA(0, 0, At, B0); PG8_BAR; PG8_SCHED;
;     ...
; #pragma unroll
;         for (int a = 0; a < 2; ++a)
; #pragma unroll
;             for (int b = 0; b < 2; ++b)
; #pragma unroll
;                 for (int m = 0; m < 4; ++m)
; #pragma unroll
;                     for (int n = 0; n < 2; ++n) acc[a][b][m][n] = (f32x4){0.f, 0.f, 0.f, 0.f};
;         cur = nxt; cA = nA; cB = nB; ++ui;
.LBB0_521:
	s_add_u32 s20, s20, 0x100080
	s_nop 0
	s_nop 0
	s_nop 0
	s_nop 0
	s_nop 0
	s_nop 0
	s_nop 0
	s_nop 0
	s_nop 0
	s_nop 0
	s_nop 0
	s_nop 0
	s_nop 0
	s_nop 0
	s_nop 0
	s_nop 0
	s_nop 0
	s_nop 0
	s_nop 0
	s_nop 0
	s_nop 0
	s_nop 0
	s_nop 0
	s_nop 0
	s_nop 0
	s_nop 0
	s_nop 0
	s_nop 0
	s_nop 0
	s_nop 0
	s_nop 0
	s_nop 0
	s_nop 0
	s_nop 0
	s_nop 0
	s_nop 0
	s_nop 0
	s_nop 0
	s_nop 0
	s_nop 0
	s_nop 0
	s_nop 0
	s_nop 0
	s_nop 0
	s_nop 0
	s_nop 0
	s_nop 0
	s_nop 0
	s_nop 0
	s_nop 0
	s_nop 0
	s_nop 0
	s_nop 0
	s_nop 0
	s_nop 0
	s_nop 0
	s_nop 0
	s_addc_u32 s21, s21, 0
	s_add_u32 s11, s22, 0x100
	v_mov_b32_e32 v0, 0
	s_addc_u32 s13, s23, 0
	s_mov_b32 s46, -2
	v_mov_b32_e32 v1, v0
	v_mov_b32_e32 v2, v0
	v_mov_b32_e32 v3, v0
	v_mov_b32_e32 v4, v0
	v_mov_b32_e32 v5, v0
	v_mov_b32_e32 v6, v0
	v_mov_b32_e32 v7, v0
	v_mov_b32_e32 v12, v0
	v_mov_b32_e32 v13, v0
	v_mov_b32_e32 v14, v0
	v_mov_b32_e32 v15, v0
	v_mov_b32_e32 v20, v0
	v_mov_b32_e32 v21, v0
	v_mov_b32_e32 v22, v0
	v_mov_b32_e32 v23, v0
	v_mov_b32_e32 v28, v0
	v_mov_b32_e32 v29, v0
	v_mov_b32_e32 v30, v0
	v_mov_b32_e32 v31, v0
	v_mov_b32_e32 v36, v0
	v_mov_b32_e32 v37, v0
	v_mov_b32_e32 v38, v0
	v_mov_b32_e32 v39, v0
	v_mov_b32_e32 v44, v0
	v_mov_b32_e32 v45, v0
	v_mov_b32_e32 v46, v0
	v_mov_b32_e32 v47, v0
	v_mov_b32_e32 v52, v0
	v_mov_b32_e32 v53, v0
	v_mov_b32_e32 v54, v0
	v_mov_b32_e32 v55, v0
	v_mov_b32_e32 v8, v0
	v_mov_b32_e32 v9, v0
	v_mov_b32_e32 v10, v0
	v_mov_b32_e32 v11, v0
	v_mov_b32_e32 v16, v0
	v_mov_b32_e32 v17, v0
	v_mov_b32_e32 v18, v0
	v_mov_b32_e32 v19, v0
	v_mov_b32_e32 v24, v0
	v_mov_b32_e32 v25, v0
	v_mov_b32_e32 v26, v0
	v_mov_b32_e32 v27, v0
	v_mov_b32_e32 v32, v0
	v_mov_b32_e32 v33, v0
	v_mov_b32_e32 v34, v0
	v_mov_b32_e32 v35, v0
	v_mov_b32_e32 v40, v0
	v_mov_b32_e32 v41, v0
	v_mov_b32_e32 v42, v0
	v_mov_b32_e32 v43, v0
	v_mov_b32_e32 v48, v0
	v_mov_b32_e32 v49, v0
	v_mov_b32_e32 v50, v0
	v_mov_b32_e32 v51, v0
	v_mov_b32_e32 v56, v0
	v_mov_b32_e32 v57, v0
	v_mov_b32_e32 v58, v0
	v_mov_b32_e32 v59, v0
	v_mov_b32_e32 v60, v0
	v_mov_b32_e32 v61, v0
	v_mov_b32_e32 v62, v0
	v_mov_b32_e32 v63, v0
	v_mov_b32_e32 v64, v0
	v_mov_b32_e32 v65, v0
	v_mov_b32_e32 v66, v0
	v_mov_b32_e32 v67, v0
	v_mov_b32_e32 v68, v0
	v_mov_b32_e32 v69, v0
	v_mov_b32_e32 v70, v0
	v_mov_b32_e32 v71, v0
	v_mov_b32_e32 v80, v0
	v_mov_b32_e32 v81, v0
	v_mov_b32_e32 v82, v0
	v_mov_b32_e32 v83, v0
	v_mov_b32_e32 v84, v0
	v_mov_b32_e32 v85, v0
	v_mov_b32_e32 v86, v0
	v_mov_b32_e32 v87, v0
	v_mov_b32_e32 v96, v0
	v_mov_b32_e32 v97, v0
	v_mov_b32_e32 v98, v0
	v_mov_b32_e32 v99, v0
	v_mov_b32_e32 v100, v0
	v_mov_b32_e32 v101, v0
	v_mov_b32_e32 v102, v0
	v_mov_b32_e32 v103, v0
	v_mov_b32_e32 v108, v0
	v_mov_b32_e32 v109, v0
	v_mov_b32_e32 v110, v0
	v_mov_b32_e32 v111, v0
	v_mov_b32_e32 v116, v0
	v_mov_b32_e32 v117, v0
	v_mov_b32_e32 v118, v0
	v_mov_b32_e32 v119, v0
	v_mov_b32_e32 v72, v0
	v_mov_b32_e32 v73, v0
	v_mov_b32_e32 v74, v0
	v_mov_b32_e32 v75, v0
	v_mov_b32_e32 v76, v0
	v_mov_b32_e32 v77, v0
	v_mov_b32_e32 v78, v0
	v_mov_b32_e32 v79, v0
	v_mov_b32_e32 v88, v0
	v_mov_b32_e32 v89, v0
	v_mov_b32_e32 v90, v0
	v_mov_b32_e32 v91, v0
	v_mov_b32_e32 v92, v0
	v_mov_b32_e32 v93, v0
	v_mov_b32_e32 v94, v0
	v_mov_b32_e32 v95, v0
	v_mov_b32_e32 v104, v0
	v_mov_b32_e32 v105, v0
	v_mov_b32_e32 v106, v0
	v_mov_b32_e32 v107, v0
	v_mov_b32_e32 v112, v0
	v_mov_b32_e32 v113, v0
	v_mov_b32_e32 v114, v0
	v_mov_b32_e32 v115, v0
	v_mov_b32_e32 v120, v0
	v_mov_b32_e32 v121, v0
	v_mov_b32_e32 v122, v0
	v_mov_b32_e32 v123, v0
	v_mov_b32_e32 v124, v0
	v_mov_b32_e32 v125, v0
	v_mov_b32_e32 v126, v0
	v_add_u32_e32 v252, 0x18000, v187
	v_add_u32_e32 v253, 0x1c000, v187
	v_mov_b32_e32 v127, v0
.LBB0_522:
	ds_read_b128 v[128:131], v193
	ds_read_b128 v[132:135], v193 offset:1024
	ds_read_b128 v[136:139], v193 offset:2048
	ds_read_b128 v[140:143], v193 offset:3072
	s_add_u32 s22, s20, 0xfff00080
	s_addc_u32 s23, s21, -1
	s_cmp_eq_u32 s46, 60
	s_cselect_b32 s25, s5, s23
	s_cselect_b32 s24, s4, s22
	s_cselect_b32 s23, s15, s13
	s_cselect_b32 s22, s14, s11
	s_add_i32 m0, s17, 0xc000
	ds_read_b128 v[144:147], v194
	ds_read_b128 v[148:151], v194 offset:1024
	ds_read_b128 v[152:155], v194 offset:2048
	ds_read_b128 v[156:159], v194 offset:3072
	ds_read_b128 v[176:179], v194 offset:4096
	ds_read_b128 v[180:183], v194 offset:5120
	ds_read_b128 v[196:199], v194 offset:6144
	ds_read_b128 v[200:203], v194 offset:7168
	global_load_lds_dwordx4 v168, s[20:21]
	s_add_i32 m0, s17, 0xe000
	s_nop 0
	global_load_lds_dwordx4 v170, s[20:21]
	s_waitcnt lgkmcnt(8)
	s_barrier
	s_waitcnt lgkmcnt(0)
	v_mfma_f32_16x16x32_bf16 v[124:127], v[128:131], v[144:147], v[124:127]
	v_mfma_f32_16x16x32_bf16 v[124:127], v[132:135], v[148:151], v[124:127]
	v_mfma_f32_16x16x32_bf16 v[120:123], v[140:143], v[148:151], v[120:123]
	v_mfma_f32_16x16x32_bf16 v[120:123], v[136:139], v[144:147], v[120:123]
	v_mfma_f32_16x16x32_bf16 v[104:107], v[136:139], v[152:155], v[104:107]
	v_mfma_f32_16x16x32_bf16 v[104:107], v[140:143], v[156:159], v[104:107]
	v_mfma_f32_16x16x32_bf16 v[112:115], v[132:135], v[156:159], v[112:115]
	v_mfma_f32_16x16x32_bf16 v[112:115], v[128:131], v[152:155], v[112:115]
	v_mfma_f32_16x16x32_bf16 v[92:95], v[128:131], v[176:179], v[92:95]
	v_mfma_f32_16x16x32_bf16 v[92:95], v[132:135], v[180:183], v[92:95]
	v_mfma_f32_16x16x32_bf16 v[88:91], v[140:143], v[180:183], v[88:91]
	v_mfma_f32_16x16x32_bf16 v[88:91], v[136:139], v[176:179], v[88:91]
	v_mfma_f32_16x16x32_bf16 v[72:75], v[136:139], v[196:199], v[72:75]
	v_mfma_f32_16x16x32_bf16 v[72:75], v[140:143], v[200:203], v[72:75]
	v_mfma_f32_16x16x32_bf16 v[76:79], v[132:135], v[200:203], v[76:79]
	v_mfma_f32_16x16x32_bf16 v[76:79], v[128:131], v[196:199], v[76:79]
	s_barrier
; #define PG8_STAGE(bufoff, gbase, voff) do { _Pragma("unroll") for (int _i = 0; _i < 2; ++_i) \
;         __builtin_amdgcn_global_load_lds((const unsigned*)((const char*)(gbase) + (voff)[_i]), (LAS unsigned*)(lds + (bufoff) + ldsw + _i * 8192), 16, 0, 0); } while (0)
; #define PG8_LDA(dst, b, h) do { _Pragma("unroll") for (int m = 0; m < 4; ++m) _Pragma("unroll") for (int k = 0; k < 2; ++k) dst[m][k] = *(const LAS bf16x8*)(lds + PG8_SA(b, h) + aoff + m * 2048 + k * 1024); } while (0)
; #define PG8_LDB(dst, b, h) do { _Pragma("unroll") for (int n = 0; n < 2; ++n) _Pragma("unroll") for (int k = 0; k < 2; ++k) dst[n][k] = *(const LAS bf16x8*)(lds + PG8_SB(b, h) + boff + n * 2048 + k * 1024); } while (0)
; #define PG8_MMA(ai, bj, At, Bt) do { __builtin_amdgcn_s_setprio(1); _Pragma("unroll") for (int m = 0; m < 4; ++m) _Pragma("unroll") for (int n = 0; n < 2; ++n) _Pragma("unroll") for (int k = 0; k < 2; ++k) \
;         acc[ai][bj][m][n] = __builtin_amdgcn_mfma_f32_16x16x32_bf16(Bt[n][k], At[m][k], acc[ai][bj][m][n], 0, 0, 0); __builtin_amdgcn_s_setprio(0); } while (0)
; #define PG8_WAIT_V(n) asm volatile("s_waitcnt vmcnt(" #n ")" ::: "memory")
; #define PG8_WAIT_L(n) asm volatile("s_waitcnt lgkmcnt(" #n ")" ::: "memory")
; #define PG8_BAR __builtin_amdgcn_s_barrier()
; #define PG8_SCHED __builtin_amdgcn_sched_barrier(0)
; template <class Epi, class Ptrs>
; __device__ __forceinline__ void gemm_phase(LAS unsigned char* lds, const int K, const StaticOrder& S, const Ptrs& P, const Epi& E) {
;     ...
;             PG8_LDB(B1, 0, 1); PG8_STAGE(PG8_SB(0, 0), b2, voffB);
;             PG8_BAR; PG8_WAIT_L(0); PG8_MMA(0, 1, At, B1); PG8_BAR;
;             PG8_LDA(At, 0, 1); PG8_STAGE(PG8_SA(0, 0), a2, voffA);
;             PG8_BAR; PG8_WAIT_L(0); PG8_MMA(1, 0, At, B0); PG8_BAR; PG8_SCHED;
;             PG8_STAGE(PG8_SB(0, 1), b2 + hstep, voffB);
;             PG8_WAIT_V(6); PG8_BAR; PG8_MMA(1, 1, At, B1); PG8_BAR;
;             PG8_LDB(B0, 1, 0); PG8_SCHED; PG8_LDA(At, 1, 0); PG8_STAGE(PG8_SA(0, 1), a2 + hstep, voffA);
	s_add_i32 s47, s42, s34
	s_add_u32 s90, s22, 0x80
	s_addc_u32 s91, s23, 0
	s_mov_b32 m0, s47
	ds_read_b128 v[204:207], v195
	ds_read_b128 v[208:211], v195 offset:1024
	ds_read_b128 v[212:215], v195 offset:2048
	ds_read_b128 v[216:219], v195 offset:3072
	global_load_lds_dwordx4 v162, s[22:23]
	s_add_i32 m0, s47, 0x2000
	s_nop 0
	global_load_lds_dwordx4 v166, s[22:23]
	s_barrier
	s_waitcnt lgkmcnt(0)
	v_mfma_f32_16x16x32_bf16 v[116:119], v[204:207], v[144:147], v[116:119]
	v_mfma_f32_16x16x32_bf16 v[116:119], v[208:211], v[148:151], v[116:119]
	v_mfma_f32_16x16x32_bf16 v[108:111], v[216:219], v[148:151], v[108:111]
	v_mfma_f32_16x16x32_bf16 v[108:111], v[212:215], v[144:147], v[108:111]
	v_mfma_f32_16x16x32_bf16 v[96:99], v[212:215], v[152:155], v[96:99]
	v_mfma_f32_16x16x32_bf16 v[96:99], v[216:219], v[156:159], v[96:99]
	v_mfma_f32_16x16x32_bf16 v[100:103], v[208:211], v[156:159], v[100:103]
	v_mfma_f32_16x16x32_bf16 v[100:103], v[204:207], v[152:155], v[100:103]
	v_mfma_f32_16x16x32_bf16 v[84:87], v[204:207], v[176:179], v[84:87]
	v_mfma_f32_16x16x32_bf16 v[84:87], v[208:211], v[180:183], v[84:87]
	v_mfma_f32_16x16x32_bf16 v[80:83], v[216:219], v[180:183], v[80:83]
	v_mfma_f32_16x16x32_bf16 v[80:83], v[212:215], v[176:179], v[80:83]
	v_mfma_f32_16x16x32_bf16 v[64:67], v[212:215], v[196:199], v[64:67]
	v_mfma_f32_16x16x32_bf16 v[64:67], v[216:219], v[200:203], v[64:67]
	v_mfma_f32_16x16x32_bf16 v[68:71], v[208:211], v[200:203], v[68:71]
	v_mfma_f32_16x16x32_bf16 v[68:71], v[204:207], v[196:199], v[68:71]
	s_barrier
	s_mov_b32 m0, s17
	s_add_u32 s92, s24, 0x80
	s_addc_u32 s93, s25, 0
	ds_read_b128 v[144:147], v194 offset:16384
	ds_read_b128 v[148:151], v194 offset:17408
	ds_read_b128 v[152:155], v194 offset:18432
	ds_read_b128 v[156:159], v194 offset:19456
	ds_read_b128 v[176:179], v194 offset:20480
	ds_read_b128 v[180:183], v194 offset:21504
	ds_read_b128 v[196:199], v194 offset:22528
	ds_read_b128 v[200:203], v194 offset:23552
	global_load_lds_dwordx4 v160, s[24:25]
	s_mov_b32 m0, s19
	s_nop 0
	global_load_lds_dwordx4 v164, s[24:25]
	s_barrier
	s_waitcnt lgkmcnt(0)
	v_mfma_f32_16x16x32_bf16 v[60:63], v[128:131], v[144:147], v[60:63]
	v_mfma_f32_16x16x32_bf16 v[60:63], v[132:135], v[148:151], v[60:63]
	v_mfma_f32_16x16x32_bf16 v[56:59], v[140:143], v[148:151], v[56:59]
	v_mfma_f32_16x16x32_bf16 v[56:59], v[136:139], v[144:147], v[56:59]
	v_mfma_f32_16x16x32_bf16 v[40:43], v[136:139], v[152:155], v[40:43]
	v_mfma_f32_16x16x32_bf16 v[40:43], v[140:143], v[156:159], v[40:43]
	v_mfma_f32_16x16x32_bf16 v[48:51], v[132:135], v[156:159], v[48:51]
	v_mfma_f32_16x16x32_bf16 v[48:51], v[128:131], v[152:155], v[48:51]
	v_mfma_f32_16x16x32_bf16 v[32:35], v[128:131], v[176:179], v[32:35]
	v_mfma_f32_16x16x32_bf16 v[32:35], v[132:135], v[180:183], v[32:35]
	v_mfma_f32_16x16x32_bf16 v[24:27], v[140:143], v[180:183], v[24:27]
	v_mfma_f32_16x16x32_bf16 v[24:27], v[136:139], v[176:179], v[24:27]
	v_mfma_f32_16x16x32_bf16 v[8:11], v[136:139], v[196:199], v[8:11]
	v_mfma_f32_16x16x32_bf16 v[8:11], v[140:143], v[200:203], v[8:11]
	v_mfma_f32_16x16x32_bf16 v[16:19], v[132:135], v[200:203], v[16:19]
	v_mfma_f32_16x16x32_bf16 v[16:19], v[128:131], v[196:199], v[16:19]
	s_barrier
	s_add_u32 s48, s22, 0x100000
	s_addc_u32 s49, s23, 0
	s_add_i32 s47, s43, s34
	s_mov_b32 m0, s47
	s_nop 0
	global_load_lds_dwordx4 v162, s[48:49]
	s_add_i32 m0, s47, 0x2000
	s_nop 0
	global_load_lds_dwordx4 v166, s[48:49]
	s_waitcnt vmcnt(6)
	s_barrier
	v_mfma_f32_16x16x32_bf16 v[52:55], v[204:207], v[144:147], v[52:55]
	v_mfma_f32_16x16x32_bf16 v[52:55], v[208:211], v[148:151], v[52:55]
	v_mfma_f32_16x16x32_bf16 v[44:47], v[216:219], v[148:151], v[44:47]
	v_mfma_f32_16x16x32_bf16 v[44:47], v[212:215], v[144:147], v[44:47]
	v_mfma_f32_16x16x32_bf16 v[28:31], v[212:215], v[152:155], v[28:31]
	v_mfma_f32_16x16x32_bf16 v[28:31], v[216:219], v[156:159], v[28:31]
	v_mfma_f32_16x16x32_bf16 v[36:39], v[208:211], v[156:159], v[36:39]
	v_mfma_f32_16x16x32_bf16 v[36:39], v[204:207], v[152:155], v[36:39]
	v_mfma_f32_16x16x32_bf16 v[20:23], v[204:207], v[176:179], v[20:23]
	v_mfma_f32_16x16x32_bf16 v[20:23], v[208:211], v[180:183], v[20:23]
	v_mfma_f32_16x16x32_bf16 v[12:15], v[216:219], v[180:183], v[12:15]
	v_mfma_f32_16x16x32_bf16 v[12:15], v[212:215], v[176:179], v[12:15]
	v_mfma_f32_16x16x32_bf16 v[0:3], v[212:215], v[196:199], v[0:3]
	v_mfma_f32_16x16x32_bf16 v[0:3], v[216:219], v[200:203], v[0:3]
	v_mfma_f32_16x16x32_bf16 v[4:7], v[208:211], v[200:203], v[4:7]
	v_mfma_f32_16x16x32_bf16 v[4:7], v[204:207], v[196:199], v[4:7]
	s_barrier
	s_add_i32 s47, 0, 0x18000
	ds_read_b128 v[128:131], v252
	ds_read_b128 v[132:135], v252 offset:1024
	ds_read_b128 v[136:139], v252 offset:2048
	ds_read_b128 v[140:143], v252 offset:3072
	s_add_u32 s24, s24, 0x100000
	s_addc_u32 s25, s25, 0
	s_mov_b32 m0, s40
	ds_read_b128 v[144:147], v194 offset:32768
	ds_read_b128 v[148:151], v194 offset:33792
	ds_read_b128 v[152:155], v194 offset:34816
	ds_read_b128 v[156:159], v194 offset:35840
	ds_read_b128 v[176:179], v194 offset:36864
	ds_read_b128 v[180:183], v194 offset:37888
	ds_read_b128 v[196:199], v194 offset:38912
	ds_read_b128 v[200:203], v194 offset:39936
	global_load_lds_dwordx4 v160, s[24:25]
	s_mov_b32 m0, s41
	s_nop 0
	global_load_lds_dwordx4 v164, s[24:25]
	s_waitcnt lgkmcnt(8)
	s_barrier
; #define PG8_STAGE(bufoff, gbase, voff) do { _Pragma("unroll") for (int _i = 0; _i < 2; ++_i) \
;         __builtin_amdgcn_global_load_lds((const unsigned*)((const char*)(gbase) + (voff)[_i]), (LAS unsigned*)(lds + (bufoff) + ldsw + _i * 8192), 16, 0, 0); } while (0)
; #define PG8_LDA(dst, b, h) do { _Pragma("unroll") for (int m = 0; m < 4; ++m) _Pragma("unroll") for (int k = 0; k < 2; ++k) dst[m][k] = *(const LAS bf16x8*)(lds + PG8_SA(b, h) + aoff + m * 2048 + k * 1024); } while (0)
; #define PG8_LDB(dst, b, h) do { _Pragma("unroll") for (int n = 0; n < 2; ++n) _Pragma("unroll") for (int k = 0; k < 2; ++k) dst[n][k] = *(const LAS bf16x8*)(lds + PG8_SB(b, h) + boff + n * 2048 + k * 1024); } while (0)
; #define PG8_MMA(ai, bj, At, Bt) do { __builtin_amdgcn_s_setprio(1); _Pragma("unroll") for (int m = 0; m < 4; ++m) _Pragma("unroll") for (int n = 0; n < 2; ++n) _Pragma("unroll") for (int k = 0; k < 2; ++k) \
;         acc[ai][bj][m][n] = __builtin_amdgcn_mfma_f32_16x16x32_bf16(Bt[n][k], At[m][k], acc[ai][bj][m][n], 0, 0, 0); __builtin_amdgcn_s_setprio(0); } while (0)
; #define PG8_WAIT_V(n) asm volatile("s_waitcnt vmcnt(" #n ")" ::: "memory")
; #define PG8_WAIT_L(n) asm volatile("s_waitcnt lgkmcnt(" #n ")" ::: "memory")
; #define PG8_BAR __builtin_amdgcn_s_barrier()
; #define PG8_SCHED __builtin_amdgcn_sched_barrier(0)
; template <class Epi, class Ptrs>
; __device__ __forceinline__ void gemm_phase(LAS unsigned char* lds, const int K, const StaticOrder& S, const Ptrs& P, const Epi& E) {
;     ...
;             PG8_WAIT_L(8); PG8_BAR; PG8_WAIT_L(0); PG8_MMA(0, 0, At, B0); PG8_BAR; PG8_SCHED;
;             PG8_LDB(B1, 1, 1); PG8_STAGE(PG8_SB(1, 0), b3, voffB);
;             PG8_BAR; PG8_WAIT_L(0); PG8_MMA(0, 1, At, B1); PG8_BAR;
;             PG8_LDA(At, 1, 1); PG8_STAGE(PG8_SA(1, 0), a3, voffA);
;             PG8_BAR; PG8_WAIT_L(0); PG8_MMA(1, 0, At, B0); PG8_BAR; PG8_SCHED;
;             PG8_STAGE(PG8_SB(1, 1), b3 + hstep, voffB);
;             PG8_WAIT_V(6); PG8_BAR; PG8_MMA(1, 1, At, B1); PG8_BAR;
	s_waitcnt lgkmcnt(0)
	v_mfma_f32_16x16x32_bf16 v[124:127], v[128:131], v[144:147], v[124:127]
	v_mfma_f32_16x16x32_bf16 v[124:127], v[132:135], v[148:151], v[124:127]
	v_mfma_f32_16x16x32_bf16 v[120:123], v[140:143], v[148:151], v[120:123]
	v_mfma_f32_16x16x32_bf16 v[120:123], v[136:139], v[144:147], v[120:123]
	v_mfma_f32_16x16x32_bf16 v[104:107], v[136:139], v[152:155], v[104:107]
	v_mfma_f32_16x16x32_bf16 v[104:107], v[140:143], v[156:159], v[104:107]
	v_mfma_f32_16x16x32_bf16 v[112:115], v[132:135], v[156:159], v[112:115]
	v_mfma_f32_16x16x32_bf16 v[112:115], v[128:131], v[152:155], v[112:115]
	v_mfma_f32_16x16x32_bf16 v[92:95], v[128:131], v[176:179], v[92:95]
	v_mfma_f32_16x16x32_bf16 v[92:95], v[132:135], v[180:183], v[92:95]
	v_mfma_f32_16x16x32_bf16 v[88:91], v[140:143], v[180:183], v[88:91]
	v_mfma_f32_16x16x32_bf16 v[88:91], v[136:139], v[176:179], v[88:91]
	v_mfma_f32_16x16x32_bf16 v[72:75], v[136:139], v[196:199], v[72:75]
	v_mfma_f32_16x16x32_bf16 v[72:75], v[140:143], v[200:203], v[72:75]
	v_mfma_f32_16x16x32_bf16 v[76:79], v[132:135], v[200:203], v[76:79]
	v_mfma_f32_16x16x32_bf16 v[76:79], v[128:131], v[196:199], v[76:79]
	s_barrier
	s_add_i32 s24, 0, 0x1c000
	s_add_i32 s25, s47, s34
	s_mov_b32 m0, s25
	ds_read_b128 v[204:207], v253
	ds_read_b128 v[208:211], v253 offset:1024
	ds_read_b128 v[212:215], v253 offset:2048
	ds_read_b128 v[216:219], v253 offset:3072
	global_load_lds_dwordx4 v162, s[90:91]
	s_add_i32 m0, s25, 0x2000
	s_nop 0
	global_load_lds_dwordx4 v166, s[90:91]
	s_barrier
	s_waitcnt lgkmcnt(0)
	v_mfma_f32_16x16x32_bf16 v[116:119], v[204:207], v[144:147], v[116:119]
	v_mfma_f32_16x16x32_bf16 v[116:119], v[208:211], v[148:151], v[116:119]
	v_mfma_f32_16x16x32_bf16 v[108:111], v[216:219], v[148:151], v[108:111]
	v_mfma_f32_16x16x32_bf16 v[108:111], v[212:215], v[144:147], v[108:111]
	v_mfma_f32_16x16x32_bf16 v[96:99], v[212:215], v[152:155], v[96:99]
	v_mfma_f32_16x16x32_bf16 v[96:99], v[216:219], v[156:159], v[96:99]
	v_mfma_f32_16x16x32_bf16 v[100:103], v[208:211], v[156:159], v[100:103]
	v_mfma_f32_16x16x32_bf16 v[100:103], v[204:207], v[152:155], v[100:103]
	v_mfma_f32_16x16x32_bf16 v[84:87], v[204:207], v[176:179], v[84:87]
	v_mfma_f32_16x16x32_bf16 v[84:87], v[208:211], v[180:183], v[84:87]
	v_mfma_f32_16x16x32_bf16 v[80:83], v[216:219], v[180:183], v[80:83]
	v_mfma_f32_16x16x32_bf16 v[80:83], v[212:215], v[176:179], v[80:83]
	v_mfma_f32_16x16x32_bf16 v[64:67], v[212:215], v[196:199], v[64:67]
	v_mfma_f32_16x16x32_bf16 v[64:67], v[216:219], v[200:203], v[64:67]
	v_mfma_f32_16x16x32_bf16 v[68:71], v[208:211], v[200:203], v[68:71]
	v_mfma_f32_16x16x32_bf16 v[68:71], v[204:207], v[196:199], v[68:71]
	s_barrier
	s_mov_b32 m0, s28
	ds_read_b128 v[144:147], v194 offset:49152
	ds_read_b128 v[148:151], v194 offset:50176
	ds_read_b128 v[152:155], v194 offset:51200
	ds_read_b128 v[156:159], v194 offset:52224
	ds_read_b128 v[176:179], v194 offset:53248
	ds_read_b128 v[180:183], v194 offset:54272
	ds_read_b128 v[196:199], v194 offset:55296
	ds_read_b128 v[200:203], v194 offset:56320
	global_load_lds_dwordx4 v160, s[92:93]
	s_mov_b32 m0, s29
	s_nop 0
	global_load_lds_dwordx4 v164, s[92:93]
	s_barrier
	s_waitcnt lgkmcnt(0)
	v_mfma_f32_16x16x32_bf16 v[60:63], v[128:131], v[144:147], v[60:63]
	v_mfma_f32_16x16x32_bf16 v[60:63], v[132:135], v[148:151], v[60:63]
	v_mfma_f32_16x16x32_bf16 v[56:59], v[140:143], v[148:151], v[56:59]
	v_mfma_f32_16x16x32_bf16 v[56:59], v[136:139], v[144:147], v[56:59]
	v_mfma_f32_16x16x32_bf16 v[40:43], v[136:139], v[152:155], v[40:43]
	v_mfma_f32_16x16x32_bf16 v[40:43], v[140:143], v[156:159], v[40:43]
	v_mfma_f32_16x16x32_bf16 v[48:51], v[132:135], v[156:159], v[48:51]
	v_mfma_f32_16x16x32_bf16 v[48:51], v[128:131], v[152:155], v[48:51]
	v_mfma_f32_16x16x32_bf16 v[32:35], v[128:131], v[176:179], v[32:35]
	v_mfma_f32_16x16x32_bf16 v[32:35], v[132:135], v[180:183], v[32:35]
	v_mfma_f32_16x16x32_bf16 v[24:27], v[140:143], v[180:183], v[24:27]
	v_mfma_f32_16x16x32_bf16 v[24:27], v[136:139], v[176:179], v[24:27]
	v_mfma_f32_16x16x32_bf16 v[8:11], v[136:139], v[196:199], v[8:11]
	v_mfma_f32_16x16x32_bf16 v[8:11], v[140:143], v[200:203], v[8:11]
	v_mfma_f32_16x16x32_bf16 v[16:19], v[132:135], v[200:203], v[16:19]
	v_mfma_f32_16x16x32_bf16 v[16:19], v[128:131], v[196:199], v[16:19]
	s_barrier
	s_add_u32 s22, s22, 0x100080
	s_addc_u32 s23, s23, 0
	s_add_i32 s24, s24, s34
	s_mov_b32 m0, s24
	s_nop 0
	global_load_lds_dwordx4 v162, s[22:23]
	s_add_i32 m0, s24, 0x2000
	s_nop 0
	global_load_lds_dwordx4 v166, s[22:23]
	s_waitcnt vmcnt(6)
	s_barrier
	v_mfma_f32_16x16x32_bf16 v[52:55], v[204:207], v[144:147], v[52:55]
	v_mfma_f32_16x16x32_bf16 v[52:55], v[208:211], v[148:151], v[52:55]
	v_mfma_f32_16x16x32_bf16 v[44:47], v[216:219], v[148:151], v[44:47]
	v_mfma_f32_16x16x32_bf16 v[44:47], v[212:215], v[144:147], v[44:47]
	v_mfma_f32_16x16x32_bf16 v[28:31], v[212:215], v[152:155], v[28:31]
	v_mfma_f32_16x16x32_bf16 v[28:31], v[216:219], v[156:159], v[28:31]
	v_mfma_f32_16x16x32_bf16 v[36:39], v[208:211], v[156:159], v[36:39]
	v_mfma_f32_16x16x32_bf16 v[36:39], v[204:207], v[152:155], v[36:39]
	v_mfma_f32_16x16x32_bf16 v[20:23], v[204:207], v[176:179], v[20:23]
	v_mfma_f32_16x16x32_bf16 v[20:23], v[208:211], v[180:183], v[20:23]
	v_mfma_f32_16x16x32_bf16 v[12:15], v[216:219], v[180:183], v[12:15]
	v_mfma_f32_16x16x32_bf16 v[12:15], v[212:215], v[176:179], v[12:15]
	v_mfma_f32_16x16x32_bf16 v[0:3], v[212:215], v[196:199], v[0:3]
	v_mfma_f32_16x16x32_bf16 v[0:3], v[216:219], v[200:203], v[0:3]
	v_mfma_f32_16x16x32_bf16 v[4:7], v[208:211], v[200:203], v[4:7]
	v_mfma_f32_16x16x32_bf16 v[4:7], v[204:207], v[196:199], v[4:7]
	s_barrier
; __device__ __forceinline__ float bf_lo(unsigned w) { return __uint_as_float(w << 16); }
; __device__ __forceinline__ float bf_hi(unsigned w) { return __uint_as_float(w & 0xffff0000u); }
;     __device__ __forceinline__ void operator()(const f32x4 (&acc)[2][2][4][2], const Unit& u, int ui, int wr, int wc, int fr, int fq) const {
;         const int rl0 = wr * 64 + fr, col0 = u.pn * 256 + wc * 32 + 8 * fq;
;         u32x4 xv[2][4][2];
; #pragma unroll
;         for (int ai = 0; ai < 2; ++ai)
; #pragma unroll
;             for (int m = 0; m < 4; ++m)
; #pragma unroll
;                 for (int bj = 0; bj < 2; ++bj) xv[ai][m][bj] = *(const u32x4*)(xb + (size_t)(u.pm * 256 + rl0 + ai * 128 + m * 16) * DM + col0 + bj * 128);
; #pragma unroll
;         for (int ai = 0; ai < 2; ++ai)
; #pragma unroll
;             for (int m = 0; m < 4; ++m) { const int rl = rl0 + ai * 128 + m * 16; float* rowp = out + (size_t)(u.pm * 256 + rl) * DM + col0;
;                 const float r2 = tab[ui * 256 + rl];
; #pragma unroll
;                 for (int bj = 0; bj < 2; ++bj) { const u32x4 x = xv[ai][m][bj];
;                     const f32x4 x0 = {bf_lo(x.x), bf_hi(x.x), bf_lo(x.y), bf_hi(x.y)}, x1 = {bf_lo(x.z), bf_hi(x.z), bf_lo(x.w), bf_hi(x.w)};
;                     *(f32x4*)(rowp + bj * 128) = acc[ai][bj][m][0] * r2 + x0; *(f32x4*)(rowp + bj * 128 + 4) = acc[ai][bj][m][1] * r2 + x1; } }
	s_add_i32 s46, s46, 2
	s_add_u32 s20, s20, 0x100
	s_addc_u32 s21, s21, 0
	s_add_u32 s11, s11, 0x100
	s_addc_u32 s13, s13, 0
	s_cmp_gt_u32 s46, 61
	s_cbranch_scc0 .LBB0_522
	s_nop 0
	s_nop 0
	s_nop 0
	s_nop 0
	s_nop 0
	s_nop 0
	s_nop 0
	s_nop 0
	s_nop 0
	s_nop 0
	s_nop 0
	s_nop 0
	s_nop 0
	s_nop 0
	s_nop 0
	s_nop 0
	s_nop 0
	s_nop 0
	s_nop 0
	s_nop 0
	s_nop 0
	s_nop 0
	s_nop 0
	s_nop 0
	s_nop 0
	s_nop 0
	s_nop 0
	s_nop 0
	s_nop 0
	s_nop 0
	s_nop 0
	s_nop 0
	s_nop 0
	s_nop 0
	s_nop 0
	s_nop 0
	s_nop 0
	s_nop 0
	s_nop 0
	s_nop 0
	s_nop 0
	s_nop 0
	s_nop 0
	s_nop 0
	s_nop 0
	s_nop 0
	s_nop 0
	s_nop 0
	s_nop 0
	s_nop 0
	s_lshl_b32 s11, s18, 8
	v_lshl_or_b32 v128, s16, 8, v191
	v_add_u32_e32 v130, s11, v186
	v_ashrrev_i32_e32 v129, 31, v128
	v_ashrrev_i32_e32 v131, 31, v130
	v_lshl_add_u64 v[132:133], v[128:129], 1, s[6:7]
	v_lshlrev_b64 v[134:135], 11, v[130:131]
	v_lshl_add_u64 v[134:135], v[132:133], 0, v[134:135]
	global_load_dwordx4 v[198:201], v[134:135], off
	global_load_dwordx4 v[202:205], v[134:135], off offset:256
	v_or_b32_e32 v134, 16, v130
	v_ashrrev_i32_e32 v135, 31, v134
	v_lshlrev_b64 v[134:135], 11, v[134:135]
	v_lshl_add_u64 v[134:135], v[132:133], 0, v[134:135]
	global_load_dwordx4 v[206:209], v[134:135], off
	global_load_dwordx4 v[210:213], v[134:135], off offset:256
	v_or_b32_e32 v136, 32, v130
	v_ashrrev_i32_e32 v137, 31, v136
	v_or_b32_e32 v138, 48, v130
	v_add_u32_e32 v184, 0x80, v130
	v_add_u32_e32 v182, 0x90, v130
	v_add_u32_e32 v180, 0xa0, v130
	v_add_u32_e32 v178, 0xb0, v130
	v_lshlrev_b64 v[176:177], 2, v[128:129]
	v_lshlrev_b64 v[128:129], 12, v[130:131]
	v_lshlrev_b64 v[130:131], 11, v[136:137]
	v_lshl_add_u64 v[130:131], v[132:133], 0, v[130:131]
	global_load_dwordx4 v[214:217], v[130:131], off
	v_ashrrev_i32_e32 v139, 31, v138
	v_ashrrev_i32_e32 v185, 31, v184
	v_ashrrev_i32_e32 v183, 31, v182
	v_ashrrev_i32_e32 v181, 31, v180
	v_ashrrev_i32_e32 v179, 31, v178
	v_lshlrev_b64 v[134:135], 11, v[138:139]
	v_lshlrev_b64 v[136:137], 11, v[184:185]
	v_lshlrev_b64 v[138:139], 11, v[182:183]
	v_lshl_add_u32 v196, s45, 10, v192
	v_lshlrev_b64 v[140:141], 11, v[180:181]
	v_lshlrev_b64 v[142:143], 11, v[178:179]
	v_lshl_add_u64 v[128:129], s[26:27], 0, v[128:129]
	v_lshl_add_u64 v[134:135], v[132:133], 0, v[134:135]
	v_lshl_add_u64 v[136:137], v[132:133], 0, v[136:137]
	v_lshl_add_u64 v[138:139], v[132:133], 0, v[138:139]
	ds_read2_b32 v[230:231], v196 offset1:16
	v_lshl_add_u64 v[234:235], v[132:133], 0, v[140:141]
	v_lshl_add_u64 v[236:237], v[132:133], 0, v[142:143]
	v_lshl_add_u64 v[238:239], v[128:129], 0, v[176:177]
	global_load_dwordx4 v[218:221], v[130:131], off offset:256
	global_load_dwordx4 v[222:225], v[134:135], off
	global_load_dwordx4 v[226:229], v[134:135], off offset:256
	global_load_dwordx4 v[156:159], v[136:137], off
	global_load_dwordx4 v[152:155], v[136:137], off offset:256
	global_load_dwordx4 v[148:151], v[138:139], off
	global_load_dwordx4 v[144:147], v[138:139], off offset:256
	global_load_dwordx4 v[140:143], v[234:235], off
	s_nop 0
	global_load_dwordx4 v[136:139], v[234:235], off offset:256
	global_load_dwordx4 v[132:135], v[236:237], off
	global_load_dwordx4 v[128:131], v[236:237], off offset:256
	v_add_u32_e32 v232, s11, v188
	v_ashrrev_i32_e32 v233, 31, v232
	s_and_b64 vcc, exec, s[0:1]
	s_mov_b32 s16, s10
	s_mov_b32 s18, s12
	s_mov_b64 s[20:21], s[4:5]
	s_mov_b64 s[22:23], s[14:15]
	s_mov_b32 s45, s44
	s_waitcnt vmcnt(0)
	v_lshlrev_b32_e32 v234, 16, v198
	v_and_b32_e32 v235, 0xffff0000, v198
	v_lshlrev_b32_e32 v198, 16, v199
	v_and_b32_e32 v199, 0xffff0000, v199
	v_lshlrev_b32_e32 v242, 16, v204
	v_and_b32_e32 v243, 0xffff0000, v204
	v_lshlrev_b32_e32 v236, 16, v200
	v_and_b32_e32 v237, 0xffff0000, v200
	v_lshlrev_b32_e32 v200, 16, v201
	v_and_b32_e32 v201, 0xffff0000, v201
	v_lshlrev_b32_e32 v240, 16, v202
	v_and_b32_e32 v241, 0xffff0000, v202
	v_lshlrev_b32_e32 v202, 16, v203
	v_and_b32_e32 v203, 0xffff0000, v203
	v_lshlrev_b32_e32 v204, 16, v205
	v_and_b32_e32 v205, 0xffff0000, v205
	s_waitcnt lgkmcnt(0)
	v_pk_fma_f32 v[126:127], v[126:127], v[230:231], v[198:199] op_sel_hi:[1,0,1]
	v_pk_fma_f32 v[124:125], v[124:125], v[230:231], v[234:235] op_sel_hi:[1,0,1]
	v_pk_fma_f32 v[108:109], v[108:109], v[230:231], v[242:243] op_sel_hi:[1,0,1]
	v_pk_fma_f32 v[122:123], v[122:123], v[230:231], v[200:201] op_sel_hi:[1,0,1]
	v_pk_fma_f32 v[120:121], v[120:121], v[230:231], v[236:237] op_sel_hi:[1,0,1]
	v_pk_fma_f32 v[118:119], v[118:119], v[230:231], v[202:203] op_sel_hi:[1,0,1]
	v_pk_fma_f32 v[116:117], v[116:117], v[230:231], v[240:241] op_sel_hi:[1,0,1]
	v_pk_fma_f32 v[110:111], v[110:111], v[230:231], v[204:205] op_sel_hi:[1,0,1]
	global_store_dwordx4 v[238:239], v[124:127], off
	global_store_dwordx4 v[238:239], v[120:123], off offset:16
	global_store_dwordx4 v[238:239], v[116:119], off offset:512
	global_store_dwordx4 v[238:239], v[108:111], off offset:528
	v_mov_b32_e32 v122, v231
	v_lshlrev_b32_e32 v118, 16, v208
	v_lshlrev_b64 v[108:109], 12, v[232:233]
	v_lshl_add_u64 v[108:109], s[26:27], 0, v[108:109]
	v_lshl_add_u64 v[116:117], v[108:109], 0, v[176:177]
	v_lshlrev_b32_e32 v108, 16, v206
	v_and_b32_e32 v109, 0xffff0000, v206
	v_lshlrev_b32_e32 v110, 16, v207
	v_and_b32_e32 v111, 0xffff0000, v207
	v_pk_fma_f32 v[110:111], v[114:115], v[122:123], v[110:111] op_sel_hi:[1,0,1]
	v_pk_fma_f32 v[108:109], v[112:113], v[122:123], v[108:109] op_sel_hi:[1,0,1]
	global_store_dwordx4 v[116:117], v[108:111], off
	v_and_b32_e32 v119, 0xffff0000, v208
	v_lshlrev_b32_e32 v120, 16, v209
	v_lshlrev_b32_e32 v108, 16, v212
	v_and_b32_e32 v109, 0xffff0000, v212
	v_lshlrev_b32_e32 v110, 16, v213
	v_and_b32_e32 v111, 0xffff0000, v213
	v_pk_fma_f32 v[98:99], v[98:99], v[122:123], v[110:111] op_sel_hi:[1,0,1]
	v_pk_fma_f32 v[96:97], v[96:97], v[122:123], v[108:109] op_sel_hi:[1,0,1]
	v_and_b32_e32 v121, 0xffff0000, v209
	global_store_dwordx4 v[116:117], v[96:99], off offset:528
	ds_read2_b32 v[98:99], v196 offset0:32 offset1:48
	v_pk_fma_f32 v[106:107], v[106:107], v[122:123], v[120:121] op_sel_hi:[1,0,1]
	v_pk_fma_f32 v[104:105], v[104:105], v[122:123], v[118:119] op_sel_hi:[1,0,1]
	v_add_u32_e32 v96, s11, v189
	global_store_dwordx4 v[116:117], v[104:107], off offset:16
	v_ashrrev_i32_e32 v97, 31, v96
	v_lshlrev_b64 v[96:97], 12, v[96:97]
	v_lshlrev_b32_e32 v104, 16, v210
	v_and_b32_e32 v105, 0xffff0000, v210
	v_lshlrev_b32_e32 v106, 16, v211
	v_and_b32_e32 v107, 0xffff0000, v211
	v_pk_fma_f32 v[102:103], v[102:103], v[122:123], v[106:107] op_sel_hi:[1,0,1]
	v_pk_fma_f32 v[100:101], v[100:101], v[122:123], v[104:105] op_sel_hi:[1,0,1]
	global_store_dwordx4 v[116:117], v[100:103], off offset:512
	v_lshl_add_u64 v[96:97], s[26:27], 0, v[96:97]
	v_lshl_add_u64 v[96:97], v[96:97], 0, v[176:177]
	v_lshlrev_b32_e32 v100, 16, v214
	v_and_b32_e32 v101, 0xffff0000, v214
	v_lshlrev_b32_e32 v102, 16, v215
	v_and_b32_e32 v103, 0xffff0000, v215
	s_waitcnt lgkmcnt(0)
; __device__ __forceinline__ float bf_lo(unsigned w) { return __uint_as_float(w << 16); }
; __device__ __forceinline__ float bf_hi(unsigned w) { return __uint_as_float(w & 0xffff0000u); }
;     __device__ __forceinline__ void operator()(const f32x4 (&acc)[2][2][4][2], const Unit& u, int ui, int wr, int wc, int fr, int fq) const {
;     ...
;             for (int m = 0; m < 4; ++m) { const int rl = rl0 + ai * 128 + m * 16; float* rowp = out + (size_t)(u.pm * 256 + rl) * DM + col0;
;                 const float r2 = tab[ui * 256 + rl];
; #pragma unroll
;                 for (int bj = 0; bj < 2; ++bj) { const u32x4 x = xv[ai][m][bj];
;                     const f32x4 x0 = {bf_lo(x.x), bf_hi(x.x), bf_lo(x.y), bf_hi(x.y)}, x1 = {bf_lo(x.z), bf_hi(x.z), bf_lo(x.w), bf_hi(x.w)};
;                     *(f32x4*)(rowp + bj * 128) = acc[ai][bj][m][0] * r2 + x0; *(f32x4*)(rowp + bj * 128 + 4) = acc[ai][bj][m][1] * r2 + x1; } }
	v_pk_fma_f32 v[94:95], v[94:95], v[98:99], v[102:103] op_sel_hi:[1,0,1]
	v_pk_fma_f32 v[92:93], v[92:93], v[98:99], v[100:101] op_sel_hi:[1,0,1]
	global_store_dwordx4 v[96:97], v[92:95], off
	v_lshlrev_b32_e32 v104, 16, v216
	v_and_b32_e32 v105, 0xffff0000, v216
	v_lshlrev_b32_e32 v92, 16, v220
	v_and_b32_e32 v93, 0xffff0000, v220
	v_lshlrev_b32_e32 v94, 16, v221
	v_and_b32_e32 v95, 0xffff0000, v221
	v_lshlrev_b32_e32 v106, 16, v217
	v_and_b32_e32 v107, 0xffff0000, v217
	v_pk_fma_f32 v[82:83], v[82:83], v[98:99], v[94:95] op_sel_hi:[1,0,1]
	v_pk_fma_f32 v[80:81], v[80:81], v[98:99], v[92:93] op_sel_hi:[1,0,1]
	v_pk_fma_f32 v[90:91], v[90:91], v[98:99], v[106:107] op_sel_hi:[1,0,1]
	v_pk_fma_f32 v[88:89], v[88:89], v[98:99], v[104:105] op_sel_hi:[1,0,1]
	global_store_dwordx4 v[96:97], v[80:83], off offset:528
	global_store_dwordx4 v[96:97], v[88:91], off offset:16
	s_nop 0
	v_add_u32_e32 v80, s11, v190
	v_lshlrev_b32_e32 v88, 16, v218
	v_and_b32_e32 v89, 0xffff0000, v218
	v_lshlrev_b32_e32 v90, 16, v219
	v_and_b32_e32 v91, 0xffff0000, v219
	v_ashrrev_i32_e32 v81, 31, v80
	v_pk_fma_f32 v[86:87], v[86:87], v[98:99], v[90:91] op_sel_hi:[1,0,1]
	v_pk_fma_f32 v[84:85], v[84:85], v[98:99], v[88:89] op_sel_hi:[1,0,1]
	v_lshlrev_b64 v[80:81], 12, v[80:81]
	global_store_dwordx4 v[96:97], v[84:87], off offset:512
	v_lshl_add_u64 v[80:81], s[26:27], 0, v[80:81]
	v_lshlrev_b32_e32 v82, 16, v222
	v_and_b32_e32 v83, 0xffff0000, v222
	v_lshlrev_b32_e32 v84, 16, v223
	v_and_b32_e32 v85, 0xffff0000, v223
	v_mov_b32_e32 v90, v99
	v_lshl_add_u64 v[80:81], v[80:81], 0, v[176:177]
	v_pk_fma_f32 v[78:79], v[78:79], v[90:91], v[84:85] op_sel_hi:[1,0,1]
	v_pk_fma_f32 v[76:77], v[76:77], v[90:91], v[82:83] op_sel_hi:[1,0,1]
	global_store_dwordx4 v[80:81], v[76:79], off
	v_lshlrev_b32_e32 v86, 16, v224
	v_and_b32_e32 v87, 0xffff0000, v224
	v_lshlrev_b32_e32 v76, 16, v228
	v_and_b32_e32 v77, 0xffff0000, v228
	v_lshlrev_b32_e32 v78, 16, v229
	v_and_b32_e32 v79, 0xffff0000, v229
	v_pk_fma_f32 v[66:67], v[66:67], v[90:91], v[78:79] op_sel_hi:[1,0,1]
	v_pk_fma_f32 v[64:65], v[64:65], v[90:91], v[76:77] op_sel_hi:[1,0,1]
	v_lshlrev_b32_e32 v88, 16, v225
	v_and_b32_e32 v89, 0xffff0000, v225
	global_store_dwordx4 v[80:81], v[64:67], off offset:528
	ds_read2_b32 v[66:67], v196 offset0:128 offset1:144
	v_pk_fma_f32 v[74:75], v[74:75], v[90:91], v[88:89] op_sel_hi:[1,0,1]
	v_pk_fma_f32 v[72:73], v[72:73], v[90:91], v[86:87] op_sel_hi:[1,0,1]
	global_store_dwordx4 v[80:81], v[72:75], off offset:16
	v_lshlrev_b64 v[64:65], 12, v[184:185]
	v_lshl_add_u64 v[64:65], s[26:27], 0, v[64:65]
	v_lshlrev_b32_e32 v72, 16, v226
	v_and_b32_e32 v73, 0xffff0000, v226
	v_lshlrev_b32_e32 v74, 16, v227
	v_and_b32_e32 v75, 0xffff0000, v227
	v_pk_fma_f32 v[70:71], v[70:71], v[90:91], v[74:75] op_sel_hi:[1,0,1]
	v_pk_fma_f32 v[68:69], v[68:69], v[90:91], v[72:73] op_sel_hi:[1,0,1]
	global_store_dwordx4 v[80:81], v[68:71], off offset:512
	v_lshl_add_u64 v[64:65], v[64:65], 0, v[176:177]
	v_lshlrev_b32_e32 v72, 16, v158
	v_lshlrev_b32_e32 v68, 16, v156
	v_and_b32_e32 v69, 0xffff0000, v156
	v_lshlrev_b32_e32 v70, 16, v157
	v_and_b32_e32 v71, 0xffff0000, v157
	v_and_b32_e32 v73, 0xffff0000, v158
	v_lshlrev_b32_e32 v74, 16, v159
	v_and_b32_e32 v75, 0xffff0000, v159
	s_waitcnt lgkmcnt(0)
; __device__ __forceinline__ float bf_lo(unsigned w) { return __uint_as_float(w << 16); }
; __device__ __forceinline__ float bf_hi(unsigned w) { return __uint_as_float(w & 0xffff0000u); }
; #define PG8_WAIT_V(n) asm volatile("s_waitcnt vmcnt(" #n ")" ::: "memory")
; #define PG8_BAR __builtin_amdgcn_s_barrier()
; template <class Epi, class Ptrs>
; __device__ __forceinline__ void gemm_phase(LAS unsigned char* lds, const int K, const StaticOrder& S, const Ptrs& P, const Epi& E) {
;     ...
;         E(acc, cur, ui, wr, wc, fr, fq);
;         if (!has_next) break;
; #pragma unroll
;         for (int a = 0; a < 2; ++a)
; #pragma unroll
;             for (int b = 0; b < 2; ++b)
; #pragma unroll
;                 for (int m = 0; m < 4; ++m)
; #pragma unroll
;                     for (int n = 0; n < 2; ++n) acc[a][b][m][n] = (f32x4){0.f, 0.f, 0.f, 0.f};
;         cur = nxt; cA = nA; cB = nB; ++ui;
;     }
;     PG8_WAIT_V(0);
;     if (wr == 0) PG8_BAR;
;     PG8_BAR;
;     __device__ __forceinline__ void operator()(const f32x4 (&acc)[2][2][4][2], const Unit& u, int ui, int wr, int wc, int fr, int fq) const {
;     ...
;             for (int m = 0; m < 4; ++m) { const int rl = rl0 + ai * 128 + m * 16; float* rowp = out + (size_t)(u.pm * 256 + rl) * DM + col0;
;                 const float r2 = tab[ui * 256 + rl];
; #pragma unroll
;                 for (int bj = 0; bj < 2; ++bj) { const u32x4 x = xv[ai][m][bj];
;                     const f32x4 x0 = {bf_lo(x.x), bf_hi(x.x), bf_lo(x.y), bf_hi(x.y)}, x1 = {bf_lo(x.z), bf_hi(x.z), bf_lo(x.w), bf_hi(x.w)};
;                     *(f32x4*)(rowp + bj * 128) = acc[ai][bj][m][0] * r2 + x0; *(f32x4*)(rowp + bj * 128 + 4) = acc[ai][bj][m][1] * r2 + x1; } }
	v_pk_fma_f32 v[62:63], v[62:63], v[66:67], v[70:71] op_sel_hi:[1,0,1]
	v_pk_fma_f32 v[60:61], v[60:61], v[66:67], v[68:69] op_sel_hi:[1,0,1]
	global_store_dwordx4 v[64:65], v[60:63], off
	v_pk_fma_f32 v[58:59], v[58:59], v[66:67], v[74:75] op_sel_hi:[1,0,1]
	v_pk_fma_f32 v[56:57], v[56:57], v[66:67], v[72:73] op_sel_hi:[1,0,1]
	v_lshlrev_b32_e32 v60, 16, v154
	v_and_b32_e32 v61, 0xffff0000, v154
	v_lshlrev_b32_e32 v62, 16, v155
	v_and_b32_e32 v63, 0xffff0000, v155
	global_store_dwordx4 v[64:65], v[56:59], off offset:16
	v_pk_fma_f32 v[46:47], v[46:47], v[66:67], v[62:63] op_sel_hi:[1,0,1]
	v_pk_fma_f32 v[44:45], v[44:45], v[66:67], v[60:61] op_sel_hi:[1,0,1]
	v_lshlrev_b32_e32 v56, 16, v152
	v_and_b32_e32 v57, 0xffff0000, v152
	v_lshlrev_b32_e32 v58, 16, v153
	v_and_b32_e32 v59, 0xffff0000, v153
	v_pk_fma_f32 v[54:55], v[54:55], v[66:67], v[58:59] op_sel_hi:[1,0,1]
	v_pk_fma_f32 v[52:53], v[52:53], v[66:67], v[56:57] op_sel_hi:[1,0,1]
	global_store_dwordx4 v[64:65], v[44:47], off offset:528
	global_store_dwordx4 v[64:65], v[52:55], off offset:512
	v_lshlrev_b32_e32 v56, 16, v151
	v_lshlrev_b64 v[44:45], 12, v[182:183]
	v_lshl_add_u64 v[44:45], s[26:27], 0, v[44:45]
	v_lshlrev_b32_e32 v54, 16, v150
	v_and_b32_e32 v55, 0xffff0000, v150
	v_and_b32_e32 v57, 0xffff0000, v151
	v_mov_b32_e32 v58, v67
	v_lshl_add_u64 v[52:53], v[44:45], 0, v[176:177]
	v_pk_fma_f32 v[42:43], v[42:43], v[58:59], v[56:57] op_sel_hi:[1,0,1]
	v_pk_fma_f32 v[40:41], v[40:41], v[58:59], v[54:55] op_sel_hi:[1,0,1]
	v_lshlrev_b32_e32 v44, 16, v148
	v_and_b32_e32 v45, 0xffff0000, v148
	v_lshlrev_b32_e32 v46, 16, v149
	v_and_b32_e32 v47, 0xffff0000, v149
	global_store_dwordx4 v[52:53], v[40:43], off offset:16
	v_pk_fma_f32 v[46:47], v[50:51], v[58:59], v[46:47] op_sel_hi:[1,0,1]
	v_pk_fma_f32 v[44:45], v[48:49], v[58:59], v[44:45] op_sel_hi:[1,0,1]
	v_lshlrev_b32_e32 v40, 16, v144
	v_and_b32_e32 v41, 0xffff0000, v144
	v_lshlrev_b32_e32 v42, 16, v145
	v_and_b32_e32 v43, 0xffff0000, v145
	v_pk_fma_f32 v[38:39], v[38:39], v[58:59], v[42:43] op_sel_hi:[1,0,1]
	v_pk_fma_f32 v[36:37], v[36:37], v[58:59], v[40:41] op_sel_hi:[1,0,1]
	global_store_dwordx4 v[52:53], v[44:47], off
	global_store_dwordx4 v[52:53], v[36:39], off offset:512
	ds_read2_b32 v[38:39], v196 offset0:160 offset1:176
	v_lshlrev_b32_e32 v44, 16, v146
	v_and_b32_e32 v45, 0xffff0000, v146
	v_lshlrev_b32_e32 v46, 16, v147
	v_and_b32_e32 v47, 0xffff0000, v147
	v_pk_fma_f32 v[30:31], v[30:31], v[58:59], v[46:47] op_sel_hi:[1,0,1]
	v_pk_fma_f32 v[28:29], v[28:29], v[58:59], v[44:45] op_sel_hi:[1,0,1]
	global_store_dwordx4 v[52:53], v[28:31], off offset:528
	v_lshlrev_b32_e32 v40, 16, v142
	v_and_b32_e32 v41, 0xffff0000, v142
	v_lshlrev_b64 v[28:29], 12, v[180:181]
	v_lshl_add_u64 v[28:29], s[26:27], 0, v[28:29]
	v_lshl_add_u64 v[36:37], v[28:29], 0, v[176:177]
	v_lshlrev_b32_e32 v28, 16, v140
	v_and_b32_e32 v29, 0xffff0000, v140
	v_lshlrev_b32_e32 v30, 16, v141
	v_and_b32_e32 v31, 0xffff0000, v141
	s_waitcnt lgkmcnt(0)
	v_pk_fma_f32 v[30:31], v[34:35], v[38:39], v[30:31] op_sel_hi:[1,0,1]
	v_pk_fma_f32 v[28:29], v[32:33], v[38:39], v[28:29] op_sel_hi:[1,0,1]
	v_lshlrev_b32_e32 v42, 16, v143
	v_and_b32_e32 v43, 0xffff0000, v143
	global_store_dwordx4 v[36:37], v[28:31], off
	v_pk_fma_f32 v[26:27], v[26:27], v[38:39], v[42:43] op_sel_hi:[1,0,1]
	v_pk_fma_f32 v[24:25], v[24:25], v[38:39], v[40:41] op_sel_hi:[1,0,1]
	v_lshlrev_b32_e32 v28, 16, v138
	v_and_b32_e32 v29, 0xffff0000, v138
	v_lshlrev_b32_e32 v30, 16, v139
	v_and_b32_e32 v31, 0xffff0000, v139
	v_pk_fma_f32 v[14:15], v[14:15], v[38:39], v[30:31] op_sel_hi:[1,0,1]
	v_pk_fma_f32 v[12:13], v[12:13], v[38:39], v[28:29] op_sel_hi:[1,0,1]
	global_store_dwordx4 v[36:37], v[24:27], off offset:16
	global_store_dwordx4 v[36:37], v[12:15], off offset:528
	s_nop 0
	v_lshlrev_b32_e32 v24, 16, v136
	v_and_b32_e32 v25, 0xffff0000, v136
	v_lshlrev_b32_e32 v26, 16, v137
	v_and_b32_e32 v27, 0xffff0000, v137
	v_lshlrev_b64 v[12:13], 12, v[178:179]
	v_pk_fma_f32 v[22:23], v[22:23], v[38:39], v[26:27] op_sel_hi:[1,0,1]
	v_pk_fma_f32 v[20:21], v[20:21], v[38:39], v[24:25] op_sel_hi:[1,0,1]
	v_lshl_add_u64 v[12:13], s[26:27], 0, v[12:13]
	global_store_dwordx4 v[36:37], v[20:23], off offset:512
	v_lshlrev_b32_e32 v14, 16, v133
	v_and_b32_e32 v15, 0xffff0000, v133
	v_lshl_add_u64 v[20:21], v[12:13], 0, v[176:177]
	v_lshlrev_b32_e32 v12, 16, v132
	v_and_b32_e32 v13, 0xffff0000, v132
	v_lshlrev_b32_e32 v22, 16, v134
	v_and_b32_e32 v23, 0xffff0000, v134
	v_lshlrev_b32_e32 v24, 16, v135
	v_and_b32_e32 v25, 0xffff0000, v135
	v_mov_b32_e32 v26, v39
	v_pk_fma_f32 v[14:15], v[18:19], v[26:27], v[14:15] op_sel_hi:[1,0,1]
	v_pk_fma_f32 v[12:13], v[16:17], v[26:27], v[12:13] op_sel_hi:[1,0,1]
	v_pk_fma_f32 v[10:11], v[10:11], v[26:27], v[24:25] op_sel_hi:[1,0,1]
	v_pk_fma_f32 v[8:9], v[8:9], v[26:27], v[22:23] op_sel_hi:[1,0,1]
	global_store_dwordx4 v[20:21], v[12:15], off
	global_store_dwordx4 v[20:21], v[8:11], off offset:16
	s_nop 0
	v_lshlrev_b32_e32 v12, 16, v130
	v_lshlrev_b32_e32 v8, 16, v128
	v_and_b32_e32 v9, 0xffff0000, v128
	v_lshlrev_b32_e32 v10, 16, v129
	v_and_b32_e32 v11, 0xffff0000, v129
	v_and_b32_e32 v13, 0xffff0000, v130
	v_lshlrev_b32_e32 v14, 16, v131
	v_and_b32_e32 v15, 0xffff0000, v131
	v_pk_fma_f32 v[6:7], v[6:7], v[26:27], v[10:11] op_sel_hi:[1,0,1]
	v_pk_fma_f32 v[4:5], v[4:5], v[26:27], v[8:9] op_sel_hi:[1,0,1]
	v_pk_fma_f32 v[2:3], v[2:3], v[26:27], v[14:15] op_sel_hi:[1,0,1]
	v_pk_fma_f32 v[0:1], v[0:1], v[26:27], v[12:13] op_sel_hi:[1,0,1]
	global_store_dwordx4 v[20:21], v[4:7], off offset:512
	global_store_dwordx4 v[20:21], v[0:3], off offset:528
	s_cbranch_vccz .LBB0_517
	s_waitcnt vmcnt(0)
	s_setprio 0
	s_cmpk_gt_u32 s33, 0xff
	s_cbranch_scc1 .LBB0_526
	s_barrier
